# last layer: skip dead context-stream work (ctx split-K GEMMs, ctx slab sum + its grid barrier, ctx attention units, ctx gla_out chunks); plus earlier MLA pipeline, batched scan, v_rcp
# speedup vs baseline: 1.0537x; 1.0065x over previous
; #define PG8_LAS __attribute__((address_space(3)))
;     asm volatile("" : "+s"(K), "+s"(N), "+s"(nsplit));
;     int gd_ = (int)gridDim.x, bi_ = (int)blockIdx.x; asm volatile("" : "+s"(gd_), "+s"(bi_));
;     bi_ = (bi_ + gd_ - (rot % gd_)) % gd_;
;     const int kloop = K / nsplit;
;     pg8::Gemm g{A, Bt, MT, N, K, kloop}; CtxSplitOrder S{N / 256, nsplit, kloop, gd_, bi_};
;     pg8::gemm_phase<Epi, CtxSplitOrder, true, true>((PG8_LAS unsigned char*)lds, g, S, E);
; __global__ void __launch_bounds__(NTHR, 2) mk_fwd(Args args) {
;     ...
;                 { EpiPartial E{(float*)(ws + O_U), 256 * 2}; run_gemm_ctx(lds, (const bf16_t*)(ws + O_ACT), (const bf16_t*)(ws + O_WDOWN), 1024, FF, 11, E); }
.LBB0_61:
	v_readlane_b32 s10, v253, 0
	s_mov_b32 s37, 11
	s_movk_i32 s1, 0x400
	s_movk_i32 s0, 0xb00
	s_mov_b32 s2, s81
	s_mov_b32 s42, s10
	s_abs_i32 s3, s42
	v_cvt_f32_u32_e32 v0, s3
	v_readlane_b32 s11, v253, 1
	s_sub_i32 s11, 0, s3
	s_add_i32 s2, s2, s42
	v_rcp_iflag_f32_e32 v0, v0
	s_ashr_i32 s10, s2, 31
	s_abs_i32 s2, s2
	v_mov_b32_e32 v18, v203
	v_mul_f32_e32 v0, 0x4f7ffffe, v0
	v_cvt_u32_f32_e32 v0, v0
	s_nop 0
	v_readfirstlane_b32 s24, v18
	v_readfirstlane_b32 s14, v0
	s_mul_i32 s11, s11, s14
	s_mul_hi_u32 s11, s14, s11
	s_add_i32 s14, s14, s11
	s_mul_hi_u32 s11, s2, s14
	s_mul_i32 s11, s11, s3
	s_sub_i32 s2, s2, s11
	s_sub_i32 s11, s2, s3
	s_cmp_ge_u32 s2, s3
	s_cselect_b32 s2, s11, s2
	s_sub_i32 s11, s2, s3
	s_cmp_ge_u32 s2, s3
	s_cselect_b32 s2, s11, s2
	s_xor_b32 s2, s2, s10
	s_sub_i32 s43, s2, s10
	s_ashr_i32 s2, s1, 31
	s_lshr_b32 s2, s2, 24
	s_add_i32 s1, s1, s2
	s_ashr_i32 s44, s1, 8
	s_mul_i32 s1, s44, s37
	s_lshl_b32 s45, s1, 1
	v_readlane_b32 s1, v254, 27
	s_nop 3
	s_cmp_eq_u32 s1, 3
	s_cbranch_scc1 .LBB0_82
	s_cmp_ge_i32 s43, s45
	s_cbranch_scc1 .LBB0_82
; #define PG8_STAGE(bufoff, gbase, voff) do { _Pragma("unroll") for (int _i = 0; _i < 2; ++_i) \
;         __builtin_amdgcn_global_load_lds((const unsigned*)((const char*)(gbase) + (voff)[_i]), (PG8_LAS unsigned*)(lds + (bufoff) + ldsw + _i * 8192), 16, 0, 0); } while (0)
; #define PG8_WAIT_V(n) asm volatile("s_waitcnt vmcnt(" #n ")" ::: "memory")
; #define PG8_BAR __builtin_amdgcn_s_barrier()
; template <class Epi, class Sched, bool ALIGN_EPI = false, bool SP2 = false>
; __device__ __forceinline__ void gemm_phase(PG8_LAS unsigned char* lds, const Gemm g, const Sched& S, const Epi& E) {
;     ...
;     const int tid = tid_, wid = __builtin_amdgcn_readfirstlane(tid >> 6), lane = tid & 63, wr = wid >> 2, wc = wid & 3, fr = lane & 15, fq = lane >> 4;
;     const int K = g.K, nt = g.Kloop / BK;
;     unsigned voffA[2], voffB[2];
; #pragma unroll
;     for (int i = 0; i < 2; ++i) { int R, C; stage_rc(tid * 16 + i * 8192, R, C); const int Rb = Epi::PERM ? ((R & ~31) + perm32(R & 31)) : R;
;         voffA[i] = (unsigned)(R * K + C) * 2u; voffB[i] = (unsigned)(Rb * K + C) * 2u; }
;     const size_t kstep = (size_t)(BK * 2);
;     const size_t hstep = (size_t)HALF * K * 2;
;     const size_t tstep = 2 * hstep;
;     const unsigned ldsw = (unsigned)wid * 1024u;
;     const int aoff = lds_byte(wr * 64 + fr, fq * 8), boff = lds_byte(wc * 32 + fr, fq * 8);
;     ...
;     Unit cur, nxt; int ui = 0;
;     if (!S.next(0, cur)) return;
;     f32x4 acc[2][2][4][2];
; #pragma unroll
;     for (int a = 0; a < 2; ++a)
; #pragma unroll
;         for (int b = 0; b < 2; ++b)
; #pragma unroll
;             for (int m = 0; m < 4; ++m)
; #pragma unroll
;                 for (int n = 0; n < 2; ++n) acc[a][b][m][n] = (f32x4){0.f, 0.f, 0.f, 0.f};
;     bf16x8 At[4][2], B0[2][2], B1[2][2];
;     const char* cA = (const char*)g.A + (size_t)cur.pm * tstep + cur.kb; const char* cB = (const char*)g.Bt + (size_t)cur.pn * tstep + cur.kb;
;     S.a_ready(cur);
;     if constexpr (SP2) {
;         PG8_STAGE(PG8_SB(0, 0), cB, voffB); PG8_STAGE(PG8_SB(0, 1), cB + hstep, voffB); PG8_STAGE(PG8_SA(0, 0), cA, voffA); PG8_STAGE(PG8_SA(0, 1), cA + hstep, voffA);
;         if (wr == 1) PG8_BAR;
;         PG8_WAIT_V(2); PG8_BAR;
;         PG8_STAGE(PG8_SB(1, 0), cB + kstep, voffB); PG8_STAGE(PG8_SA(1, 0), cA + kstep, voffA); PG8_STAGE(PG8_SB(1, 1), cB + hstep + kstep, voffB);
;         PG8_WAIT_V(6); PG8_BAR;
	s_abs_i32 s47, s37
	v_cvt_f32_u32_e32 v0, s47
	s_sub_i32 s10, 0, s47
	s_abs_i32 s3, s0
	s_ashr_i32 s1, s0, 31
	v_rcp_iflag_f32_e32 v0, v0
	s_ashr_i32 s46, s37, 31
	s_xor_b32 s2, s1, s46
	s_waitcnt vmcnt(0)
	v_mov_b32_e32 v141, v36
	v_mul_f32_e32 v0, 0x4f7ffffe, v0
	v_cvt_u32_f32_e32 v0, v0
	v_mov_b32_e32 v39, v36
	v_mov_b32_e32 v143, v36
	v_mov_b32_e32 v43, v36
	v_readfirstlane_b32 s48, v0
	v_lshlrev_b32_e32 v0, 4, v18
	v_add_u32_e32 v1, 0x2000, v0
	v_ashrrev_i32_e32 v2, 31, v1
	v_lshrrev_b32_e32 v2, 22, v2
	v_add_u32_e32 v2, v1, v2
	v_ashrrev_i32_e32 v2, 10, v2
	v_mul_i32_i24_e32 v3, 0x400, v2
	s_mul_i32 s10, s10, s48
	v_sub_u32_e32 v1, v1, v3
	s_mul_hi_u32 s10, s48, s10
	v_lshrrev_b32_e32 v3, 4, v1
	s_add_i32 s48, s48, s10
	v_bitop3_b32 v1, v3, v1, 32 bitop3:0x6c
	s_mul_hi_u32 s10, s3, s48
	v_ashrrev_i32_e32 v3, 31, v1
	s_mul_i32 s11, s10, s47
	v_lshrrev_b32_e32 v3, 26, v3
	s_sub_i32 s3, s3, s11
	v_add_u32_e32 v3, v1, v3
	v_lshlrev_b32_e32 v5, 3, v2
	s_add_i32 s11, s10, 1
	s_sub_i32 s14, s3, s47
	v_ashrrev_i32_e32 v4, 6, v3
	v_and_b32_e32 v5, -16, v5
	v_lshlrev_b32_e32 v2, 5, v2
	s_cmp_ge_u32 s3, s47
	v_add_u32_e32 v5, v4, v5
	v_and_b32_e32 v12, 32, v2
	v_and_b32_e32 v2, 0xc0, v3
	s_cselect_b32 s3, s14, s3
	v_and_b32_e32 v4, 3, v4
	s_mov_b32 s14, 0x7fffffe0
	v_lshrrev_b32_e32 v6, 2, v5
	v_lshlrev_b32_e32 v7, 1, v5
	v_sub_u32_e32 v1, v1, v2
	v_and_or_b32 v4, v5, s14, v4
	v_and_b32_e32 v6, 4, v6
	v_and_b32_e32 v7, 24, v7
	v_ashrrev_i16_sdwa v1, v217, sext(v1) dst_sel:DWORD dst_unused:UNUSED_PAD src0_sel:DWORD src1_sel:BYTE_0
	v_or3_b32 v4, v4, v6, v7
	v_bfe_i32 v13, v1, 0, 16
	v_mul_lo_u32 v4, v4, s0
	v_add_u32_e32 v1, v12, v13
	v_mul_lo_u32 v14, v5, s0
	v_add_lshl_u32 v38, v4, v1, 1
	v_add_lshl_u32 v42, v1, v14, 1
	v_bfe_i32 v1, v18, 27, 1
	v_lshrrev_b32_e32 v1, 22, v1
	v_add_u32_e32 v1, v0, v1
	v_and_b32_e32 v1, 0xfffffc00, v1
	v_sub_u32_e32 v0, v0, v1
	v_lshrrev_b32_e32 v1, 4, v0
	v_ashrrev_i32_e32 v3, 31, v18
	s_cselect_b32 s10, s11, s10
	v_bitop3_b32 v0, v1, v0, 32 bitop3:0x6c
	v_lshrrev_b32_e32 v3, 26, v3
	s_add_i32 s11, s10, 1
	v_ashrrev_i32_e32 v1, 31, v0
	v_add_u32_e32 v3, v18, v3
	s_cmp_ge_u32 s3, s47
	v_lshrrev_b32_e32 v1, 26, v1
	v_ashrrev_i32_e32 v3, 6, v3
	s_cselect_b32 s3, s11, s10
	v_add_u32_e32 v1, v0, v1
	v_lshlrev_b32_e32 v4, 3, v3
	s_abs_i32 s15, s43
	v_ashrrev_i32_e32 v2, 6, v1
	v_and_b32_e32 v4, -16, v4
	s_mul_hi_u32 s16, s15, s48
	v_add_u32_e32 v4, v2, v4
	v_and_b32_e32 v2, 3, v2
	s_mul_i32 s17, s16, s47
	s_xor_b32 s3, s3, s2
	s_ashr_i32 s28, s24, 6
	v_and_or_b32 v2, v4, s14, v2
	s_ashr_i32 s14, s43, 31
	s_sub_i32 s15, s15, s17
	s_sub_i32 s25, s3, s2
	s_ashr_i32 s29, s24, 8
	s_lshl_b64 s[2:3], s[0:1], 8
	s_lshl_b64 s[10:11], s[0:1], 9
	s_lshl_b32 s49, s28, 10
	s_xor_b32 s14, s14, s46
	s_add_i32 s17, s16, 1
	s_sub_i32 s18, s15, s47
	v_and_b32_e32 v1, 0xc0, v1
	s_cmp_ge_u32 s15, s47
	v_lshrrev_b32_e32 v5, 2, v4
	v_lshlrev_b32_e32 v6, 1, v4
	v_sub_u32_e32 v0, v0, v1
	s_cselect_b32 s16, s17, s16
	v_and_b32_e32 v5, 4, v5
	v_and_b32_e32 v6, 24, v6
	v_lshlrev_b32_e32 v3, 5, v3
	v_ashrrev_i16_sdwa v0, v217, sext(v0) dst_sel:DWORD dst_unused:UNUSED_PAD src0_sel:DWORD src1_sel:BYTE_0
	s_cselect_b32 s15, s18, s15
	s_add_i32 s17, s16, 1
	v_or3_b32 v2, v2, v5, v6
	v_and_b32_e32 v15, 32, v3
	v_bfe_i32 v16, v0, 0, 16
	s_cmp_ge_u32 s15, s47
	v_mul_lo_u32 v2, v2, s0
	v_add_u32_e32 v0, v15, v16
	v_mul_lo_u32 v17, v4, s0
	s_cselect_b32 s15, s17, s16
	s_abs_i32 s51, s44
	v_add_lshl_u32 v140, v2, v0, 1
	v_add_lshl_u32 v142, v0, v17, 1
	v_cvt_f32_u32_e32 v0, s51
	s_sub_i32 s18, 0, s51
	s_xor_b32 s15, s15, s14
	s_sub_i32 s14, s15, s14
	v_rcp_iflag_f32_e32 v0, v0
	s_abs_i32 s17, s14
	s_mul_i32 s15, s14, s37
	s_ashr_i32 s16, s14, 31
	v_mul_f32_e32 v0, 0x4f7ffffe, v0
	v_cvt_u32_f32_e32 v0, v0
	s_ashr_i32 s50, s44, 31
	s_sub_i32 s15, s43, s15
	s_xor_b32 s16, s16, s50
	v_readfirstlane_b32 s52, v0
	s_mul_i32 s18, s18, s52
	s_mul_hi_u32 s18, s52, s18
	s_add_i32 s52, s52, s18
	s_mul_hi_u32 s18, s17, s52
	s_mul_i32 s19, s18, s51
	s_sub_i32 s17, s17, s19
	s_add_i32 s19, s18, 1
	s_sub_i32 s30, s17, s51
	s_cmp_ge_u32 s17, s51
	s_cselect_b32 s18, s19, s18
	s_cselect_b32 s17, s30, s17
	s_add_i32 s19, s18, 1
	s_cmp_ge_u32 s17, s51
	s_cselect_b32 s17, s19, s18
	s_xor_b32 s17, s17, s16
	s_sub_i32 s16, s17, s16
	s_mul_i32 s17, s16, s44
	s_sub_i32 s63, s14, s17
	s_cmp_eq_u32 s16, 0
	s_cselect_b32 s62, 0, 33
	s_lshr_b64 s[0:1], s[0:1], 23
	s_mul_i32 s1, s0, s62
	s_mul_hi_u32 s14, s10, s62
	s_add_i32 s14, s14, s1
	s_ashr_i32 s1, s63, 31
	s_mul_i32 s15, s15, s25
	s_mul_i32 s1, s10, s1
	s_mul_hi_u32 s17, s10, s63
	s_lshl_b32 s64, s15, 1
	s_add_i32 s1, s17, s1
	s_mul_i32 s0, s0, s63
	s_ashr_i32 s16, s64, 31
	s_add_i32 s1, s1, s0
	s_mul_i32 s0, s10, s63
	s_add_u32 s0, s27, s0
	s_addc_u32 s1, s36, s1
	s_add_u32 s0, s0, s64
	s_addc_u32 s1, s1, s16
	s_add_i32 s53, s49, 0
	s_add_i32 m0, s53, 0x10000
	s_mul_i32 s15, s10, s62
	global_load_lds_dwordx4 v140, s[0:1]
	s_add_i32 m0, s53, 0x12000
	s_add_u32 s17, s13, s15
	s_addc_u32 s19, s26, s14
	s_add_u32 s14, s0, s2
	global_load_lds_dwordx4 v38, s[0:1]
	s_addc_u32 s15, s1, s3
	s_add_i32 m0, s53, 0x14000
	v_lshl_add_u64 v[4:5], s[14:15], 0, v[140:141]
	global_load_lds_dwordx4 v140, s[14:15]
	s_add_i32 m0, s53, 0x16000
	s_add_u32 s18, s17, s64
	s_addc_u32 s19, s19, s16
	s_add_i32 s54, s53, 0x2000
	v_lshl_add_u64 v[6:7], s[14:15], 0, v[38:39]
	global_load_lds_dwordx4 v38, s[14:15]
	s_mov_b32 m0, s53
	s_add_u32 s14, s18, s2
	global_load_lds_dwordx4 v142, s[18:19]
	s_mov_b32 m0, s54
	s_addc_u32 s15, s19, s3
	s_add_i32 s55, s53, 0x4000
	global_load_lds_dwordx4 v42, s[18:19]
	s_mov_b32 m0, s55
	s_add_i32 s56, s53, 0x6000
	global_load_lds_dwordx4 v142, s[14:15]
	s_mov_b32 m0, s56
	s_cmp_eq_u32 s29, 1
	global_load_lds_dwordx4 v42, s[14:15]
	v_lshl_add_u64 v[0:1], s[0:1], 0, v[140:141]
	v_lshl_add_u64 v[2:3], s[0:1], 0, v[38:39]
	v_lshl_add_u64 v[8:9], s[18:19], 0, v[142:143]
	v_lshl_add_u64 v[10:11], s[18:19], 0, v[42:43]
	s_cselect_b64 s[14:15], -1, 0
	s_cmp_lg_u32 s29, 1
	s_cbranch_scc1 .LBB0_64
	s_barrier

; __device__ __forceinline__ unsigned pk2(float lo, float hi) { f32x2_t v = {lo, hi}; bf16x2_t b = __builtin_convertvector(v, bf16x2_t); return __builtin_bit_cast(unsigned, b); }
; __global__ void __launch_bounds__(NTHR, 2) mk_fwd(Args args) {
;     ...
;                 for (int r = gw; r < 512; r += NGW) { const int t = (r < 256) ? r : (TB + r - 256);
;                     const f32x4* sp = (const f32x4*)((const float*)(ws + O_CQ) + (size_t)r * 1024);
; #pragma unroll
;                     for (int j = 0; j < 4; ++j) { f32x4 a = sp[64 * j + lane];
; #pragma unroll
;                         for (int q = 1; q < 6; ++q) a = a + sp[(size_t)q * 512 * 256 + 64 * j + lane];
;                         u32x2 o; o.x = pk2(a[0], a[1]); o.y = pk2(a[2], a[3]); ((u32x2*)(HM + (size_t)t * 1024))[64 * j + lane] = o; } }
;                 xcd_barrier(xbar);
.LBB0_155:
	s_andn2_b64 vcc, exec, s[0:1]
	s_cbranch_vccnz .LBB0_255
	v_readlane_b32 s18, v254, 21
	v_readlane_b32 s24, v254, 23
	v_readlane_b32 s19, v254, 22
	v_readlane_b32 s25, v254, 24
	s_mov_b32 s13, 0xa00000
	v_readlane_b32 s0, v254, 27
	s_nop 3
	s_cmp_eq_u32 s0, 3
	s_mov_b64 s[0:1], exec
	s_cbranch_scc1 .LBB0_211
	s_cmpk_gt_i32 s18, 0x1ff
	s_cbranch_scc1 .LBB0_159
	s_ashr_i32 s19, s18, 31
	s_lshl_b64 s[0:1], s[18:19], 12
	s_add_u32 s0, s4, s0
	v_lshlrev_b32_e32 v2, 4, v202
	v_mov_b32_e32 v3, v36
	s_addc_u32 s1, s5, s1
	v_lshlrev_b32_e32 v0, 3, v202
	v_mov_b32_e32 v1, v36
	v_lshl_add_u64 v[2:3], s[0:1], 0, v[2:3]
	s_mov_b64 s[0:1], 0xf4e0000
	s_ashr_i32 s25, s24, 31
	v_lshl_add_u64 v[0:1], s[20:21], 0, v[0:1]
	v_lshl_add_u64 v[2:3], v[2:3], 0, s[0:1]
	s_lshl_b64 s[0:1], s[24:25], 12
	s_mov_b32 s2, s18

; #define PG8_LAS __attribute__((address_space(3)))
;     asm volatile("" : "+s"(K), "+s"(N), "+s"(nsplit));
;     int gd_ = (int)gridDim.x, bi_ = (int)blockIdx.x; asm volatile("" : "+s"(gd_), "+s"(bi_));
;     bi_ = (bi_ + gd_ - (rot % gd_)) % gd_;
;     const int kloop = K / nsplit;
;     pg8::Gemm g{A, Bt, MT, N, K, kloop}; CtxSplitOrder S{N / 256, nsplit, kloop, gd_, bi_};
;     pg8::gemm_phase<Epi, CtxSplitOrder, true, true>((PG8_LAS unsigned char*)lds, g, S, E);
; __global__ void __launch_bounds__(NTHR, 2) mk_fwd(Args args) {
;     ...
;                 { EpiPartial E{(float*)(ws + O_GATES), 256 * 2}; run_gemm_ctx(lds, HM, (const bf16_t*)(ws + O_WOUT), 1024, 1024, 4, E); }
.LBB0_233:
	v_readlane_b32 s10, v253, 0
	s_mov_b32 s27, 4
	s_movk_i32 s0, 0x400
	s_movk_i32 s1, 0x400
	s_mov_b32 s2, s81
	s_mov_b32 s36, s10
	s_abs_i32 s3, s36
	v_cvt_f32_u32_e32 v0, s3
	v_readlane_b32 s11, v253, 1
	s_sub_i32 s11, 0, s3
	s_add_i32 s2, s2, s36
	v_rcp_iflag_f32_e32 v0, v0
	s_ashr_i32 s10, s2, 31
	s_abs_i32 s2, s2
	v_mov_b32_e32 v18, v203
	v_mul_f32_e32 v0, 0x4f7ffffe, v0
	v_cvt_u32_f32_e32 v0, v0
	s_nop 0
	v_readfirstlane_b32 s24, v18
	v_readfirstlane_b32 s14, v0
	s_mul_i32 s11, s11, s14
	s_mul_hi_u32 s11, s14, s11
	s_add_i32 s14, s14, s11
	s_mul_hi_u32 s11, s2, s14
	s_mul_i32 s11, s11, s3
	s_sub_i32 s2, s2, s11
	s_sub_i32 s11, s2, s3
	s_cmp_ge_u32 s2, s3
	s_cselect_b32 s2, s11, s2
	s_sub_i32 s11, s2, s3
	s_cmp_ge_u32 s2, s3
	s_cselect_b32 s2, s11, s2
	s_xor_b32 s2, s2, s10
	s_sub_i32 s37, s2, s10
	s_ashr_i32 s2, s1, 31
	s_lshr_b32 s2, s2, 24
	s_add_i32 s1, s1, s2
	s_ashr_i32 s42, s1, 8
	s_mul_i32 s1, s42, s27
	s_lshl_b32 s43, s1, 1
	v_readlane_b32 s1, v254, 27
	s_nop 3
	s_cmp_eq_u32 s1, 3
	s_cbranch_scc1 .LBB0_255
	s_cmp_ge_i32 s37, s43
	s_cbranch_scc1 .LBB0_255
; #define PG8_STAGE(bufoff, gbase, voff) do { _Pragma("unroll") for (int _i = 0; _i < 2; ++_i) \
;         __builtin_amdgcn_global_load_lds((const unsigned*)((const char*)(gbase) + (voff)[_i]), (PG8_LAS unsigned*)(lds + (bufoff) + ldsw + _i * 8192), 16, 0, 0); } while (0)
; #define PG8_WAIT_V(n) asm volatile("s_waitcnt vmcnt(" #n ")" ::: "memory")
; #define PG8_BAR __builtin_amdgcn_s_barrier()
; template <class Epi, class Sched, bool ALIGN_EPI = false, bool SP2 = false>
; __device__ __forceinline__ void gemm_phase(PG8_LAS unsigned char* lds, const Gemm g, const Sched& S, const Epi& E) {
;     ...
;     const int tid = tid_, wid = __builtin_amdgcn_readfirstlane(tid >> 6), lane = tid & 63, wr = wid >> 2, wc = wid & 3, fr = lane & 15, fq = lane >> 4;
;     const int K = g.K, nt = g.Kloop / BK;
;     unsigned voffA[2], voffB[2];
; #pragma unroll
;     for (int i = 0; i < 2; ++i) { int R, C; stage_rc(tid * 16 + i * 8192, R, C); const int Rb = Epi::PERM ? ((R & ~31) + perm32(R & 31)) : R;
;         voffA[i] = (unsigned)(R * K + C) * 2u; voffB[i] = (unsigned)(Rb * K + C) * 2u; }
;     const size_t kstep = (size_t)(BK * 2);
;     const size_t hstep = (size_t)HALF * K * 2;
;     const size_t tstep = 2 * hstep;
;     const unsigned ldsw = (unsigned)wid * 1024u;
;     const int aoff = lds_byte(wr * 64 + fr, fq * 8), boff = lds_byte(wc * 32 + fr, fq * 8);
;     ...
;     Unit cur, nxt; int ui = 0;
;     if (!S.next(0, cur)) return;
;     f32x4 acc[2][2][4][2];
; #pragma unroll
;     for (int a = 0; a < 2; ++a)
; #pragma unroll
;         for (int b = 0; b < 2; ++b)
; #pragma unroll
;             for (int m = 0; m < 4; ++m)
; #pragma unroll
;                 for (int n = 0; n < 2; ++n) acc[a][b][m][n] = (f32x4){0.f, 0.f, 0.f, 0.f};
;     bf16x8 At[4][2], B0[2][2], B1[2][2];
;     const char* cA = (const char*)g.A + (size_t)cur.pm * tstep + cur.kb; const char* cB = (const char*)g.Bt + (size_t)cur.pn * tstep + cur.kb;
;     S.a_ready(cur);
;     if constexpr (SP2) {
;         PG8_STAGE(PG8_SB(0, 0), cB, voffB); PG8_STAGE(PG8_SB(0, 1), cB + hstep, voffB); PG8_STAGE(PG8_SA(0, 0), cA, voffA); PG8_STAGE(PG8_SA(0, 1), cA + hstep, voffA);
;         if (wr == 1) PG8_BAR;
;         PG8_WAIT_V(2); PG8_BAR;
;         PG8_STAGE(PG8_SB(1, 0), cB + kstep, voffB); PG8_STAGE(PG8_SA(1, 0), cA + kstep, voffA); PG8_STAGE(PG8_SB(1, 1), cB + hstep + kstep, voffB);
;         PG8_WAIT_V(6); PG8_BAR;
	s_abs_i32 s45, s27
	v_cvt_f32_u32_e32 v0, s45
	s_sub_i32 s10, 0, s45
	s_abs_i32 s3, s0
	s_ashr_i32 s1, s0, 31
	v_rcp_iflag_f32_e32 v0, v0
	s_ashr_i32 s44, s27, 31
	s_xor_b32 s2, s1, s44
	v_mov_b32_e32 v141, v36
	v_mul_f32_e32 v0, 0x4f7ffffe, v0
	v_cvt_u32_f32_e32 v0, v0
	v_mov_b32_e32 v39, v36
	v_mov_b32_e32 v143, v36
	v_mov_b32_e32 v43, v36
	v_readfirstlane_b32 s46, v0
	v_lshlrev_b32_e32 v0, 4, v18
	v_add_u32_e32 v1, 0x2000, v0
	v_ashrrev_i32_e32 v2, 31, v1
	v_lshrrev_b32_e32 v2, 22, v2
	v_add_u32_e32 v2, v1, v2
	v_ashrrev_i32_e32 v2, 10, v2
	v_mul_i32_i24_e32 v3, 0x400, v2
	s_mul_i32 s10, s10, s46
	v_sub_u32_e32 v1, v1, v3
	s_mul_hi_u32 s10, s46, s10
	v_lshrrev_b32_e32 v3, 4, v1
	s_add_i32 s46, s46, s10
	v_bitop3_b32 v1, v3, v1, 32 bitop3:0x6c
	s_mul_hi_u32 s10, s3, s46
	v_ashrrev_i32_e32 v3, 31, v1
	s_mul_i32 s11, s10, s45
	v_lshrrev_b32_e32 v3, 26, v3
	s_sub_i32 s3, s3, s11
	v_add_u32_e32 v3, v1, v3
	v_lshlrev_b32_e32 v5, 3, v2
	s_add_i32 s11, s10, 1
	s_sub_i32 s14, s3, s45
	v_ashrrev_i32_e32 v4, 6, v3
	v_and_b32_e32 v5, -16, v5
	v_lshlrev_b32_e32 v2, 5, v2
	s_cmp_ge_u32 s3, s45
	v_add_u32_e32 v5, v4, v5
	v_and_b32_e32 v12, 32, v2
	v_and_b32_e32 v2, 0xc0, v3
	s_cselect_b32 s3, s14, s3
	v_and_b32_e32 v4, 3, v4
	s_mov_b32 s14, 0x7fffffe0
	v_lshrrev_b32_e32 v6, 2, v5
	v_lshlrev_b32_e32 v7, 1, v5
	v_sub_u32_e32 v1, v1, v2
	v_and_or_b32 v4, v5, s14, v4
	v_and_b32_e32 v6, 4, v6
	v_and_b32_e32 v7, 24, v7
	v_ashrrev_i16_sdwa v1, v217, sext(v1) dst_sel:DWORD dst_unused:UNUSED_PAD src0_sel:DWORD src1_sel:BYTE_0
	v_or3_b32 v4, v4, v6, v7
	v_bfe_i32 v13, v1, 0, 16
	v_mul_lo_u32 v4, v4, s0
	v_add_u32_e32 v1, v12, v13
	v_mul_lo_u32 v14, v5, s0
	v_add_lshl_u32 v38, v4, v1, 1
	v_add_lshl_u32 v42, v1, v14, 1
	v_bfe_i32 v1, v18, 27, 1
	v_lshrrev_b32_e32 v1, 22, v1
	v_add_u32_e32 v1, v0, v1
	v_and_b32_e32 v1, 0xfffffc00, v1
	v_sub_u32_e32 v0, v0, v1
	v_lshrrev_b32_e32 v1, 4, v0
	v_ashrrev_i32_e32 v3, 31, v18
	s_cselect_b32 s10, s11, s10
	v_bitop3_b32 v0, v1, v0, 32 bitop3:0x6c
	v_lshrrev_b32_e32 v3, 26, v3
	s_add_i32 s11, s10, 1
	v_ashrrev_i32_e32 v1, 31, v0
	v_add_u32_e32 v3, v18, v3
	s_cmp_ge_u32 s3, s45
	v_lshrrev_b32_e32 v1, 26, v1
	v_ashrrev_i32_e32 v3, 6, v3
	s_cselect_b32 s3, s11, s10
	v_add_u32_e32 v1, v0, v1
	v_lshlrev_b32_e32 v4, 3, v3
	s_abs_i32 s15, s37
	v_ashrrev_i32_e32 v2, 6, v1
	v_and_b32_e32 v4, -16, v4
	s_mul_hi_u32 s16, s15, s46
	v_add_u32_e32 v4, v2, v4
	v_and_b32_e32 v2, 3, v2
	s_mul_i32 s17, s16, s45
	s_xor_b32 s3, s3, s2
	s_ashr_i32 s28, s24, 6
	v_and_or_b32 v2, v4, s14, v2
	s_ashr_i32 s14, s37, 31
	s_sub_i32 s15, s15, s17
	s_sub_i32 s25, s3, s2
	s_ashr_i32 s29, s24, 8
	s_lshl_b64 s[2:3], s[0:1], 8
	s_lshl_b64 s[10:11], s[0:1], 9
	s_lshl_b32 s47, s28, 10
	s_xor_b32 s14, s14, s44
	s_add_i32 s17, s16, 1
	s_sub_i32 s18, s15, s45
	v_and_b32_e32 v1, 0xc0, v1
	s_cmp_ge_u32 s15, s45
	v_lshrrev_b32_e32 v5, 2, v4
	v_lshlrev_b32_e32 v6, 1, v4
	v_sub_u32_e32 v0, v0, v1
	s_cselect_b32 s16, s17, s16
	v_and_b32_e32 v5, 4, v5
	v_and_b32_e32 v6, 24, v6
	v_lshlrev_b32_e32 v3, 5, v3
	v_ashrrev_i16_sdwa v0, v217, sext(v0) dst_sel:DWORD dst_unused:UNUSED_PAD src0_sel:DWORD src1_sel:BYTE_0
	s_cselect_b32 s15, s18, s15
	s_add_i32 s17, s16, 1
	v_or3_b32 v2, v2, v5, v6
	v_and_b32_e32 v15, 32, v3
	v_bfe_i32 v16, v0, 0, 16
	s_cmp_ge_u32 s15, s45
	v_mul_lo_u32 v2, v2, s0
	v_add_u32_e32 v0, v15, v16
	v_mul_lo_u32 v17, v4, s0
	s_cselect_b32 s15, s17, s16
	s_abs_i32 s49, s42
	v_add_lshl_u32 v140, v2, v0, 1
	v_add_lshl_u32 v142, v0, v17, 1
	v_cvt_f32_u32_e32 v0, s49
	s_sub_i32 s18, 0, s49
	s_xor_b32 s15, s15, s14
	s_sub_i32 s14, s15, s14
	v_rcp_iflag_f32_e32 v0, v0
	s_abs_i32 s17, s14
	s_mul_i32 s15, s14, s27
	s_ashr_i32 s16, s14, 31
	v_mul_f32_e32 v0, 0x4f7ffffe, v0
	v_cvt_u32_f32_e32 v0, v0
	s_ashr_i32 s48, s42, 31
	s_sub_i32 s15, s37, s15
	s_xor_b32 s16, s16, s48
	v_readfirstlane_b32 s50, v0
	s_mul_i32 s18, s18, s50
	s_mul_hi_u32 s18, s50, s18
	s_add_i32 s50, s50, s18
	s_mul_hi_u32 s18, s17, s50
	s_mul_i32 s19, s18, s49
	s_sub_i32 s17, s17, s19
	s_add_i32 s19, s18, 1
	s_sub_i32 s30, s17, s49
	s_cmp_ge_u32 s17, s49
	s_cselect_b32 s18, s19, s18
	s_cselect_b32 s17, s30, s17
	s_add_i32 s19, s18, 1
	s_cmp_ge_u32 s17, s49
	s_cselect_b32 s17, s19, s18
	s_xor_b32 s17, s17, s16
	s_sub_i32 s16, s17, s16
	s_mul_i32 s17, s16, s42
	s_sub_i32 s61, s14, s17
	s_cmp_eq_u32 s16, 0
	s_cselect_b32 s60, 0, 33
	s_lshr_b64 s[0:1], s[0:1], 23
	s_mul_i32 s1, s0, s60
	s_mul_hi_u32 s14, s10, s60
	s_add_i32 s14, s14, s1
	s_ashr_i32 s1, s61, 31
	s_mul_i32 s15, s15, s25
	s_mul_i32 s1, s10, s1
	s_mul_hi_u32 s17, s10, s61
	s_lshl_b32 s62, s15, 1
	s_add_i32 s1, s17, s1
	s_mul_i32 s0, s0, s61
	s_ashr_i32 s16, s62, 31
	s_add_i32 s1, s1, s0
	s_mul_i32 s0, s10, s61
	s_add_u32 s0, s13, s0
	s_addc_u32 s1, s26, s1
	s_add_u32 s0, s0, s62
	s_addc_u32 s1, s1, s16
	s_add_i32 s51, s47, 0
	s_add_i32 m0, s51, 0x10000
	s_mul_i32 s15, s10, s60
	global_load_lds_dwordx4 v140, s[0:1]
	s_add_i32 m0, s51, 0x12000
	s_add_u32 s17, s20, s15
	s_addc_u32 s19, s21, s14
	s_add_u32 s14, s0, s2
	global_load_lds_dwordx4 v38, s[0:1]
	s_addc_u32 s15, s1, s3
	s_add_i32 m0, s51, 0x14000
	v_lshl_add_u64 v[4:5], s[14:15], 0, v[140:141]
	global_load_lds_dwordx4 v140, s[14:15]
	s_add_i32 m0, s51, 0x16000
	s_add_u32 s18, s17, s62
	s_addc_u32 s19, s19, s16
	s_add_i32 s52, s51, 0x2000
	v_lshl_add_u64 v[6:7], s[14:15], 0, v[38:39]
	global_load_lds_dwordx4 v38, s[14:15]
	s_mov_b32 m0, s51
	s_add_u32 s14, s18, s2
	global_load_lds_dwordx4 v142, s[18:19]
	s_mov_b32 m0, s52
	s_addc_u32 s15, s19, s3
	s_add_i32 s53, s51, 0x4000
	global_load_lds_dwordx4 v42, s[18:19]
	s_mov_b32 m0, s53
	s_add_i32 s54, s51, 0x6000
	global_load_lds_dwordx4 v142, s[14:15]
	s_mov_b32 m0, s54
	s_cmp_eq_u32 s29, 1
	global_load_lds_dwordx4 v42, s[14:15]
	v_lshl_add_u64 v[0:1], s[0:1], 0, v[140:141]
	v_lshl_add_u64 v[2:3], s[0:1], 0, v[38:39]
	v_lshl_add_u64 v[8:9], s[18:19], 0, v[142:143]
	v_lshl_add_u64 v[10:11], s[18:19], 0, v[42:43]
	s_cselect_b64 s[14:15], -1, 0
	s_cmp_lg_u32 s29, 1
	s_cbranch_scc1 .LBB0_236
	s_barrier

; #define PG8_LAS __attribute__((address_space(3)))
;     asm volatile("" : "+s"(K), "+s"(N), "+s"(nsplit));
;     int gd_ = (int)gridDim.x, bi_ = (int)blockIdx.x; asm volatile("" : "+s"(gd_), "+s"(bi_));
;     bi_ = (bi_ + gd_ - (rot % gd_)) % gd_;
;     const int kloop = K / nsplit;
;     pg8::Gemm g{A, Bt, MT, N, K, kloop}; CtxSplitOrder S{N / 256, nsplit, kloop, gd_, bi_};
;     pg8::gemm_phase<Epi, CtxSplitOrder, true, true>((PG8_LAS unsigned char*)lds, g, S, E);
; __global__ void __launch_bounds__(NTHR, 2) mk_fwd(Args args) {
;     ...
;                 { EpiMergePart<0> E{ws, 256 * 2}; run_gemm_ctx(lds, (const bf16_t*)(ws + O_QA), (const bf16_t*)(ws + O_WBR), 1024, 512, 2, E, 64); }
.LBB0_322:
	v_readlane_b32 s2, v253, 0
	s_movk_i32 s1, 0x400
	s_movk_i32 s0, 0x200
	s_mov_b32 s51, 2
	v_readlane_b32 s3, v253, 1
	s_mov_b32 s52, s2
	s_mov_b32 s2, s81
	s_abs_i32 s3, s52
	v_cvt_f32_u32_e32 v0, s3
	s_sub_i32 s10, 0, s3
	s_add_i32 s2, s2, s52
	v_mov_b32_e32 v18, v203
	v_rcp_iflag_f32_e32 v0, v0
	s_nop 0
	v_readfirstlane_b32 s24, v18
	v_mul_f32_e32 v0, 0x4f7ffffe, v0
	v_cvt_u32_f32_e32 v0, v0
	s_nop 0
	v_readfirstlane_b32 s11, v0
	s_mul_i32 s10, s10, s11
	s_mul_hi_u32 s10, s11, s10
	s_add_i32 s11, s11, s10
	s_lshr_b32 s10, s11, 26
	s_mul_i32 s10, s10, s3
	s_sub_i32 s10, 64, s10
	s_sub_i32 s14, s10, s3
	s_cmp_ge_u32 s10, s3
	s_cselect_b32 s10, s14, s10
	s_sub_i32 s14, s10, s3
	s_cmp_ge_u32 s10, s3
	s_cselect_b32 s10, s14, s10
	s_sub_i32 s2, s2, s10
	s_ashr_i32 s10, s2, 31
	s_abs_i32 s2, s2
	s_mul_hi_u32 s11, s2, s11
	s_mul_i32 s11, s11, s3
	s_sub_i32 s2, s2, s11
	s_sub_i32 s11, s2, s3
	s_cmp_ge_u32 s2, s3
	s_cselect_b32 s2, s11, s2
	s_sub_i32 s11, s2, s3
	s_cmp_ge_u32 s2, s3
	s_cselect_b32 s2, s11, s2
	s_ashr_i32 s3, s1, 31
	s_xor_b32 s2, s2, s10
	s_sub_i32 s53, s2, s10
	s_lshr_b32 s2, s3, 24
	s_add_i32 s1, s1, s2
	s_ashr_i32 s54, s1, 8
	s_mul_i32 s1, s54, s51
	s_lshl_b32 s55, s1, 1
	v_readlane_b32 s1, v254, 27
	s_nop 3
	s_cmp_eq_u32 s1, 3
	s_cbranch_scc1 .LBB0_344
	s_cmp_ge_i32 s53, s55
	s_cbranch_scc1 .LBB0_344
; #define PG8_STAGE(bufoff, gbase, voff) do { _Pragma("unroll") for (int _i = 0; _i < 2; ++_i) \
;         __builtin_amdgcn_global_load_lds((const unsigned*)((const char*)(gbase) + (voff)[_i]), (PG8_LAS unsigned*)(lds + (bufoff) + ldsw + _i * 8192), 16, 0, 0); } while (0)
; #define PG8_WAIT_V(n) asm volatile("s_waitcnt vmcnt(" #n ")" ::: "memory")
; #define PG8_BAR __builtin_amdgcn_s_barrier()
; template <class Epi, class Sched, bool ALIGN_EPI = false, bool SP2 = false>
; __device__ __forceinline__ void gemm_phase(PG8_LAS unsigned char* lds, const Gemm g, const Sched& S, const Epi& E) {
;     ...
;     const int tid = tid_, wid = __builtin_amdgcn_readfirstlane(tid >> 6), lane = tid & 63, wr = wid >> 2, wc = wid & 3, fr = lane & 15, fq = lane >> 4;
;     const int K = g.K, nt = g.Kloop / BK;
;     unsigned voffA[2], voffB[2];
; #pragma unroll
;     for (int i = 0; i < 2; ++i) { int R, C; stage_rc(tid * 16 + i * 8192, R, C); const int Rb = Epi::PERM ? ((R & ~31) + perm32(R & 31)) : R;
;         voffA[i] = (unsigned)(R * K + C) * 2u; voffB[i] = (unsigned)(Rb * K + C) * 2u; }
;     const size_t kstep = (size_t)(BK * 2);
;     const size_t hstep = (size_t)HALF * K * 2;
;     const size_t tstep = 2 * hstep;
;     const unsigned ldsw = (unsigned)wid * 1024u;
;     const int aoff = lds_byte(wr * 64 + fr, fq * 8), boff = lds_byte(wc * 32 + fr, fq * 8);
;     ...
;     Unit cur, nxt; int ui = 0;
;     if (!S.next(0, cur)) return;
;     f32x4 acc[2][2][4][2];
; #pragma unroll
;     for (int a = 0; a < 2; ++a)
; #pragma unroll
;         for (int b = 0; b < 2; ++b)
; #pragma unroll
;             for (int m = 0; m < 4; ++m)
; #pragma unroll
;                 for (int n = 0; n < 2; ++n) acc[a][b][m][n] = (f32x4){0.f, 0.f, 0.f, 0.f};
;     bf16x8 At[4][2], B0[2][2], B1[2][2];
;     const char* cA = (const char*)g.A + (size_t)cur.pm * tstep + cur.kb; const char* cB = (const char*)g.Bt + (size_t)cur.pn * tstep + cur.kb;
;     S.a_ready(cur);
;     if constexpr (SP2) {
;         PG8_STAGE(PG8_SB(0, 0), cB, voffB); PG8_STAGE(PG8_SB(0, 1), cB + hstep, voffB); PG8_STAGE(PG8_SA(0, 0), cA, voffA); PG8_STAGE(PG8_SA(0, 1), cA + hstep, voffA);
;         if (wr == 1) PG8_BAR;
;         PG8_WAIT_V(2); PG8_BAR;
;         PG8_STAGE(PG8_SB(1, 0), cB + kstep, voffB); PG8_STAGE(PG8_SA(1, 0), cA + kstep, voffA); PG8_STAGE(PG8_SB(1, 1), cB + hstep + kstep, voffB);
;         PG8_WAIT_V(6); PG8_BAR;
	s_abs_i32 s57, s51
	v_cvt_f32_u32_e32 v0, s57
	s_sub_i32 s10, 0, s57
	s_abs_i32 s3, s0
	s_ashr_i32 s1, s0, 31
	v_rcp_iflag_f32_e32 v0, v0
	s_ashr_i32 s56, s51, 31
	s_xor_b32 s2, s1, s56
	s_waitcnt vmcnt(0)
	v_mov_b32_e32 v141, v36
	v_mul_f32_e32 v0, 0x4f7ffffe, v0
	v_cvt_u32_f32_e32 v0, v0
	v_mov_b32_e32 v39, v36
	v_mov_b32_e32 v143, v36
	v_mov_b32_e32 v43, v36
	v_readfirstlane_b32 s58, v0
	v_lshlrev_b32_e32 v0, 4, v18
	v_add_u32_e32 v1, 0x2000, v0
	v_ashrrev_i32_e32 v2, 31, v1
	v_lshrrev_b32_e32 v2, 22, v2
	v_add_u32_e32 v2, v1, v2
	v_ashrrev_i32_e32 v2, 10, v2
	v_mul_i32_i24_e32 v3, 0x400, v2
	s_mul_i32 s10, s10, s58
	v_sub_u32_e32 v1, v1, v3
	s_mul_hi_u32 s10, s58, s10
	v_lshrrev_b32_e32 v3, 4, v1
	s_add_i32 s58, s58, s10
	v_bitop3_b32 v1, v3, v1, 32 bitop3:0x6c
	s_mul_hi_u32 s10, s3, s58
	v_ashrrev_i32_e32 v3, 31, v1
	s_mul_i32 s11, s10, s57
	v_lshrrev_b32_e32 v3, 26, v3
	s_sub_i32 s3, s3, s11
	v_add_u32_e32 v3, v1, v3
	v_lshlrev_b32_e32 v5, 3, v2
	s_add_i32 s11, s10, 1
	s_sub_i32 s14, s3, s57
	v_ashrrev_i32_e32 v4, 6, v3
	v_and_b32_e32 v5, -16, v5
	v_lshlrev_b32_e32 v2, 5, v2
	s_cmp_ge_u32 s3, s57
	v_add_u32_e32 v5, v4, v5
	v_and_b32_e32 v12, 32, v2
	v_and_b32_e32 v2, 0xc0, v3
	s_cselect_b32 s3, s14, s3
	v_and_b32_e32 v4, 3, v4
	s_mov_b32 s14, 0x7fffffe0
	v_lshrrev_b32_e32 v6, 2, v5
	v_lshlrev_b32_e32 v7, 1, v5
	v_sub_u32_e32 v1, v1, v2
	v_and_or_b32 v4, v5, s14, v4
	v_and_b32_e32 v6, 4, v6
	v_and_b32_e32 v7, 24, v7
	v_ashrrev_i16_sdwa v1, v217, sext(v1) dst_sel:DWORD dst_unused:UNUSED_PAD src0_sel:DWORD src1_sel:BYTE_0
	v_or3_b32 v4, v4, v6, v7
	v_bfe_i32 v13, v1, 0, 16
	v_mul_lo_u32 v4, v4, s0
	v_add_u32_e32 v1, v12, v13
	v_mul_lo_u32 v14, v5, s0
	v_add_lshl_u32 v38, v4, v1, 1
	v_add_lshl_u32 v42, v1, v14, 1
	v_bfe_i32 v1, v18, 27, 1
	v_lshrrev_b32_e32 v1, 22, v1
	v_add_u32_e32 v1, v0, v1
	v_and_b32_e32 v1, 0xfffffc00, v1
	v_sub_u32_e32 v0, v0, v1
	v_lshrrev_b32_e32 v1, 4, v0
	v_ashrrev_i32_e32 v3, 31, v18
	s_cselect_b32 s10, s11, s10
	v_bitop3_b32 v0, v1, v0, 32 bitop3:0x6c
	v_lshrrev_b32_e32 v3, 26, v3
	s_add_i32 s11, s10, 1
	v_ashrrev_i32_e32 v1, 31, v0
	v_add_u32_e32 v3, v18, v3
	s_cmp_ge_u32 s3, s57
	v_lshrrev_b32_e32 v1, 26, v1
	v_ashrrev_i32_e32 v3, 6, v3
	s_cselect_b32 s3, s11, s10
	v_add_u32_e32 v1, v0, v1
	v_lshlrev_b32_e32 v4, 3, v3
	s_abs_i32 s15, s53
	v_ashrrev_i32_e32 v2, 6, v1
	v_and_b32_e32 v4, -16, v4
	s_mul_hi_u32 s18, s15, s58
	v_add_u32_e32 v4, v2, v4
	v_and_b32_e32 v2, 3, v2
	s_mul_i32 s19, s18, s57
	s_xor_b32 s3, s3, s2
	s_ashr_i32 s16, s24, 6
	v_and_or_b32 v2, v4, s14, v2
	s_ashr_i32 s14, s53, 31
	s_sub_i32 s15, s15, s19
	s_sub_i32 s25, s3, s2
	s_ashr_i32 s17, s24, 8
	s_lshl_b64 s[2:3], s[0:1], 8
	s_lshl_b64 s[10:11], s[0:1], 9
	s_lshl_b32 s59, s16, 10
	s_xor_b32 s14, s14, s56
	s_add_i32 s19, s18, 1
	s_sub_i32 s28, s15, s57
	v_and_b32_e32 v1, 0xc0, v1
	s_cmp_ge_u32 s15, s57
	v_lshrrev_b32_e32 v5, 2, v4
	v_lshlrev_b32_e32 v6, 1, v4
	v_sub_u32_e32 v0, v0, v1
	s_cselect_b32 s18, s19, s18
	v_and_b32_e32 v5, 4, v5
	v_and_b32_e32 v6, 24, v6
	v_lshlrev_b32_e32 v3, 5, v3
	v_ashrrev_i16_sdwa v0, v217, sext(v0) dst_sel:DWORD dst_unused:UNUSED_PAD src0_sel:DWORD src1_sel:BYTE_0
	s_cselect_b32 s15, s28, s15
	s_add_i32 s19, s18, 1
	v_or3_b32 v2, v2, v5, v6
	v_and_b32_e32 v15, 32, v3
	v_bfe_i32 v16, v0, 0, 16
	s_cmp_ge_u32 s15, s57
	v_mul_lo_u32 v2, v2, s0
	v_add_u32_e32 v0, v15, v16
	v_mul_lo_u32 v17, v4, s0
	s_cselect_b32 s15, s19, s18
	s_abs_i32 s61, s54
	v_add_lshl_u32 v140, v2, v0, 1
	v_add_lshl_u32 v142, v0, v17, 1
	v_cvt_f32_u32_e32 v0, s61
	s_sub_i32 s28, 0, s61
	s_xor_b32 s15, s15, s14
	s_sub_i32 s14, s15, s14
	v_rcp_iflag_f32_e32 v0, v0
	s_abs_i32 s19, s14
	s_mul_i32 s15, s14, s51
	s_ashr_i32 s18, s14, 31
	v_mul_f32_e32 v0, 0x4f7ffffe, v0
	v_cvt_u32_f32_e32 v0, v0
	s_ashr_i32 s60, s54, 31
	s_sub_i32 s15, s53, s15
	s_xor_b32 s18, s18, s60
	v_readfirstlane_b32 s62, v0
	s_mul_i32 s28, s28, s62
	s_mul_hi_u32 s28, s62, s28
	s_add_i32 s62, s62, s28
	s_mul_hi_u32 s28, s19, s62
	s_mul_i32 s29, s28, s61
	s_sub_i32 s19, s19, s29
	s_add_i32 s29, s28, 1
	s_sub_i32 s30, s19, s61
	s_cmp_ge_u32 s19, s61
	s_cselect_b32 s28, s29, s28
	s_cselect_b32 s19, s30, s19
	s_add_i32 s29, s28, 1
	s_cmp_ge_u32 s19, s61
	s_cselect_b32 s19, s29, s28
	s_xor_b32 s19, s19, s18
	s_sub_i32 s18, s19, s18
	s_mul_i32 s19, s18, s54
	s_sub_i32 s80, s14, s19
	s_cmp_eq_u32 s18, 0
	s_cselect_b32 s79, 0, 33
	s_lshr_b64 s[0:1], s[0:1], 23
	s_mul_i32 s1, s0, s79
	s_mul_hi_u32 s14, s10, s79
	s_add_i32 s14, s14, s1
	s_ashr_i32 s1, s80, 31
	s_mul_i32 s15, s15, s25
	s_mul_i32 s1, s10, s1
	s_mul_hi_u32 s18, s10, s80
	s_lshl_b32 s78, s15, 1
	s_add_i32 s1, s18, s1
	s_mul_i32 s0, s0, s80
	s_ashr_i32 s19, s78, 31
	s_add_i32 s1, s1, s0
	s_mul_i32 s0, s10, s80
	s_add_u32 s0, s27, s0
	s_addc_u32 s1, s36, s1
	s_add_u32 s0, s0, s78
	s_addc_u32 s1, s1, s19
	s_add_i32 s63, s59, 0
	s_add_i32 m0, s63, 0x10000
	s_mul_i32 s15, s10, s79
	global_load_lds_dwordx4 v140, s[0:1]
	s_add_i32 m0, s63, 0x12000
	s_add_u32 s18, s13, s15
	s_addc_u32 s28, s26, s14
	s_add_u32 s14, s0, s2
	global_load_lds_dwordx4 v38, s[0:1]
	s_addc_u32 s15, s1, s3
	s_add_i32 m0, s63, 0x14000
	v_lshl_add_u64 v[4:5], s[14:15], 0, v[140:141]
	global_load_lds_dwordx4 v140, s[14:15]
	s_add_i32 m0, s63, 0x16000
	s_add_u32 s18, s18, s78
	s_addc_u32 s19, s28, s19
	s_add_i32 s64, s63, 0x2000
	v_lshl_add_u64 v[6:7], s[14:15], 0, v[38:39]
	global_load_lds_dwordx4 v38, s[14:15]
	s_mov_b32 m0, s63
	s_add_u32 s14, s18, s2
	global_load_lds_dwordx4 v142, s[18:19]
	s_mov_b32 m0, s64
	s_addc_u32 s15, s19, s3
	s_add_i32 s65, s63, 0x4000
	global_load_lds_dwordx4 v42, s[18:19]
	s_mov_b32 m0, s65
	s_add_i32 s66, s63, 0x6000
	global_load_lds_dwordx4 v142, s[14:15]
	s_mov_b32 m0, s66
	s_cmp_eq_u32 s17, 1
	global_load_lds_dwordx4 v42, s[14:15]
	v_lshl_add_u64 v[0:1], s[0:1], 0, v[140:141]
	v_lshl_add_u64 v[2:3], s[0:1], 0, v[38:39]
	v_lshl_add_u64 v[8:9], s[18:19], 0, v[142:143]
	v_lshl_add_u64 v[10:11], s[18:19], 0, v[42:43]
	s_cselect_b64 s[14:15], -1, 0
	s_cmp_lg_u32 s17, 1
	s_cbranch_scc1 .LBB0_325
	s_barrier

; #define PG8_LAS __attribute__((address_space(3)))
;     asm volatile("" : "+s"(K), "+s"(N), "+s"(nsplit));
;     int gd_ = (int)gridDim.x, bi_ = (int)blockIdx.x; asm volatile("" : "+s"(gd_), "+s"(bi_));
;     bi_ = (bi_ + gd_ - (rot % gd_)) % gd_;
;     const int kloop = K / nsplit;
;     pg8::Gemm g{A, Bt, MT, N, K, kloop}; CtxSplitOrder S{N / 256, nsplit, kloop, gd_, bi_};
;     pg8::gemm_phase<Epi, CtxSplitOrder, true, true>((PG8_LAS unsigned char*)lds, g, S, E);
; __global__ void __launch_bounds__(NTHR, 2) mk_fwd(Args args) {
;     ...
;                 { EpiMergePart<1> E{ws, 256 * 2}; run_gemm_ctx(lds, (const bf16_t*)(ws + O_YB), (const bf16_t*)(ws + O_WBR) + (size_t)1024 * 512, 1024, 512, 2, E, 96); }
.LBB0_344:
	v_readlane_b32 s2, v253, 0
	s_movk_i32 s1, 0x400
	s_movk_i32 s0, 0x200
	s_mov_b32 s13, 2
	v_readlane_b32 s3, v253, 1
	s_mov_b32 s26, s2
	s_mov_b32 s2, s81
	s_abs_i32 s3, s26
	v_cvt_f32_u32_e32 v0, s3
	s_sub_i32 s10, 0, s3
	s_add_i32 s2, s2, s26
	v_mov_b32_e32 v18, v203
	v_rcp_iflag_f32_e32 v0, v0
	s_nop 0
	v_readfirstlane_b32 s24, v18
	v_mul_f32_e32 v0, 0x4f7ffffe, v0
	v_cvt_u32_f32_e32 v0, v0
	s_nop 0
	v_readfirstlane_b32 s11, v0
	s_mul_i32 s10, s10, s11
	s_mul_hi_u32 s10, s11, s10
	s_add_i32 s11, s11, s10
	s_mul_hi_u32 s10, s11, 0x60
	s_mul_i32 s10, s10, s3
	s_sub_i32 s10, 0x60, s10
	s_sub_i32 s14, s10, s3
	s_cmp_ge_u32 s10, s3
	s_cselect_b32 s10, s14, s10
	s_sub_i32 s14, s10, s3
	s_cmp_ge_u32 s10, s3
	s_cselect_b32 s10, s14, s10
	s_sub_i32 s2, s2, s10
	s_ashr_i32 s10, s2, 31
	s_abs_i32 s2, s2
	s_mul_hi_u32 s11, s2, s11
	s_mul_i32 s11, s11, s3
	s_sub_i32 s2, s2, s11
	s_sub_i32 s11, s2, s3
	s_cmp_ge_u32 s2, s3
	s_cselect_b32 s2, s11, s2
	s_sub_i32 s11, s2, s3
	s_cmp_ge_u32 s2, s3
	s_cselect_b32 s2, s11, s2
	s_ashr_i32 s3, s1, 31
	s_xor_b32 s2, s2, s10
	s_sub_i32 s27, s2, s10
	s_lshr_b32 s2, s3, 24
	s_add_i32 s1, s1, s2
	s_ashr_i32 s36, s1, 8
	s_mul_i32 s1, s36, s13
	s_lshl_b32 s42, s1, 1
	v_readlane_b32 s1, v254, 27
	s_nop 3
	s_cmp_eq_u32 s1, 3
	s_cbranch_scc1 .LBB0_366
	s_cmp_ge_i32 s27, s42
	s_cbranch_scc1 .LBB0_366
; #define PG8_STAGE(bufoff, gbase, voff) do { _Pragma("unroll") for (int _i = 0; _i < 2; ++_i) \
;         __builtin_amdgcn_global_load_lds((const unsigned*)((const char*)(gbase) + (voff)[_i]), (PG8_LAS unsigned*)(lds + (bufoff) + ldsw + _i * 8192), 16, 0, 0); } while (0)
; #define PG8_WAIT_V(n) asm volatile("s_waitcnt vmcnt(" #n ")" ::: "memory")
; #define PG8_BAR __builtin_amdgcn_s_barrier()
; template <class Epi, class Sched, bool ALIGN_EPI = false, bool SP2 = false>
; __device__ __forceinline__ void gemm_phase(PG8_LAS unsigned char* lds, const Gemm g, const Sched& S, const Epi& E) {
;     ...
;     const int tid = tid_, wid = __builtin_amdgcn_readfirstlane(tid >> 6), lane = tid & 63, wr = wid >> 2, wc = wid & 3, fr = lane & 15, fq = lane >> 4;
;     const int K = g.K, nt = g.Kloop / BK;
;     unsigned voffA[2], voffB[2];
; #pragma unroll
;     for (int i = 0; i < 2; ++i) { int R, C; stage_rc(tid * 16 + i * 8192, R, C); const int Rb = Epi::PERM ? ((R & ~31) + perm32(R & 31)) : R;
;         voffA[i] = (unsigned)(R * K + C) * 2u; voffB[i] = (unsigned)(Rb * K + C) * 2u; }
;     const size_t kstep = (size_t)(BK * 2);
;     const size_t hstep = (size_t)HALF * K * 2;
;     const size_t tstep = 2 * hstep;
;     const unsigned ldsw = (unsigned)wid * 1024u;
;     const int aoff = lds_byte(wr * 64 + fr, fq * 8), boff = lds_byte(wc * 32 + fr, fq * 8);
;     ...
;     Unit cur, nxt; int ui = 0;
;     if (!S.next(0, cur)) return;
;     f32x4 acc[2][2][4][2];
; #pragma unroll
;     for (int a = 0; a < 2; ++a)
; #pragma unroll
;         for (int b = 0; b < 2; ++b)
; #pragma unroll
;             for (int m = 0; m < 4; ++m)
; #pragma unroll
;                 for (int n = 0; n < 2; ++n) acc[a][b][m][n] = (f32x4){0.f, 0.f, 0.f, 0.f};
;     bf16x8 At[4][2], B0[2][2], B1[2][2];
;     const char* cA = (const char*)g.A + (size_t)cur.pm * tstep + cur.kb; const char* cB = (const char*)g.Bt + (size_t)cur.pn * tstep + cur.kb;
;     S.a_ready(cur);
;     if constexpr (SP2) {
;         PG8_STAGE(PG8_SB(0, 0), cB, voffB); PG8_STAGE(PG8_SB(0, 1), cB + hstep, voffB); PG8_STAGE(PG8_SA(0, 0), cA, voffA); PG8_STAGE(PG8_SA(0, 1), cA + hstep, voffA);
;         if (wr == 1) PG8_BAR;
;         PG8_WAIT_V(2); PG8_BAR;
;         PG8_STAGE(PG8_SB(1, 0), cB + kstep, voffB); PG8_STAGE(PG8_SA(1, 0), cA + kstep, voffA); PG8_STAGE(PG8_SB(1, 1), cB + hstep + kstep, voffB);
;         PG8_WAIT_V(6); PG8_BAR;
	s_abs_i32 s51, s13
	v_cvt_f32_u32_e32 v0, s51
	s_sub_i32 s10, 0, s51
	s_abs_i32 s3, s0
	s_ashr_i32 s1, s0, 31
	v_rcp_iflag_f32_e32 v0, v0
	s_ashr_i32 s43, s13, 31
	s_xor_b32 s2, s1, s43
	s_waitcnt vmcnt(0)
	v_mov_b32_e32 v141, v36
	v_mul_f32_e32 v0, 0x4f7ffffe, v0
	v_cvt_u32_f32_e32 v0, v0
	v_mov_b32_e32 v39, v36
	v_mov_b32_e32 v143, v36
	v_mov_b32_e32 v43, v36
	v_readfirstlane_b32 s52, v0
	v_lshlrev_b32_e32 v0, 4, v18
	v_add_u32_e32 v1, 0x2000, v0
	v_ashrrev_i32_e32 v2, 31, v1
	v_lshrrev_b32_e32 v2, 22, v2
	v_add_u32_e32 v2, v1, v2
	v_ashrrev_i32_e32 v2, 10, v2
	v_mul_i32_i24_e32 v3, 0x400, v2
	s_mul_i32 s10, s10, s52
	v_sub_u32_e32 v1, v1, v3
	s_mul_hi_u32 s10, s52, s10
	v_lshrrev_b32_e32 v3, 4, v1
	s_add_i32 s52, s52, s10
	v_bitop3_b32 v1, v3, v1, 32 bitop3:0x6c
	s_mul_hi_u32 s10, s3, s52
	v_ashrrev_i32_e32 v3, 31, v1
	s_mul_i32 s11, s10, s51
	v_lshrrev_b32_e32 v3, 26, v3
	s_sub_i32 s3, s3, s11
	v_add_u32_e32 v3, v1, v3
	v_lshlrev_b32_e32 v5, 3, v2
	s_add_i32 s11, s10, 1
	s_sub_i32 s14, s3, s51
	v_ashrrev_i32_e32 v4, 6, v3
	v_and_b32_e32 v5, -16, v5
	v_lshlrev_b32_e32 v2, 5, v2
	s_cmp_ge_u32 s3, s51
	v_add_u32_e32 v5, v4, v5
	v_and_b32_e32 v12, 32, v2
	v_and_b32_e32 v2, 0xc0, v3
	s_cselect_b32 s3, s14, s3
	v_and_b32_e32 v4, 3, v4
	s_mov_b32 s14, 0x7fffffe0
	v_lshrrev_b32_e32 v6, 2, v5
	v_lshlrev_b32_e32 v7, 1, v5
	v_sub_u32_e32 v1, v1, v2
	v_and_or_b32 v4, v5, s14, v4
	v_and_b32_e32 v6, 4, v6
	v_and_b32_e32 v7, 24, v7
	v_ashrrev_i16_sdwa v1, v217, sext(v1) dst_sel:DWORD dst_unused:UNUSED_PAD src0_sel:DWORD src1_sel:BYTE_0
	v_or3_b32 v4, v4, v6, v7
	v_bfe_i32 v13, v1, 0, 16
	v_mul_lo_u32 v4, v4, s0
	v_add_u32_e32 v1, v12, v13
	v_mul_lo_u32 v14, v5, s0
	v_add_lshl_u32 v38, v4, v1, 1
	v_add_lshl_u32 v42, v1, v14, 1
	v_bfe_i32 v1, v18, 27, 1
	v_lshrrev_b32_e32 v1, 22, v1
	v_add_u32_e32 v1, v0, v1
	v_and_b32_e32 v1, 0xfffffc00, v1
	v_sub_u32_e32 v0, v0, v1
	v_lshrrev_b32_e32 v1, 4, v0
	v_ashrrev_i32_e32 v3, 31, v18
	s_cselect_b32 s10, s11, s10
	v_bitop3_b32 v0, v1, v0, 32 bitop3:0x6c
	v_lshrrev_b32_e32 v3, 26, v3
	s_add_i32 s11, s10, 1
	v_ashrrev_i32_e32 v1, 31, v0
	v_add_u32_e32 v3, v18, v3
	s_cmp_ge_u32 s3, s51
	v_lshrrev_b32_e32 v1, 26, v1
	v_ashrrev_i32_e32 v3, 6, v3
	s_cselect_b32 s3, s11, s10
	v_add_u32_e32 v1, v0, v1
	v_lshlrev_b32_e32 v4, 3, v3
	s_abs_i32 s15, s27
	v_ashrrev_i32_e32 v2, 6, v1
	v_and_b32_e32 v4, -16, v4
	s_mul_hi_u32 s18, s15, s52
	v_add_u32_e32 v4, v2, v4
	v_and_b32_e32 v2, 3, v2
	s_mul_i32 s19, s18, s51
	s_xor_b32 s3, s3, s2
	s_ashr_i32 s16, s24, 6
	v_and_or_b32 v2, v4, s14, v2
	s_ashr_i32 s14, s27, 31
	s_sub_i32 s15, s15, s19
	s_sub_i32 s25, s3, s2
	s_ashr_i32 s17, s24, 8
	s_lshl_b64 s[2:3], s[0:1], 8
	s_lshl_b64 s[10:11], s[0:1], 9
	s_lshl_b32 s53, s16, 10
	s_xor_b32 s14, s14, s43
	s_add_i32 s19, s18, 1
	s_sub_i32 s28, s15, s51
	v_and_b32_e32 v1, 0xc0, v1
	s_cmp_ge_u32 s15, s51
	v_lshrrev_b32_e32 v5, 2, v4
	v_lshlrev_b32_e32 v6, 1, v4
	v_sub_u32_e32 v0, v0, v1
	s_cselect_b32 s18, s19, s18
	v_and_b32_e32 v5, 4, v5
	v_and_b32_e32 v6, 24, v6
	v_lshlrev_b32_e32 v3, 5, v3
	v_ashrrev_i16_sdwa v0, v217, sext(v0) dst_sel:DWORD dst_unused:UNUSED_PAD src0_sel:DWORD src1_sel:BYTE_0
	s_cselect_b32 s15, s28, s15
	s_add_i32 s19, s18, 1
	v_or3_b32 v2, v2, v5, v6
	v_and_b32_e32 v15, 32, v3
	v_bfe_i32 v16, v0, 0, 16
	s_cmp_ge_u32 s15, s51
	v_mul_lo_u32 v2, v2, s0
	v_add_u32_e32 v0, v15, v16
	v_mul_lo_u32 v17, v4, s0
	s_cselect_b32 s15, s19, s18
	s_abs_i32 s55, s36
	v_add_lshl_u32 v140, v2, v0, 1
	v_add_lshl_u32 v142, v0, v17, 1
	v_cvt_f32_u32_e32 v0, s55
	s_sub_i32 s28, 0, s55
	s_xor_b32 s15, s15, s14
	s_sub_i32 s14, s15, s14
	v_rcp_iflag_f32_e32 v0, v0
	s_abs_i32 s19, s14
	s_mul_i32 s15, s14, s13
	s_ashr_i32 s18, s14, 31
	v_mul_f32_e32 v0, 0x4f7ffffe, v0
	v_cvt_u32_f32_e32 v0, v0
	s_ashr_i32 s54, s36, 31
	s_sub_i32 s15, s27, s15
	s_xor_b32 s18, s18, s54
	v_readfirstlane_b32 s56, v0
	s_mul_i32 s28, s28, s56
	s_mul_hi_u32 s28, s56, s28
	s_add_i32 s56, s56, s28
	s_mul_hi_u32 s28, s19, s56
	s_mul_i32 s29, s28, s55
	s_sub_i32 s19, s19, s29
	s_add_i32 s29, s28, 1
	s_sub_i32 s30, s19, s55
	s_cmp_ge_u32 s19, s55
	s_cselect_b32 s28, s29, s28
	s_cselect_b32 s19, s30, s19
	s_add_i32 s29, s28, 1
	s_cmp_ge_u32 s19, s55
	s_cselect_b32 s19, s29, s28
	s_xor_b32 s19, s19, s18
	s_sub_i32 s18, s19, s18
	s_mul_i32 s19, s18, s36
	s_sub_i32 s74, s14, s19
	s_cmp_eq_u32 s18, 0
	s_cselect_b32 s73, 0, 33
	s_lshr_b64 s[0:1], s[0:1], 23
	s_mul_i32 s1, s0, s73
	s_mul_hi_u32 s14, s10, s73
	s_add_i32 s14, s14, s1
	s_ashr_i32 s1, s74, 31
	s_mul_i32 s15, s15, s25
	s_mul_i32 s1, s10, s1
	s_mul_hi_u32 s18, s10, s74
	s_lshl_b32 s72, s15, 1
	s_add_i32 s1, s18, s1
	s_mul_i32 s0, s0, s74
	s_ashr_i32 s19, s72, 31
	s_add_i32 s1, s1, s0
	s_mul_i32 s0, s10, s74
	s_add_u32 s0, s45, s0
	s_addc_u32 s1, s46, s1
	s_add_u32 s0, s0, s72
	s_addc_u32 s1, s1, s19
	s_add_i32 s57, s53, 0
	s_add_i32 m0, s57, 0x10000
	s_mul_i32 s15, s10, s73
	global_load_lds_dwordx4 v140, s[0:1]
	s_add_i32 m0, s57, 0x12000
	s_add_u32 s18, s37, s15
	s_addc_u32 s28, s44, s14
	s_add_u32 s14, s0, s2
	global_load_lds_dwordx4 v38, s[0:1]
	s_addc_u32 s15, s1, s3
	s_add_i32 m0, s57, 0x14000
	v_lshl_add_u64 v[4:5], s[14:15], 0, v[140:141]
	global_load_lds_dwordx4 v140, s[14:15]
	s_add_i32 m0, s57, 0x16000
	s_add_u32 s18, s18, s72
	s_addc_u32 s19, s28, s19
	s_add_i32 s58, s57, 0x2000
	v_lshl_add_u64 v[6:7], s[14:15], 0, v[38:39]
	global_load_lds_dwordx4 v38, s[14:15]
	s_mov_b32 m0, s57
	s_add_u32 s14, s18, s2
	global_load_lds_dwordx4 v142, s[18:19]
	s_mov_b32 m0, s58
	s_addc_u32 s15, s19, s3
	s_add_i32 s59, s57, 0x4000
	global_load_lds_dwordx4 v42, s[18:19]
	s_mov_b32 m0, s59
	s_add_i32 s60, s57, 0x6000
	global_load_lds_dwordx4 v142, s[14:15]
	s_mov_b32 m0, s60
	s_cmp_eq_u32 s17, 1
	global_load_lds_dwordx4 v42, s[14:15]
	v_lshl_add_u64 v[0:1], s[0:1], 0, v[140:141]
	v_lshl_add_u64 v[2:3], s[0:1], 0, v[38:39]
	v_lshl_add_u64 v[8:9], s[18:19], 0, v[142:143]
	v_lshl_add_u64 v[10:11], s[18:19], 0, v[42:43]
	s_cselect_b64 s[14:15], -1, 0
	s_cmp_lg_u32 s17, 1
	s_cbranch_scc1 .LBB0_347
	s_barrier

; #define PG8_LAS __attribute__((address_space(3)))
;     asm volatile("" : "+s"(K), "+s"(N), "+s"(nsplit));
;     int gd_ = (int)gridDim.x, bi_ = (int)blockIdx.x; asm volatile("" : "+s"(gd_), "+s"(bi_));
;     bi_ = (bi_ + gd_ - (rot % gd_)) % gd_;
;     const int kloop = K / nsplit;
;     pg8::Gemm g{A, Bt, MT, N, K, kloop}; CtxSplitOrder S{N / 256, nsplit, kloop, gd_, bi_};
;     pg8::gemm_phase<Epi, CtxSplitOrder, true, true>((PG8_LAS unsigned char*)lds, g, S, E);
; __global__ void __launch_bounds__(NTHR, 2) mk_fwd(Args args) {
;     ...
;                 { EpiMergePart<2> E{ws, 256 * 2}; run_gemm_ctx(lds, (const bf16_t*)(ws + O_CR), (const bf16_t*)(ws + O_WBR) + (size_t)2 * 1024 * 512, 1024, 512, 2, E, 128); }
.LBB0_366:
	v_readlane_b32 s10, v253, 0
	s_movk_i32 s1, 0x400
	s_movk_i32 s0, 0x200
	s_mov_b32 s13, 2
	s_mov_b32 s2, s81
	s_mov_b32 s26, s10
	s_abs_i32 s3, s26
	v_cvt_f32_u32_e32 v0, s3
	v_readlane_b32 s11, v253, 1
	s_sub_i32 s10, 0, s3
	s_add_i32 s2, s2, s26
	v_rcp_iflag_f32_e32 v0, v0
	v_mov_b32_e32 v18, v203
	v_mul_f32_e32 v0, 0x4f7ffffe, v0
	v_cvt_u32_f32_e32 v0, v0
	v_readfirstlane_b32 s24, v18
	v_readfirstlane_b32 s11, v0
	s_mul_i32 s10, s10, s11
	s_mul_hi_u32 s10, s11, s10
	s_add_i32 s11, s11, s10
	s_lshr_b32 s10, s11, 25
	s_mul_i32 s10, s10, s3
	s_sub_i32 s10, 0x80, s10
	s_sub_i32 s14, s10, s3
	s_cmp_ge_u32 s10, s3
	s_cselect_b32 s10, s14, s10
	s_sub_i32 s14, s10, s3
	s_cmp_ge_u32 s10, s3
	s_cselect_b32 s10, s14, s10
	s_sub_i32 s2, s2, s10
	s_ashr_i32 s10, s2, 31
	s_abs_i32 s2, s2
	s_mul_hi_u32 s11, s2, s11
	s_mul_i32 s11, s11, s3
	s_sub_i32 s2, s2, s11
	s_sub_i32 s11, s2, s3
	s_cmp_ge_u32 s2, s3
	s_cselect_b32 s2, s11, s2
	s_sub_i32 s11, s2, s3
	s_cmp_ge_u32 s2, s3
	s_cselect_b32 s2, s11, s2
	s_ashr_i32 s3, s1, 31
	s_xor_b32 s2, s2, s10
	s_sub_i32 s27, s2, s10
	s_lshr_b32 s2, s3, 24
	s_add_i32 s1, s1, s2
	s_ashr_i32 s36, s1, 8
	s_mul_i32 s1, s36, s13
	s_lshl_b32 s37, s1, 1
	v_readlane_b32 s1, v254, 27
	s_nop 3
	s_cmp_eq_u32 s1, 3
	s_cbranch_scc1 .LBB0_387
	s_cmp_ge_i32 s27, s37
	s_cbranch_scc1 .LBB0_387
; #define PG8_STAGE(bufoff, gbase, voff) do { _Pragma("unroll") for (int _i = 0; _i < 2; ++_i) \
;         __builtin_amdgcn_global_load_lds((const unsigned*)((const char*)(gbase) + (voff)[_i]), (PG8_LAS unsigned*)(lds + (bufoff) + ldsw + _i * 8192), 16, 0, 0); } while (0)
; #define PG8_WAIT_V(n) asm volatile("s_waitcnt vmcnt(" #n ")" ::: "memory")
; #define PG8_BAR __builtin_amdgcn_s_barrier()
; template <class Epi, class Sched, bool ALIGN_EPI = false, bool SP2 = false>
; __device__ __forceinline__ void gemm_phase(PG8_LAS unsigned char* lds, const Gemm g, const Sched& S, const Epi& E) {
;     ...
;     const int tid = tid_, wid = __builtin_amdgcn_readfirstlane(tid >> 6), lane = tid & 63, wr = wid >> 2, wc = wid & 3, fr = lane & 15, fq = lane >> 4;
;     const int K = g.K, nt = g.Kloop / BK;
;     unsigned voffA[2], voffB[2];
; #pragma unroll
;     for (int i = 0; i < 2; ++i) { int R, C; stage_rc(tid * 16 + i * 8192, R, C); const int Rb = Epi::PERM ? ((R & ~31) + perm32(R & 31)) : R;
;         voffA[i] = (unsigned)(R * K + C) * 2u; voffB[i] = (unsigned)(Rb * K + C) * 2u; }
;     const size_t kstep = (size_t)(BK * 2);
;     const size_t hstep = (size_t)HALF * K * 2;
;     const size_t tstep = 2 * hstep;
;     const unsigned ldsw = (unsigned)wid * 1024u;
;     const int aoff = lds_byte(wr * 64 + fr, fq * 8), boff = lds_byte(wc * 32 + fr, fq * 8);
;     ...
;     Unit cur, nxt; int ui = 0;
;     if (!S.next(0, cur)) return;
;     f32x4 acc[2][2][4][2];
; #pragma unroll
;     for (int a = 0; a < 2; ++a)
; #pragma unroll
;         for (int b = 0; b < 2; ++b)
; #pragma unroll
;             for (int m = 0; m < 4; ++m)
; #pragma unroll
;                 for (int n = 0; n < 2; ++n) acc[a][b][m][n] = (f32x4){0.f, 0.f, 0.f, 0.f};
;     bf16x8 At[4][2], B0[2][2], B1[2][2];
;     const char* cA = (const char*)g.A + (size_t)cur.pm * tstep + cur.kb; const char* cB = (const char*)g.Bt + (size_t)cur.pn * tstep + cur.kb;
;     S.a_ready(cur);
;     if constexpr (SP2) {
;         PG8_STAGE(PG8_SB(0, 0), cB, voffB); PG8_STAGE(PG8_SB(0, 1), cB + hstep, voffB); PG8_STAGE(PG8_SA(0, 0), cA, voffA); PG8_STAGE(PG8_SA(0, 1), cA + hstep, voffA);
;         if (wr == 1) PG8_BAR;
;         PG8_WAIT_V(2); PG8_BAR;
;         PG8_STAGE(PG8_SB(1, 0), cB + kstep, voffB); PG8_STAGE(PG8_SA(1, 0), cA + kstep, voffA); PG8_STAGE(PG8_SB(1, 1), cB + hstep + kstep, voffB);
;         PG8_WAIT_V(6); PG8_BAR;
	s_abs_i32 s43, s13
	v_cvt_f32_u32_e32 v0, s43
	s_sub_i32 s10, 0, s43
	s_abs_i32 s3, s0
	s_ashr_i32 s1, s0, 31
	v_rcp_iflag_f32_e32 v0, v0
	s_ashr_i32 s42, s13, 31
	s_xor_b32 s2, s1, s42
	s_waitcnt vmcnt(0)
	v_mov_b32_e32 v141, v36
	v_mul_f32_e32 v0, 0x4f7ffffe, v0
	v_cvt_u32_f32_e32 v0, v0
	v_mov_b32_e32 v39, v36
	v_mov_b32_e32 v143, v36
	v_mov_b32_e32 v43, v36
	v_readfirstlane_b32 s44, v0
	v_lshlrev_b32_e32 v0, 4, v18
	v_add_u32_e32 v1, 0x2000, v0
	v_ashrrev_i32_e32 v2, 31, v1
	v_lshrrev_b32_e32 v2, 22, v2
	v_add_u32_e32 v2, v1, v2
	v_ashrrev_i32_e32 v2, 10, v2
	v_mul_i32_i24_e32 v3, 0x400, v2
	s_mul_i32 s10, s10, s44
	v_sub_u32_e32 v1, v1, v3
	s_mul_hi_u32 s10, s44, s10
	v_lshrrev_b32_e32 v3, 4, v1
	s_add_i32 s44, s44, s10
	v_bitop3_b32 v1, v3, v1, 32 bitop3:0x6c
	s_mul_hi_u32 s10, s3, s44
	v_ashrrev_i32_e32 v3, 31, v1
	s_mul_i32 s11, s10, s43
	v_lshrrev_b32_e32 v3, 26, v3
	s_sub_i32 s3, s3, s11
	v_add_u32_e32 v3, v1, v3
	v_lshlrev_b32_e32 v5, 3, v2
	s_add_i32 s11, s10, 1
	s_sub_i32 s14, s3, s43
	v_ashrrev_i32_e32 v4, 6, v3
	v_and_b32_e32 v5, -16, v5
	v_lshlrev_b32_e32 v2, 5, v2
	s_cmp_ge_u32 s3, s43
	v_add_u32_e32 v5, v4, v5
	v_and_b32_e32 v12, 32, v2
	v_and_b32_e32 v2, 0xc0, v3
	s_cselect_b32 s3, s14, s3
	v_and_b32_e32 v4, 3, v4
	s_mov_b32 s14, 0x7fffffe0
	v_lshrrev_b32_e32 v6, 2, v5
	v_lshlrev_b32_e32 v7, 1, v5
	v_sub_u32_e32 v1, v1, v2
	v_and_or_b32 v4, v5, s14, v4
	v_and_b32_e32 v6, 4, v6
	v_and_b32_e32 v7, 24, v7
	v_ashrrev_i16_sdwa v1, v217, sext(v1) dst_sel:DWORD dst_unused:UNUSED_PAD src0_sel:DWORD src1_sel:BYTE_0
	v_or3_b32 v4, v4, v6, v7
	v_bfe_i32 v13, v1, 0, 16
	v_mul_lo_u32 v4, v4, s0
	v_add_u32_e32 v1, v12, v13
	v_mul_lo_u32 v14, v5, s0
	v_add_lshl_u32 v38, v4, v1, 1
	v_add_lshl_u32 v42, v1, v14, 1
	v_bfe_i32 v1, v18, 27, 1
	v_lshrrev_b32_e32 v1, 22, v1
	v_add_u32_e32 v1, v0, v1
	v_and_b32_e32 v1, 0xfffffc00, v1
	v_sub_u32_e32 v0, v0, v1
	v_lshrrev_b32_e32 v1, 4, v0
	v_ashrrev_i32_e32 v3, 31, v18
	s_cselect_b32 s10, s11, s10
	v_bitop3_b32 v0, v1, v0, 32 bitop3:0x6c
	v_lshrrev_b32_e32 v3, 26, v3
	s_add_i32 s11, s10, 1
	v_ashrrev_i32_e32 v1, 31, v0
	v_add_u32_e32 v3, v18, v3
	s_cmp_ge_u32 s3, s43
	v_lshrrev_b32_e32 v1, 26, v1
	v_ashrrev_i32_e32 v3, 6, v3
	s_cselect_b32 s3, s11, s10
	v_add_u32_e32 v1, v0, v1
	v_lshlrev_b32_e32 v4, 3, v3
	s_abs_i32 s15, s27
	v_ashrrev_i32_e32 v2, 6, v1
	v_and_b32_e32 v4, -16, v4
	s_mul_hi_u32 s18, s15, s44
	v_add_u32_e32 v4, v2, v4
	v_and_b32_e32 v2, 3, v2
	s_mul_i32 s19, s18, s43
	s_xor_b32 s3, s3, s2
	s_ashr_i32 s16, s24, 6
	v_and_or_b32 v2, v4, s14, v2
	s_ashr_i32 s14, s27, 31
	s_sub_i32 s15, s15, s19
	s_sub_i32 s25, s3, s2
	s_ashr_i32 s17, s24, 8
	s_lshl_b64 s[2:3], s[0:1], 8
	s_lshl_b64 s[10:11], s[0:1], 9
	s_lshl_b32 s45, s16, 10
	s_xor_b32 s14, s14, s42
	s_add_i32 s19, s18, 1
	s_sub_i32 s28, s15, s43
	v_and_b32_e32 v1, 0xc0, v1
	s_cmp_ge_u32 s15, s43
	v_lshrrev_b32_e32 v5, 2, v4
	v_lshlrev_b32_e32 v6, 1, v4
	v_sub_u32_e32 v0, v0, v1
	s_cselect_b32 s18, s19, s18
	v_and_b32_e32 v5, 4, v5
	v_and_b32_e32 v6, 24, v6
	v_lshlrev_b32_e32 v3, 5, v3
	v_ashrrev_i16_sdwa v0, v217, sext(v0) dst_sel:DWORD dst_unused:UNUSED_PAD src0_sel:DWORD src1_sel:BYTE_0
	s_cselect_b32 s15, s28, s15
	s_add_i32 s19, s18, 1
	v_or3_b32 v2, v2, v5, v6
	v_and_b32_e32 v15, 32, v3
	v_bfe_i32 v16, v0, 0, 16
	s_cmp_ge_u32 s15, s43
	v_mul_lo_u32 v2, v2, s0
	v_add_u32_e32 v0, v15, v16
	v_mul_lo_u32 v17, v4, s0
	s_cselect_b32 s15, s19, s18
	s_abs_i32 s51, s36
	v_add_lshl_u32 v140, v2, v0, 1
	v_add_lshl_u32 v142, v0, v17, 1
	v_cvt_f32_u32_e32 v0, s51
	s_sub_i32 s28, 0, s51
	s_xor_b32 s15, s15, s14
	s_sub_i32 s14, s15, s14
	v_rcp_iflag_f32_e32 v0, v0
	s_abs_i32 s19, s14
	s_mul_i32 s15, s14, s13
	s_ashr_i32 s18, s14, 31
	v_mul_f32_e32 v0, 0x4f7ffffe, v0
	v_cvt_u32_f32_e32 v0, v0
	s_ashr_i32 s46, s36, 31
	s_sub_i32 s15, s27, s15
	s_xor_b32 s18, s18, s46
	v_readfirstlane_b32 s52, v0
	s_mul_i32 s28, s28, s52
	s_mul_hi_u32 s28, s52, s28
	s_add_i32 s52, s52, s28
	s_mul_hi_u32 s28, s19, s52
	s_mul_i32 s29, s28, s51
	s_sub_i32 s19, s19, s29
	s_add_i32 s29, s28, 1
	s_sub_i32 s30, s19, s51
	s_cmp_ge_u32 s19, s51
	s_cselect_b32 s28, s29, s28
	s_cselect_b32 s19, s30, s19
	s_add_i32 s29, s28, 1
	s_cmp_ge_u32 s19, s51
	s_cselect_b32 s19, s29, s28
	s_xor_b32 s19, s19, s18
	s_sub_i32 s18, s19, s18
	s_mul_i32 s19, s18, s36
	s_sub_i32 s70, s14, s19
	s_cmp_eq_u32 s18, 0
	s_cselect_b32 s69, 0, 33
	s_lshr_b64 s[0:1], s[0:1], 23
	s_mul_i32 s1, s0, s69
	s_mul_hi_u32 s14, s10, s69
	s_add_i32 s14, s14, s1
	s_ashr_i32 s1, s70, 31
	s_mul_i32 s15, s15, s25
	s_mul_i32 s1, s10, s1
	s_mul_hi_u32 s18, s10, s70
	s_lshl_b32 s68, s15, 1
	s_add_i32 s1, s18, s1
	s_mul_i32 s0, s0, s70
	s_ashr_i32 s19, s68, 31
	s_add_i32 s1, s1, s0
	s_mul_i32 s0, s10, s70
	s_add_u32 s0, s49, s0
	s_addc_u32 s1, s50, s1
	s_add_u32 s0, s0, s68
	s_addc_u32 s1, s1, s19
	s_add_i32 s53, s45, 0
	s_add_i32 m0, s53, 0x10000
	s_mul_i32 s15, s10, s69
	global_load_lds_dwordx4 v140, s[0:1]
	s_add_i32 m0, s53, 0x12000
	s_add_u32 s18, s47, s15
	s_addc_u32 s28, s48, s14
	s_add_u32 s14, s0, s2
	global_load_lds_dwordx4 v38, s[0:1]
	s_addc_u32 s15, s1, s3
	s_add_i32 m0, s53, 0x14000
	v_lshl_add_u64 v[4:5], s[14:15], 0, v[140:141]
	global_load_lds_dwordx4 v140, s[14:15]
	s_add_i32 m0, s53, 0x16000
	s_add_u32 s18, s18, s68
	s_addc_u32 s19, s28, s19
	s_add_i32 s54, s53, 0x2000
	v_lshl_add_u64 v[6:7], s[14:15], 0, v[38:39]
	global_load_lds_dwordx4 v38, s[14:15]
	s_mov_b32 m0, s53
	s_add_u32 s14, s18, s2
	global_load_lds_dwordx4 v142, s[18:19]
	s_mov_b32 m0, s54
	s_addc_u32 s15, s19, s3
	s_add_i32 s55, s53, 0x4000
	global_load_lds_dwordx4 v42, s[18:19]
	s_mov_b32 m0, s55
	s_add_i32 s56, s53, 0x6000
	global_load_lds_dwordx4 v142, s[14:15]
	s_mov_b32 m0, s56
	s_cmp_eq_u32 s17, 1
	global_load_lds_dwordx4 v42, s[14:15]
	v_lshl_add_u64 v[0:1], s[0:1], 0, v[140:141]
	v_lshl_add_u64 v[2:3], s[0:1], 0, v[38:39]
	v_lshl_add_u64 v[8:9], s[18:19], 0, v[142:143]
	v_lshl_add_u64 v[10:11], s[18:19], 0, v[42:43]
	s_cselect_b64 s[14:15], -1, 0
	s_cmp_lg_u32 s17, 1
	s_cbranch_scc1 .LBB0_369
	s_barrier

; __device__ __forceinline__ void gla_decay(unsigned char* lds, const float* glow_t0, const float* Wg  , const float* bg  , int dir) {
;     float* Bs = (float*)(lds + GL_BS); float* Tot = (float*)(lds + GL_TOT); float* GLs = (float*)(lds + GL_O);
;     int tid_ = threadIdx.x; asm volatile("" : "+v"(tid_)); const int tid = tid_;
;     { const int s = tid >> 3, q = tid & 7;
;       const float* gp = glow_t0 + (size_t)s * 32 + dir * 16 + q * 2;
;       GLs[s * 16 + q * 2] = gp[0]; GLs[s * 16 + q * 2 + 1] = gp[1]; }
;     const int d = tid & 63, seg = tid >> 6;
;     float w[16];
; #pragma unroll
;     for (int r = 0; r < 16; ++r) w[r] = Wg[r * 256 + d];
; __device__ __forceinline__ void gla_out_item(unsigned char* lds, unsigned char* ws, const float* wgate, const float* bgate, const float* hnorm, int l, int item, bool dowrite = true) {
;     const int c = item % 132, h = (item / 132) & 3, b = item / 528;
;     const int t0 = b * TB + c * 64;
;     int tid_ = threadIdx.x; asm volatile("" : "+v"(tid_));
;     const int tid = tid_, lane = tid & 63, wid = tid >> 6, ql = lane & 15, g = lane >> 4;
;     const float* Bs = (const float*)(lds + GL_BS);
;     bf16_t* QE = (bf16_t*)(lds + GL_QE); bf16_t* KE = (bf16_t*)(lds + GL_KE); bf16_t* ATT = (bf16_t*)(lds + GL_ATT); const bf16_t* Vt = (const bf16_t*)(lds + GL_VT);
;     const u32x4 qraw = *(const u32x4*)((const bf16_t*)(ws + O_CQ) + (size_t)(t0 + (tid >> 3)) * 256 + h * 64 + (tid & 7) * 8);
;     const u32x4 kraw = *(const u32x4*)((const bf16_t*)(ws + O_CK) + (size_t)(t0 + (tid >> 3)) * 256 + h * 64 + (tid & 7) * 8);
;     bf16x8 sfr[2][2];
; #pragma unroll
;     for (int dd = 0; dd < 2; ++dd)
; #pragma unroll
;         for (int kk = 0; kk < 2; ++kk) sfr[dd][kk] = *(const bf16x8*)((const bf16_t*)(ws + O_ST) + (size_t)(((b * 4 + h) * 2 + dd) * 132 + c) * 8192 + (wid * 16 + ql) * 64 + kk * 32 + g * 8);
;     const u32x4 rraw0 = *(const u32x4*)((const bf16_t*)(ws + O_CR) + (size_t)(t0 + (tid >> 3)) * 512 + h * 128 + (tid & 7) * 16);
;     const u32x4 rraw1 = *(const u32x4*)((const bf16_t*)(ws + O_CR) + (size_t)(t0 + (tid >> 3)) * 512 + h * 128 + (tid & 7) * 16 + 8);
;     gla_load_vt(lds, (const bf16_t*)(ws + O_CV) + (size_t)t0 * 512 + h * 128);
.LBB0_389:
	v_readlane_b32 s0, v254, 33
	s_cmp_lt_i32 s0, 2
	s_mov_b64 s[0:1], -1
	v_writelane_b32 v254, s97, 41
	s_cbranch_scc1 .LBB0_727
	v_readlane_b32 s0, v254, 33
	s_cmp_lt_i32 s0, 3
	s_mov_b64 s[0:1], -1
	s_cbranch_scc1 .LBB0_507
	v_readlane_b32 s0, v254, 33
	s_cmp_gt_i32 s0, 3
	s_mov_b64 s[0:1], -1
	s_cbranch_scc0 .LBB0_396
	v_readlane_b32 s0, v254, 38
	s_cmpk_gt_i32 s0, 0x41f
	s_mov_b32 s55, 0xbfb8aa3b
	s_movk_i32 s56, 0x104
	s_mov_b32 s57, 0x3f317217
	s_mov_b32 s58, 0x7f800000
	s_movk_i32 s59, 0x820
	s_mov_b32 s61, s29
	s_cbranch_scc1 .LBB0_395
	s_add_u32 s2, s4, 0xf4e0000
	s_addc_u32 s3, s5, 0
	s_add_u32 s10, s4, 0xfd20000
	s_addc_u32 s11, s5, 0
	s_add_u32 s14, s4, 0x115e0000
	s_addc_u32 s15, s5, 0
	s_add_u32 s13, s4, 0x10560000
	s_addc_u32 s24, s5, 0
	s_add_u32 s25, s4, 0x12660000
	v_readlane_b32 s16, v254, 27
	s_load_dwordx4 s[44:47], s[6:7], 0x70
	s_load_dwordx2 s[0:1], s[6:7], 0x80
	s_addc_u32 s26, s5, 0
	s_lshl_b32 s27, s16, 1
	s_mov_b32 s18, s16
	s_or_b32 s27, s27, 1
	v_readlane_b32 s17, v254, 28
	s_lshl_b32 s16, s16, 5
	s_lshl_b32 s18, s18, 9
	s_lshl_b32 s28, s27, 4
	s_ashr_i32 s17, s16, 31
	s_ashr_i32 s19, s18, 31
	s_ashr_i32 s29, s28, 31
	s_lshl_b32 s34, s27, 8
	s_lshl_b64 s[16:17], s[16:17], 10
	s_lshl_b64 s[28:29], s[28:29], 10
	s_ashr_i32 s35, s34, 31
	s_lshl_b64 s[30:31], s[18:19], 2
	s_waitcnt lgkmcnt(0)
	s_add_u32 s27, s0, s30
	v_readlane_b32 s51, v254, 38
	s_addc_u32 s36, s1, s31
	s_lshl_b32 s37, s51, 6
	s_nop 0
	s_mov_b32 s98, s51
	v_readlane_b32 s99, v254, 27
	s_nop 3
	s_cmp_eq_u32 s99, 3
	s_movk_i32 s99, 0x41f
	s_cselect_b32 s99, 0x3ff, s99
	s_lshl_b32 s50, s97, 6
	s_lshl_b64 s[34:35], s[34:35], 2
.LBB0_394:
	s_cmpk_eq_i32 s99, 0x3ff
	s_cbranch_scc0 .Lgo_ident
	s_lshr_b32 s0, s98, 9
	s_mul_i32 s51, s0, 0x210
	s_bfe_u32 s0, s98, 0x20007
	s_mul_i32 s0, s0, 0x84
	s_add_i32 s51, s51, s0
	s_and_b32 s0, s98, 0x7f
	s_add_i32 s51, s51, s0
	s_add_i32 s51, s51, 4
	s_branch .Lgo_map
.Lgo_ident:
	s_mov_b32 s51, s98
.Lgo_map:
	s_lshl_b32 s37, s51, 6
	s_mul_hi_i32 s0, s51, 0x3e0f83e1
	s_ashr_i32 s1, s0, 5
	s_lshr_b32 s18, s0, 31
	s_ashr_i32 s0, s0, 7
	s_add_i32 s1, s1, s18
	s_add_i32 s18, s0, s18
	s_waitcnt vmcnt(0)
	v_mov_b32_e32 v68, v203
	s_mul_i32 s38, s18, 0x2100
	s_mul_i32 s19, s1, 0x84
	v_ashrrev_i32_e32 v37, 3, v68
	s_and_b32 s52, s1, 3
	s_mulk_i32 s1, 0x2100
	v_add_u32_e32 v0, s38, v37
	v_subrev_u32_e32 v0, s1, v0
	v_add_u32_e32 v0, s37, v0
	v_ashrrev_i32_e32 v1, 31, v0
	v_lshlrev_b64 v[2:3], 9, v[0:1]
	s_sub_i32 s0, s38, s1
	v_lshl_add_u64 v[4:5], s[2:3], 0, v[2:3]
	s_lshl_b32 s60, s52, 7
	v_and_b32_e32 v41, 7, v68
	v_lshl_add_u64 v[2:3], s[10:11], 0, v[2:3]
	s_mul_i32 s1, s18, 0x420
	s_mul_i32 s18, s52, 0x108
	v_lshl_add_u64 v[4:5], v[4:5], 0, s[60:61]
	v_lshlrev_b32_e32 v34, 4, v41
	v_mov_b32_e32 v35, v36
	v_lshl_add_u64 v[2:3], v[2:3], 0, s[60:61]
	s_add_i32 s1, s1, s18
	v_and_b32_e32 v69, 15, v68
	v_lshl_add_u64 v[4:5], v[4:5], 0, v[34:35]
	v_lshl_add_u64 v[2:3], v[2:3], 0, v[34:35]
	s_sub_i32 s1, s1, s19
	v_ashrrev_i32_e32 v55, 6, v68
	global_load_dwordx4 v[24:27], v[4:5], off
	global_load_dwordx4 v[20:23], v[2:3], off
	v_lshlrev_b32_e32 v2, 6, v69
	s_add_i32 s18, s51, s1
	v_lshl_or_b32 v2, v55, 10, v2
	s_ashr_i32 s19, s18, 31
	v_bfe_u32 v70, v68, 4, 2
	v_ashrrev_i32_e32 v3, 31, v2
	s_lshl_b64 s[38:39], s[18:19], 14
	s_addk_i32 s18, 0x84
	s_add_i32 s0, s37, s0
	v_lshl_add_u64 v[2:3], v[2:3], 1, s[20:21]
	v_lshlrev_b32_e32 v38, 4, v70
	v_mov_b32_e32 v39, v36
	s_ashr_i32 s19, s18, 31
	v_lshl_add_u64 v[2:3], v[2:3], 0, v[38:39]
	s_lshl_b64 s[18:19], s[18:19], 14
	v_lshlrev_b64 v[0:1], 10, v[0:1]
	s_ashr_i32 s1, s0, 31
	v_lshl_add_u64 v[4:5], v[2:3], 0, s[38:39]
	v_lshl_add_u64 v[2:3], v[2:3], 0, s[18:19]
	v_lshl_add_u64 v[0:1], s[14:15], 0, v[0:1]
	s_lshl_b32 s60, s52, 8
	s_lshl_b64 s[18:19], s[0:1], 10
	v_lshl_add_u64 v[0:1], v[0:1], 0, s[60:61]
	v_lshlrev_b32_e32 v42, 5, v41
	v_mov_b32_e32 v43, v36
	s_add_u32 s18, s13, s18
	v_lshl_add_u64 v[32:33], v[0:1], 0, v[42:43]
	s_addc_u32 s19, s24, s19
	v_mov_b32_e32 v35, v203
	global_load_dwordx4 v[16:19], v[4:5], off
	global_load_dwordx4 v[28:31], v[4:5], off offset:64
	global_load_dwordx4 v[12:15], v[2:3], off
	global_load_dwordx4 v[8:11], v[2:3], off offset:64
	s_nop 0
	global_load_dwordx4 v[0:3], v[32:33], off offset:16
	global_load_dwordx4 v[4:7], v[32:33], off
	s_add_u32 s18, s18, s60
	s_addc_u32 s19, s19, 0
	v_and_b32_e32 v39, 63, v35
	v_lshlrev_b32_e32 v48, 10, v39
	v_mov_b32_e32 v49, v36
	v_lshl_add_u32 v54, v39, 1, 0
	v_ashrrev_i32_e32 v39, 3, v35
	v_lshl_add_u64 v[52:53], s[18:19], 0, v[48:49]
	v_and_b32_e32 v48, -8, v39
	v_ashrrev_i32_e32 v49, 31, v48
	v_lshl_add_u64 v[50:51], v[48:49], 1, v[52:53]
	v_mad_u64_u32 v[56:57], s[18:19], v48, s76, v[54:55]
	global_load_dwordx4 v[48:51], v[50:51], off
	v_add_u32_e32 v35, 0x200, v35
	v_ashrrev_i32_e32 v35, 3, v35
	s_lshl_b64 s[0:1], s[0:1], 7
	s_add_u32 s42, s25, s0
	v_add_u32_e32 v42, 0, v42
	s_addc_u32 s43, s26, s1
	v_sub_u32_e32 v34, v42, v34
	v_add_u32_e32 v66, 0, v38
	s_add_u32 s48, s44, s60
	s_addc_u32 s49, s45, 0
	s_add_u32 s53, s46, s60
	s_addc_u32 s54, s47, 0
	s_waitcnt vmcnt(0)
	ds_write_b16 v56, v48 offset:46336
	ds_write_b16_d16_hi v56, v48 offset:46480
	ds_write_b16 v56, v49 offset:46624
	ds_write_b16_d16_hi v56, v49 offset:46768
	ds_write_b16 v56, v50 offset:46912
	ds_write_b16_d16_hi v56, v50 offset:47056
	ds_write_b16 v56, v51 offset:47200
	ds_write_b16_d16_hi v56, v51 offset:47344
	v_and_b32_e32 v48, -8, v35
	v_ashrrev_i32_e32 v49, 31, v48
	v_lshl_add_u64 v[50:51], v[48:49], 1, v[52:53]
	v_mad_u64_u32 v[52:53], s[18:19], v48, s76, v[54:55]
	global_load_dwordx4 v[48:51], v[50:51], off
	s_add_u32 s18, s48, s16
	s_addc_u32 s19, s49, s17
	s_waitcnt vmcnt(0)
; __device__ __forceinline__ void gla_decay(unsigned char* lds, const float* glow_t0, const float* Wg  , const float* bg  , int dir) {
;     float* Bs = (float*)(lds + GL_BS); float* Tot = (float*)(lds + GL_TOT); float* GLs = (float*)(lds + GL_O);
;     int tid_ = threadIdx.x; asm volatile("" : "+v"(tid_)); const int tid = tid_;
;     { const int s = tid >> 3, q = tid & 7;
;       const float* gp = glow_t0 + (size_t)s * 32 + dir * 16 + q * 2;
;       GLs[s * 16 + q * 2] = gp[0]; GLs[s * 16 + q * 2 + 1] = gp[1]; }
;     const int d = tid & 63, seg = tid >> 6;
;     float w[16];
; #pragma unroll
;     for (int r = 0; r < 16; ++r) w[r] = Wg[r * 256 + d];
;     const float bias = bg[d];
;     __syncthreads();
;     float loc[8];
; #pragma unroll
;     for (int k = 0; k < 8; ++k) { const float* gl = GLs + (seg * 8 + k) * 16; float a = bias;
; #pragma unroll
;         for (int r = 0; r < 16; ++r) a += gl[r] * w[r];
;         loc[k] = (fminf(a, 0.f) - __logf(1.f + __expf(-fabsf(a)))) * (1.f / 16.f); }
	ds_write_b16 v52, v48 offset:46336
	ds_write_b16_d16_hi v52, v48 offset:46480
	ds_write_b16 v52, v49 offset:46624
	ds_write_b16_d16_hi v52, v49 offset:46768
	ds_write_b16 v52, v50 offset:46912
	ds_write_b16_d16_hi v52, v50 offset:47056
	ds_write_b16 v52, v51 offset:47200
	ds_write_b16_d16_hi v52, v51 offset:47344
	v_mad_u64_u32 v[48:49], s[0:1], v37, s56, v[42:43]
	v_mov_b32_e32 v49, v203
	v_mad_u64_u32 v[42:43], s[0:1], v37, s76, v[34:35]
	v_ashrrev_i32_e32 v50, 3, v49
	v_bfi_b32 v35, -16, v37, v68
	v_ashrrev_i32_e32 v51, 31, v50
	v_and_b32_e32 v34, -16, v37
	v_mad_u64_u32 v[38:39], s[0:1], v35, s76, v[66:67]
	v_lshlrev_b64 v[52:53], 7, v[50:51]
	v_lshlrev_b32_e32 v51, 3, v49
	v_lshlrev_b32_e32 v43, 5, v55
	v_lshl_or_b32 v39, v70, 2, v34
	v_lshl_or_b32 v34, v55, 4, v69
	v_lshl_add_u64 v[52:53], s[42:43], 0, v[52:53]
	v_and_b32_e32 v54, 56, v51
	v_mov_b32_e32 v55, v36
	v_lshl_add_u64 v[52:53], v[52:53], 0, v[54:55]
	v_lshlrev_b32_e32 v50, 6, v50
	v_add3_u32 v54, 0, v50, v54
	global_load_dwordx2 v[50:51], v[52:53], off
	v_lshlrev_b32_e32 v64, 2, v49
	v_mad_u64_u32 v[34:35], s[0:1], v34, s76, v[66:67]
	s_add_u32 s0, s53, s30
	s_addc_u32 s1, s54, s31
	v_ashrrev_i32_e32 v49, 6, v49
	v_lshl_add_u32 v72, v49, 9, 0
	v_mul_u32_u24_e32 v35, 0x48, v69
	v_lshl_add_u32 v35, v35, 1, v66
	s_waitcnt vmcnt(0)
	ds_write_b64 v54, v[50:51] offset:64768
	v_and_b32_e32 v50, 0xfc, v64
	v_mov_b32_e32 v51, v36
	v_lshl_add_u64 v[52:53], s[18:19], 0, v[50:51]
	v_add_co_u32_e32 v54, vcc, s69, v52
	global_load_dword v51, v50, s[18:19]
	global_load_dword v65, v50, s[18:19] offset:1024
	global_load_dword v67, v50, s[18:19] offset:2048
	global_load_dword v71, v50, s[18:19] offset:3072
	v_addc_co_u32_e32 v55, vcc, 0, v53, vcc
	v_add_co_u32_e32 v56, vcc, s67, v52
	s_nop 1
	v_addc_co_u32_e32 v57, vcc, 0, v53, vcc
	v_add_co_u32_e32 v52, vcc, s66, v52
	global_load_dword v76, v[56:57], off offset:-4096
	global_load_dword v77, v[54:55], off offset:1024
	global_load_dword v78, v[54:55], off offset:2048
	global_load_dword v79, v[54:55], off offset:3072
	global_load_dword v80, v[56:57], off
	global_load_dword v81, v[56:57], off offset:1024
	global_load_dword v82, v[56:57], off offset:2048
	global_load_dword v83, v[56:57], off offset:3072
	v_addc_co_u32_e32 v53, vcc, 0, v53, vcc
	global_load_dword v84, v[52:53], off
	global_load_dword v85, v[52:53], off offset:1024
	global_load_dword v86, v[52:53], off offset:2048
	global_load_dword v87, v[52:53], off offset:3072
	global_load_dword v88, v50, s[0:1]
	s_waitcnt lgkmcnt(0)
	s_barrier
	ds_read_b128 v[52:55], v72 offset:65216
	v_add_u32_e32 v50, 0, v50
	s_waitcnt vmcnt(0) lgkmcnt(0)
	v_fma_f32 v56, v51, v52, v88
	v_fmac_f32_e32 v56, v65, v53
	v_fmac_f32_e32 v56, v67, v54
	v_fmac_f32_e32 v56, v71, v55
	ds_read_b128 v[52:55], v72 offset:65232
	s_waitcnt lgkmcnt(0)
	v_fmac_f32_e32 v56, v76, v52
	v_fmac_f32_e32 v56, v77, v53
	v_fmac_f32_e32 v56, v78, v54
	v_fmac_f32_e32 v56, v79, v55
	ds_read_b128 v[52:55], v72 offset:65248
	s_waitcnt lgkmcnt(0)
	v_fmac_f32_e32 v56, v80, v52
	v_fmac_f32_e32 v56, v81, v53
	v_fmac_f32_e32 v56, v82, v54
	v_fmac_f32_e32 v56, v83, v55
	ds_read_b128 v[52:55], v72 offset:65264
	s_waitcnt lgkmcnt(0)
	v_fmac_f32_e32 v56, v84, v52
	v_fmac_f32_e32 v56, v85, v53
	v_fmac_f32_e32 v56, v86, v54
	v_fmac_f32_e32 v56, v87, v55
	v_mul_f32_e64 v53, |v56|, s55
	v_exp_f32_e32 v53, v53
	v_min_f32_e32 v52, 0, v56
	v_add_f32_e32 v53, 1.0, v53
	v_cmp_gt_f32_e32 vcc, s33, v53
	s_nop 1
	v_cndmask_b32_e64 v54, 0, 32, vcc
	v_ldexp_f32 v53, v53, v54
	v_log_f32_e32 v53, v53
	s_nop 0
	v_mul_f32_e32 v54, 0x3f317217, v53
	v_fma_f32 v54, v53, s57, -v54
	v_fmac_f32_e32 v54, 0x3377d1cf, v53
	v_fmac_f32_e32 v54, 0x3f317217, v53
	v_cmp_lt_f32_e64 s[38:39], |v53|, s58
	s_nop 1
	v_cndmask_b32_e64 v53, v53, v54, s[38:39]
	v_cndmask_b32_e32 v54, 0, v229, vcc
	v_sub_f32_e32 v53, v53, v54
	v_sub_f32_e32 v89, v52, v53
	ds_read_b128 v[52:55], v72 offset:65152
	s_waitcnt lgkmcnt(0)
	v_fma_f32 v56, v51, v52, v88
	v_fmac_f32_e32 v56, v65, v53
	v_fmac_f32_e32 v56, v67, v54
	v_fmac_f32_e32 v56, v71, v55
	ds_read_b128 v[52:55], v72 offset:65168
	s_waitcnt lgkmcnt(0)
	v_fmac_f32_e32 v56, v76, v52
	v_fmac_f32_e32 v56, v77, v53
	v_fmac_f32_e32 v56, v78, v54
	v_fmac_f32_e32 v56, v79, v55
	ds_read_b128 v[52:55], v72 offset:65184
	s_waitcnt lgkmcnt(0)
	v_fmac_f32_e32 v56, v80, v52
	v_fmac_f32_e32 v56, v81, v53
	v_fmac_f32_e32 v56, v82, v54
	v_fmac_f32_e32 v56, v83, v55
	ds_read_b128 v[52:55], v72 offset:65200
	s_waitcnt lgkmcnt(0)
	v_fmac_f32_e32 v56, v84, v52
	v_fmac_f32_e32 v56, v85, v53
	v_fmac_f32_e32 v56, v86, v54
	v_fmac_f32_e32 v56, v87, v55
	v_mul_f32_e64 v53, |v56|, s55
	v_exp_f32_e32 v53, v53
	v_min_f32_e32 v52, 0, v56
	v_add_f32_e32 v53, 1.0, v53
	v_cmp_gt_f32_e32 vcc, s33, v53
	s_nop 1
	v_cndmask_b32_e64 v54, 0, 32, vcc
	v_ldexp_f32 v53, v53, v54
	v_log_f32_e32 v53, v53
	s_nop 0
	v_mul_f32_e32 v54, 0x3f317217, v53
	v_fma_f32 v54, v53, s57, -v54
	v_fmac_f32_e32 v54, 0x3377d1cf, v53
	v_fmac_f32_e32 v54, 0x3f317217, v53
	v_cmp_lt_f32_e64 s[38:39], |v53|, s58
	s_nop 1
	v_cndmask_b32_e64 v53, v53, v54, s[38:39]
	v_cndmask_b32_e32 v54, 0, v229, vcc
	v_sub_f32_e32 v53, v53, v54
	v_sub_f32_e32 v90, v52, v53
	ds_read_b128 v[52:55], v72 offset:65088
	s_waitcnt lgkmcnt(0)
	v_fma_f32 v56, v51, v52, v88
	v_fmac_f32_e32 v56, v65, v53
	v_fmac_f32_e32 v56, v67, v54
	v_fmac_f32_e32 v56, v71, v55
	ds_read_b128 v[52:55], v72 offset:65104
	s_waitcnt lgkmcnt(0)
	v_fmac_f32_e32 v56, v76, v52
	v_fmac_f32_e32 v56, v77, v53
	v_fmac_f32_e32 v56, v78, v54
	v_fmac_f32_e32 v56, v79, v55
	ds_read_b128 v[52:55], v72 offset:65120
	s_waitcnt lgkmcnt(0)
; __device__ __forceinline__ void gla_decay(unsigned char* lds, const float* glow_t0, const float* Wg  , const float* bg  , int dir) {
;     ...
;     for (int k = 0; k < 8; ++k) { const float* gl = GLs + (seg * 8 + k) * 16; float a = bias;
; #pragma unroll
;         for (int r = 0; r < 16; ++r) a += gl[r] * w[r];
;         loc[k] = (fminf(a, 0.f) - __logf(1.f + __expf(-fabsf(a)))) * (1.f / 16.f); }
	v_fmac_f32_e32 v56, v80, v52
	v_fmac_f32_e32 v56, v81, v53
	v_fmac_f32_e32 v56, v82, v54
	v_fmac_f32_e32 v56, v83, v55
	ds_read_b128 v[52:55], v72 offset:65136
	s_waitcnt lgkmcnt(0)
	v_fmac_f32_e32 v56, v84, v52
	v_fmac_f32_e32 v56, v85, v53
	v_fmac_f32_e32 v56, v86, v54
	v_fmac_f32_e32 v56, v87, v55
	v_mul_f32_e64 v53, |v56|, s55
	v_exp_f32_e32 v53, v53
	v_min_f32_e32 v52, 0, v56
	v_add_f32_e32 v53, 1.0, v53
	v_cmp_gt_f32_e32 vcc, s33, v53
	s_nop 1
	v_cndmask_b32_e64 v54, 0, 32, vcc
	v_ldexp_f32 v53, v53, v54
	v_log_f32_e32 v53, v53
	s_nop 0
	v_mul_f32_e32 v54, 0x3f317217, v53
	v_fma_f32 v54, v53, s57, -v54
	v_fmac_f32_e32 v54, 0x3377d1cf, v53
	v_fmac_f32_e32 v54, 0x3f317217, v53
	v_cmp_lt_f32_e64 s[38:39], |v53|, s58
	s_nop 1
	v_cndmask_b32_e64 v53, v53, v54, s[38:39]
	v_cndmask_b32_e32 v54, 0, v229, vcc
	v_sub_f32_e32 v53, v53, v54
	v_sub_f32_e32 v91, v52, v53
	ds_read_b128 v[52:55], v72 offset:65024
	s_waitcnt lgkmcnt(0)
	v_fma_f32 v56, v51, v52, v88
	v_fmac_f32_e32 v56, v65, v53
	v_fmac_f32_e32 v56, v67, v54
	v_fmac_f32_e32 v56, v71, v55
	ds_read_b128 v[52:55], v72 offset:65040
	s_waitcnt lgkmcnt(0)
	v_fmac_f32_e32 v56, v76, v52
	v_fmac_f32_e32 v56, v77, v53
	v_fmac_f32_e32 v56, v78, v54
	v_fmac_f32_e32 v56, v79, v55
	ds_read_b128 v[52:55], v72 offset:65056
	s_waitcnt lgkmcnt(0)
	v_fmac_f32_e32 v56, v80, v52
	v_fmac_f32_e32 v56, v81, v53
	v_fmac_f32_e32 v56, v82, v54
	v_fmac_f32_e32 v56, v83, v55
	ds_read_b128 v[52:55], v72 offset:65072
	s_waitcnt lgkmcnt(0)
	v_fmac_f32_e32 v56, v84, v52
	v_fmac_f32_e32 v56, v85, v53
	v_fmac_f32_e32 v56, v86, v54
	v_fmac_f32_e32 v56, v87, v55
	v_mul_f32_e64 v53, |v56|, s55
	v_exp_f32_e32 v53, v53
	v_min_f32_e32 v52, 0, v56
	v_add_f32_e32 v53, 1.0, v53
	v_cmp_gt_f32_e32 vcc, s33, v53
	s_nop 1
	v_cndmask_b32_e64 v54, 0, 32, vcc
	v_ldexp_f32 v53, v53, v54
	v_log_f32_e32 v53, v53
	s_nop 0
	v_mul_f32_e32 v54, 0x3f317217, v53
	v_fma_f32 v54, v53, s57, -v54
	v_fmac_f32_e32 v54, 0x3377d1cf, v53
	v_fmac_f32_e32 v54, 0x3f317217, v53
	v_cmp_lt_f32_e64 s[38:39], |v53|, s58
	s_nop 1
	v_cndmask_b32_e64 v53, v53, v54, s[38:39]
	v_cndmask_b32_e32 v54, 0, v229, vcc
	v_sub_f32_e32 v53, v53, v54
	v_sub_f32_e32 v92, v52, v53
	ds_read_b128 v[52:55], v72 offset:64960
	s_waitcnt lgkmcnt(0)
	v_fma_f32 v56, v51, v52, v88
	v_fmac_f32_e32 v56, v65, v53
	v_fmac_f32_e32 v56, v67, v54
	v_fmac_f32_e32 v56, v71, v55
	ds_read_b128 v[52:55], v72 offset:64976
	s_waitcnt lgkmcnt(0)
	v_fmac_f32_e32 v56, v76, v52
	v_fmac_f32_e32 v56, v77, v53
	v_fmac_f32_e32 v56, v78, v54
	v_fmac_f32_e32 v56, v79, v55
	ds_read_b128 v[52:55], v72 offset:64992
	s_waitcnt lgkmcnt(0)
	v_fmac_f32_e32 v56, v80, v52
	v_fmac_f32_e32 v56, v81, v53
	v_fmac_f32_e32 v56, v82, v54
	v_fmac_f32_e32 v56, v83, v55
	ds_read_b128 v[52:55], v72 offset:65008
	s_waitcnt lgkmcnt(0)
	v_fmac_f32_e32 v56, v84, v52
	v_fmac_f32_e32 v56, v85, v53
	v_fmac_f32_e32 v56, v86, v54
	v_fmac_f32_e32 v56, v87, v55
	v_mul_f32_e64 v53, |v56|, s55
	v_exp_f32_e32 v53, v53
	v_min_f32_e32 v52, 0, v56
	v_add_f32_e32 v53, 1.0, v53
	v_cmp_gt_f32_e32 vcc, s33, v53
	s_nop 1
	v_cndmask_b32_e64 v54, 0, 32, vcc
	v_ldexp_f32 v53, v53, v54
	v_log_f32_e32 v53, v53
	s_nop 0
	v_mul_f32_e32 v54, 0x3f317217, v53
	v_fma_f32 v54, v53, s57, -v54
	v_fmac_f32_e32 v54, 0x3377d1cf, v53
	v_fmac_f32_e32 v54, 0x3f317217, v53
	v_cmp_lt_f32_e64 s[38:39], |v53|, s58
	s_nop 1
	v_cndmask_b32_e64 v53, v53, v54, s[38:39]
	v_cndmask_b32_e32 v54, 0, v229, vcc
	v_sub_f32_e32 v53, v53, v54
	v_sub_f32_e32 v93, v52, v53
	ds_read_b128 v[52:55], v72 offset:64896
	s_waitcnt lgkmcnt(0)
	v_fma_f32 v56, v51, v52, v88
	v_fmac_f32_e32 v56, v65, v53
	v_fmac_f32_e32 v56, v67, v54
	v_fmac_f32_e32 v56, v71, v55
	ds_read_b128 v[52:55], v72 offset:64912
	s_waitcnt lgkmcnt(0)
	v_fmac_f32_e32 v56, v76, v52
	v_fmac_f32_e32 v56, v77, v53
	v_fmac_f32_e32 v56, v78, v54
	v_fmac_f32_e32 v56, v79, v55
	ds_read_b128 v[52:55], v72 offset:64928
	s_waitcnt lgkmcnt(0)
	v_fmac_f32_e32 v56, v80, v52
	v_fmac_f32_e32 v56, v81, v53
	v_fmac_f32_e32 v56, v82, v54
	v_fmac_f32_e32 v56, v83, v55
	ds_read_b128 v[52:55], v72 offset:64944
	s_waitcnt lgkmcnt(0)
	v_fmac_f32_e32 v56, v84, v52
	v_fmac_f32_e32 v56, v85, v53
	v_fmac_f32_e32 v56, v86, v54
	v_fmac_f32_e32 v56, v87, v55
	v_mul_f32_e64 v53, |v56|, s55
	v_exp_f32_e32 v53, v53
	v_min_f32_e32 v52, 0, v56
	v_add_f32_e32 v53, 1.0, v53
	v_cmp_gt_f32_e32 vcc, s33, v53
	s_nop 1
	v_cndmask_b32_e64 v54, 0, 32, vcc
	v_ldexp_f32 v53, v53, v54
	v_log_f32_e32 v53, v53
	s_nop 0
	v_mul_f32_e32 v54, 0x3f317217, v53
	v_fma_f32 v54, v53, s57, -v54
	v_fmac_f32_e32 v54, 0x3377d1cf, v53
	v_fmac_f32_e32 v54, 0x3f317217, v53
	v_cmp_lt_f32_e64 s[38:39], |v53|, s58
	s_nop 1
	v_cndmask_b32_e64 v53, v53, v54, s[38:39]
	v_cndmask_b32_e32 v54, 0, v229, vcc
	v_sub_f32_e32 v53, v53, v54
	v_sub_f32_e32 v94, v52, v53
	ds_read_b128 v[52:55], v72 offset:64832
	s_waitcnt lgkmcnt(0)
	v_fma_f32 v56, v51, v52, v88
	v_fmac_f32_e32 v56, v65, v53
	v_fmac_f32_e32 v56, v67, v54
	v_fmac_f32_e32 v56, v71, v55
	ds_read_b128 v[52:55], v72 offset:64848
	s_waitcnt lgkmcnt(0)
	v_fmac_f32_e32 v56, v76, v52
	v_fmac_f32_e32 v56, v77, v53
	v_fmac_f32_e32 v56, v78, v54
	v_fmac_f32_e32 v56, v79, v55
	ds_read_b128 v[52:55], v72 offset:64864
	s_waitcnt lgkmcnt(0)
	v_fmac_f32_e32 v56, v80, v52
	v_fmac_f32_e32 v56, v81, v53
	v_fmac_f32_e32 v56, v82, v54
	v_fmac_f32_e32 v56, v83, v55
	ds_read_b128 v[52:55], v72 offset:64880
	s_waitcnt lgkmcnt(0)
; __device__ __forceinline__ u32x4 pack8(const float* v) { u32x4 w; w.x = pk2(v[0], v[1]); w.y = pk2(v[2], v[3]); w.z = pk2(v[4], v[5]); w.w = pk2(v[6], v[7]); return w; }
; __device__ __forceinline__ void unpack8(u32x4 w, float* v) { v[0] = bflo(w.x); v[1] = bfhi(w.x); v[2] = bflo(w.y); v[3] = bfhi(w.y); v[4] = bflo(w.z); v[5] = bfhi(w.z); v[6] = bflo(w.w); v[7] = bfhi(w.w); }
; __device__ __forceinline__ void gla_decay(unsigned char* lds, const float* glow_t0, const float* Wg  , const float* bg  , int dir) {
;     ...
;     for (int k = 0; k < 8; ++k) { const float* gl = GLs + (seg * 8 + k) * 16; float a = bias;
; #pragma unroll
;         for (int r = 0; r < 16; ++r) a += gl[r] * w[r];
;         loc[k] = (fminf(a, 0.f) - __logf(1.f + __expf(-fabsf(a)))) * (1.f / 16.f); }
;     float run = 0.f;
;     if (dir == 0) {
; #pragma unroll
;         for (int k = 0; k < 8; ++k) { run += loc[k]; loc[k] = run; }
;     } else {
; #pragma unroll
;         for (int k = 7; k >= 0; --k) { run += loc[k]; loc[k] = run; }
;     }
;     Tot[seg * 64 + d] = run;
;     __syncthreads();
;     float off = 0.f;
; #pragma unroll
;     for (int sg = 0; sg < 8; ++sg) { const float tv = Tot[sg * 64 + d]; if (dir == 0 ? (sg < seg) : (sg > seg)) off += tv; }
; #pragma unroll
;     for (int k = 0; k < 8; ++k) Bs[(seg * 8 + k) * 65 + d] = loc[k] + off;
; __device__ __forceinline__ void gla_out_item(unsigned char* lds, unsigned char* ws, const float* wgate, const float* bgate, const float* hnorm, int l, int item, bool dowrite = true) {
;     ...
;         { const int s = tid >> 3, dg = tid & 7;
;           float qv[8], kv[8];
;           unpack8(qraw, qv);
;           unpack8(kraw, kv);
; #pragma unroll
;           for (int e = 0; e < 8; ++e) { const float bv = Bs[s * 65 + dg * 8 + e]; qv[e] *= __expf(bv); kv[e] *= __expf(-bv); }
;           *(u32x4*)(QE + s * 72 + dg * 8) = pack8(qv); *(u32x4*)(KE + s * 72 + dg * 8) = pack8(kv); }
	v_fmac_f32_e32 v56, v84, v52
	v_fmac_f32_e32 v56, v85, v53
	v_fmac_f32_e32 v56, v86, v54
	v_fmac_f32_e32 v56, v87, v55
	v_mul_f32_e64 v53, |v56|, s55
	v_exp_f32_e32 v53, v53
	v_min_f32_e32 v52, 0, v56
	v_add_f32_e32 v53, 1.0, v53
	v_cmp_gt_f32_e32 vcc, s33, v53
	s_nop 1
	v_cndmask_b32_e64 v54, 0, 32, vcc
	v_ldexp_f32 v53, v53, v54
	v_log_f32_e32 v53, v53
	s_nop 0
	v_mul_f32_e32 v54, 0x3f317217, v53
	v_fma_f32 v54, v53, s57, -v54
	v_fmac_f32_e32 v54, 0x3377d1cf, v53
	v_fmac_f32_e32 v54, 0x3f317217, v53
	v_cmp_lt_f32_e64 s[38:39], |v53|, s58
	s_nop 1
	v_cndmask_b32_e64 v53, v53, v54, s[38:39]
	v_cndmask_b32_e32 v54, 0, v229, vcc
	v_sub_f32_e32 v53, v53, v54
	v_sub_f32_e32 v95, v52, v53
	ds_read_b128 v[52:55], v72 offset:64768
	ds_read_b128 v[56:59], v72 offset:64784
	ds_read_b128 v[60:63], v72 offset:64800
	ds_read_b128 v[72:75], v72 offset:64816
	s_waitcnt lgkmcnt(3)
	v_fmac_f32_e32 v88, v51, v52
	v_fmac_f32_e32 v88, v65, v53
	v_fmac_f32_e32 v88, v67, v54
	v_fmac_f32_e32 v88, v71, v55
	s_waitcnt lgkmcnt(2)
	v_fmac_f32_e32 v88, v76, v56
	v_fmac_f32_e32 v88, v77, v57
	v_fmac_f32_e32 v88, v78, v58
	v_fmac_f32_e32 v88, v79, v59
	s_waitcnt lgkmcnt(1)
	v_fmac_f32_e32 v88, v80, v60
	v_fmac_f32_e32 v88, v81, v61
	v_fmac_f32_e32 v88, v82, v62
	v_fmac_f32_e32 v88, v83, v63
	s_waitcnt lgkmcnt(0)
	v_fmac_f32_e32 v88, v84, v72
	v_fmac_f32_e32 v88, v85, v73
	v_fmac_f32_e32 v88, v86, v74
	v_fmac_f32_e32 v88, v87, v75
	v_mul_f32_e64 v52, |v88|, s55
	v_exp_f32_e32 v52, v52
	v_min_f32_e32 v51, 0, v88
	v_lshlrev_b32_e32 v62, 16, v27
	v_and_b32_e32 v63, 0xffff0000, v27
	v_add_f32_e32 v52, 1.0, v52
	v_cmp_gt_f32_e32 vcc, s33, v52
	v_and_or_b32 v71, v43, 32, v69
	s_nop 0
	v_cndmask_b32_e64 v53, 0, 32, vcc
	v_ldexp_f32 v52, v52, v53
	v_log_f32_e32 v52, v52
	s_nop 0
	v_mul_f32_e32 v53, 0x3f317217, v52
	v_fma_f32 v53, v52, s57, -v53
	v_fmac_f32_e32 v53, 0x3377d1cf, v52
	v_fmac_f32_e32 v53, 0x3f317217, v52
	v_cmp_lt_f32_e64 s[38:39], |v52|, s58
	s_nop 1
	v_cndmask_b32_e64 v52, v52, v53, s[38:39]
	v_cndmask_b32_e32 v53, 0, v229, vcc
	v_sub_f32_e32 v52, v52, v53
	v_sub_f32_e32 v51, v51, v52
	v_fma_f32 v51, v51, s62, 0
	v_fmamk_f32 v54, v95, 0x3d800000, v51
	v_fmamk_f32 v55, v94, 0x3d800000, v54
	v_fmamk_f32 v56, v93, 0x3d800000, v55
	v_fmamk_f32 v57, v92, 0x3d800000, v56
	v_fmamk_f32 v58, v91, 0x3d800000, v57
	v_fmamk_f32 v59, v90, 0x3d800000, v58
	v_fmamk_f32 v60, v89, 0x3d800000, v59
	v_add_u32_e32 v52, 0, v64
	ds_write_b32 v52, v60 offset:16640
	s_waitcnt lgkmcnt(0)
	s_barrier
	ds_read2st64_b32 v[52:53], v50 offset0:65 offset1:66
	v_cmp_lt_i32_e32 vcc, 0, v49
	s_waitcnt lgkmcnt(0)
	v_add_f32_e32 v52, 0, v52
	v_cndmask_b32_e32 v52, 0, v52, vcc
	v_cmp_lt_i32_e32 vcc, 1, v49
	v_add_f32_e32 v53, v53, v52
	s_nop 0
	v_cndmask_b32_e32 v61, v52, v53, vcc
	ds_read2st64_b32 v[52:53], v50 offset0:67 offset1:68
	v_cmp_lt_i32_e32 vcc, 2, v49
	s_waitcnt lgkmcnt(0)
	v_add_f32_e32 v52, v52, v61
	v_cndmask_b32_e32 v52, v61, v52, vcc
	v_cmp_lt_i32_e32 vcc, 3, v49
	v_add_f32_e32 v53, v53, v52
	s_nop 0
	v_cndmask_b32_e32 v61, v52, v53, vcc
	ds_read2st64_b32 v[52:53], v50 offset0:69 offset1:70
	v_cmp_lt_i32_e32 vcc, 4, v49
	s_waitcnt lgkmcnt(0)
	v_add_f32_e32 v52, v52, v61
	v_cndmask_b32_e32 v52, v61, v52, vcc
	v_cmp_lt_i32_e32 vcc, 5, v49
	v_add_f32_e32 v53, v53, v52
	s_nop 0
	v_cndmask_b32_e32 v61, v52, v53, vcc
	ds_read2st64_b32 v[52:53], v50 offset0:71 offset1:72
	v_cmp_lt_i32_e32 vcc, 6, v49
	s_waitcnt lgkmcnt(0)
	v_add_f32_e32 v52, v52, v61
	v_cndmask_b32_e32 v52, v61, v52, vcc
	v_cmp_lt_i32_e32 vcc, 7, v49
	v_add_f32_e32 v53, v53, v52
	s_nop 0
	v_cndmask_b32_e32 v52, v52, v53, vcc
	v_add_f32_e32 v53, v51, v52
	v_mad_u64_u32 v[50:51], s[0:1], v49, s59, v[50:51]
	v_add_f32_e32 v49, v54, v52
	ds_write2_b32 v50, v53, v49 offset1:65
	v_add_f32_e32 v49, v55, v52
	v_add_f32_e32 v51, v56, v52
	ds_write2_b32 v50, v49, v51 offset0:130 offset1:195
	v_add_f32_e32 v49, v57, v52
	v_add_f32_e32 v51, v58, v52
	v_add_u32_e32 v50, 0x400, v50
	ds_write2_b32 v50, v49, v51 offset0:4 offset1:69
	v_add_f32_e32 v49, v59, v52
	v_add_f32_e32 v51, v60, v52
	ds_write2_b32 v50, v49, v51 offset0:134 offset1:199
	s_waitcnt lgkmcnt(0)
	s_barrier
	ds_read2_b32 v[52:53], v48 offset1:1
	v_lshlrev_b32_e32 v50, 16, v24
	v_and_b32_e32 v51, 0xffff0000, v24
	v_cmp_gt_i32_e32 vcc, v71, v39
	s_waitcnt lgkmcnt(0)
	v_mul_f32_e32 v49, 0x3fb8aa3b, v52
	v_exp_f32_e32 v54, v49
	v_mul_f32_e32 v49, 0xbfb8aa3b, v52
	v_mul_f32_e32 v24, 0xbfb8aa3b, v53
	v_exp_f32_e32 v56, v49
	v_exp_f32_e32 v57, v24
	v_mul_f32_e32 v49, 0x3fb8aa3b, v53
	v_lshlrev_b32_e32 v52, 16, v20
	v_and_b32_e32 v53, 0xffff0000, v20
	v_pk_mul_f32 v[74:75], v[56:57], v[52:53]
	ds_read2_b32 v[56:57], v48 offset0:2 offset1:3
	v_exp_f32_e32 v55, v49
	s_waitcnt lgkmcnt(0)
	v_mul_f32_e32 v20, 0x3fb8aa3b, v56
	v_exp_f32_e32 v58, v20
	v_mul_f32_e32 v20, 0xbfb8aa3b, v56
	v_exp_f32_e32 v24, v20
	v_mul_f32_e32 v20, 0x3fb8aa3b, v57
	v_exp_f32_e32 v59, v20
	v_mul_f32_e32 v20, 0xbfb8aa3b, v57
	v_pk_mul_f32 v[72:73], v[54:55], v[50:51]
	v_lshlrev_b32_e32 v54, 16, v25
	v_and_b32_e32 v55, 0xffff0000, v25
	v_exp_f32_e32 v25, v20
	v_lshlrev_b32_e32 v56, 16, v21
	v_and_b32_e32 v57, 0xffff0000, v21
	ds_read2_b32 v[20:21], v48 offset0:4 offset1:5
	v_pk_mul_f32 v[76:77], v[58:59], v[54:55]
	v_lshlrev_b32_e32 v58, 16, v26
	v_and_b32_e32 v59, 0xffff0000, v26
	v_pk_mul_f32 v[24:25], v[24:25], v[56:57]
	s_waitcnt lgkmcnt(0)
	v_mul_f32_e32 v49, 0x3fb8aa3b, v20
	v_exp_f32_e32 v60, v49
	v_mul_f32_e32 v49, 0x3fb8aa3b, v21
	v_mul_f32_e32 v20, 0xbfb8aa3b, v20
	v_exp_f32_e32 v61, v49
	v_mul_f32_e32 v21, 0xbfb8aa3b, v21
	v_exp_f32_e32 v20, v20
	v_exp_f32_e32 v21, v21
	v_pk_mul_f32 v[78:79], v[60:61], v[58:59]
	v_lshlrev_b32_e32 v60, 16, v22
	v_and_b32_e32 v61, 0xffff0000, v22
	v_pk_mul_f32 v[80:81], v[20:21], v[60:61]
	ds_read2_b32 v[20:21], v48 offset0:6 offset1:7
	v_mad_u32_u24 v49, v71, s76, v66
	v_or_b32_e32 v66, 1, v39
	v_cmp_le_i32_e64 s[38:39], v71, v66
	s_waitcnt lgkmcnt(0)
	v_mul_f32_e32 v22, 0x3fb8aa3b, v20
	v_exp_f32_e32 v64, v22
	v_mul_f32_e32 v22, 0x3fb8aa3b, v21
	v_mul_f32_e32 v20, 0xbfb8aa3b, v20
	v_exp_f32_e32 v65, v22
	v_mul_f32_e32 v21, 0xbfb8aa3b, v21
	v_exp_f32_e32 v20, v20
	v_exp_f32_e32 v21, v21
	v_pk_mul_f32 v[26:27], v[64:65], v[62:63]
	v_lshlrev_b32_e32 v64, 16, v23
	v_and_b32_e32 v65, 0xffff0000, v23
	v_pk_mul_f32 v[82:83], v[20:21], v[64:65]
	v_cvt_pk_bf16_f32 v20, v72, v73
	v_cvt_pk_bf16_f32 v21, v76, v77
	v_cvt_pk_bf16_f32 v22, v78, v79
	v_cvt_pk_bf16_f32 v23, v26, v27
	ds_write_b128 v42, v[20:23] offset:18688
	v_cvt_pk_bf16_f32 v20, v74, v75
	v_cvt_pk_bf16_f32 v21, v24, v25
	v_cvt_pk_bf16_f32 v22, v80, v81
	v_cvt_pk_bf16_f32 v23, v82, v83
	ds_write_b128 v42, v[20:23] offset:27904
	s_waitcnt lgkmcnt(0)
	s_barrier
; __device__ __forceinline__ void gla_decay(unsigned char* lds, const float* glow_t0, const float* Wg  , const float* bg  , int dir) {
;     float* Bs = (float*)(lds + GL_BS); float* Tot = (float*)(lds + GL_TOT); float* GLs = (float*)(lds + GL_O);
;     int tid_ = threadIdx.x; asm volatile("" : "+v"(tid_)); const int tid = tid_;
;     { const int s = tid >> 3, q = tid & 7;
;       const float* gp = glow_t0 + (size_t)s * 32 + dir * 16 + q * 2;
;       GLs[s * 16 + q * 2] = gp[0]; GLs[s * 16 + q * 2 + 1] = gp[1]; }
;     const int d = tid & 63, seg = tid >> 6;
;     float w[16];
; #pragma unroll
; __device__ __forceinline__ void gla_out_item(unsigned char* lds, unsigned char* ws, const float* wgate, const float* bgate, const float* hnorm, int l, int item, bool dowrite = true) {
;     ...
;         { const int rb = wid >> 1;
; #pragma unroll
;           for (int cc = 0; cc < 2; ++cc) { const int cb = (wid & 1) * 2 + cc; f32x4 a4 = (f32x4){0.f, 0.f, 0.f, 0.f};
; #pragma unroll
;               for (int kk = 0; kk < 2; ++kk) { const bf16x8 a = *(const bf16x8*)(QE + (rb * 16 + ql) * 72 + kk * 32 + g * 8); const bf16x8 bb = *(const bf16x8*)(KE + (cb * 16 + ql) * 72 + kk * 32 + g * 8);
;                   a4 = __builtin_amdgcn_mfma_f32_16x16x32_bf16(a, bb, a4, 0, 0, 0); }
; #pragma unroll
;               for (int j = 0; j < 4; ++j) { const int i = rb * 16 + g * 4 + j, ip = cb * 16 + ql; const bool keep = dir == 0 ? (ip <= i) : (ip >= i); ATT[i * 72 + ip] = (bf16_t)f2bf(keep ? a4[j] : 0.f); } } }
;         __syncthreads();
;         { const int sidx = ((b * 4 + h) * 2 + dir) * 132 + c;
;           const bf16_t* st = (const bf16_t*)(ws + O_ST) + (size_t)sidx * 8192;
; #pragma unroll
;           for (int kk = 0; kk < 2; ++kk) {
;               const bf16x8 bv = *(const bf16x8*)(Vt + (wid * 16 + ql) * 72 + kk * 32 + g * 8);
;               const bf16x8 bs = dir == 0 ? sfr[0][kk] : sfr[1][kk];
; #pragma unroll
;               for (int rb = 0; rb < 4; ++rb) {
;                   const bf16x8 a1 = *(const bf16x8*)(ATT + (rb * 16 + ql) * 72 + kk * 32 + g * 8);
;                   const bf16x8 a2 = *(const bf16x8*)(QE + (rb * 16 + ql) * 72 + kk * 32 + g * 8);
;                   oacc[rb] = __builtin_amdgcn_mfma_f32_16x16x32_bf16(a1, bv, oacc[rb], 0, 0, 0);
;                   oacc[rb] = __builtin_amdgcn_mfma_f32_16x16x32_bf16(a2, bs, oacc[rb], 0, 0, 0);
;               } } }
	ds_read_b128 v[20:23], v38 offset:18688
	ds_read_b128 v[24:27], v49 offset:27904
	s_waitcnt lgkmcnt(0)
	v_mfma_f32_16x16x32_bf16 v[20:23], v[20:23], v[24:27], 0
	ds_read_b128 v[24:27], v38 offset:18752
	ds_read_b128 v[72:75], v49 offset:27968
	s_waitcnt lgkmcnt(0)
	v_mfma_f32_16x16x32_bf16 v[20:23], v[24:27], v[72:75], v[20:23]
	v_lshlrev_b32_e32 v24, 1, v71
	v_or_b32_e32 v72, 2, v39
	v_or_b32_e32 v73, 3, v39
	s_nop 4
	v_cndmask_b32_e64 v20, v20, 0, vcc
	v_bfe_u32 v25, v20, 16, 1
	v_add3_u32 v20, v20, v25, s86
	v_mul_lo_u32 v25, v39, s76
	v_add3_u32 v43, 0, v24, v25
	ds_write_b16_d16_hi v43, v20 offset:37120
	v_cndmask_b32_e64 v20, 0, v21, s[38:39]
	v_bfe_u32 v21, v20, 16, 1
	v_add3_u32 v20, v20, v21, s86
	v_cmp_le_i32_e64 s[38:39], v71, v72
	ds_write_b16_d16_hi v43, v20 offset:37264
	v_or_b32_e32 v74, 16, v71
	v_cndmask_b32_e64 v20, 0, v22, s[38:39]
	v_bfe_u32 v21, v20, 16, 1
	v_add3_u32 v20, v20, v21, s86
	v_cmp_le_i32_e64 s[38:39], v71, v73
	ds_write_b16_d16_hi v43, v20 offset:37408
	v_cmp_le_i32_e64 s[40:41], v74, v66
	v_cndmask_b32_e64 v20, 0, v23, s[38:39]
	v_bfe_u32 v21, v20, 16, 1
	v_add3_u32 v20, v20, v21, s86
	ds_write_b16_d16_hi v43, v20 offset:37552
	ds_read_b128 v[20:23], v38 offset:18688
	ds_read_b128 v[24:27], v49 offset:30208
	s_waitcnt lgkmcnt(0)
	v_mfma_f32_16x16x32_bf16 v[20:23], v[20:23], v[24:27], 0
	ds_read_b128 v[24:27], v38 offset:18752
	ds_read_b128 v[76:79], v49 offset:30272
	v_cmp_gt_i32_e64 s[38:39], v74, v39
	v_mov_b32_e32 v75, v203
	s_waitcnt lgkmcnt(0)
	v_mfma_f32_16x16x32_bf16 v[20:23], v[24:27], v[76:79], v[20:23]
	s_nop 7
	v_cndmask_b32_e64 v20, v20, 0, s[38:39]
	v_bfe_u32 v24, v20, 16, 1
	v_add3_u32 v20, v20, v24, s86
	ds_write_b16_d16_hi v43, v20 offset:37152
	v_cndmask_b32_e64 v20, 0, v21, s[40:41]
	v_bfe_u32 v21, v20, 16, 1
	v_add3_u32 v20, v20, v21, s86
	v_cmp_le_i32_e64 s[40:41], v74, v72
	ds_write_b16_d16_hi v43, v20 offset:37296
	s_nop 0
	v_cndmask_b32_e64 v20, 0, v22, s[40:41]
	v_bfe_u32 v21, v20, 16, 1
	v_add3_u32 v20, v20, v21, s86
	v_cmp_le_i32_e64 s[40:41], v74, v73
	ds_write_b16_d16_hi v43, v20 offset:37440
	s_nop 0
	v_cndmask_b32_e64 v20, 0, v23, s[40:41]
	v_bfe_u32 v21, v20, 16, 1
	v_add3_u32 v20, v20, v21, s86
	ds_write_b16_d16_hi v43, v20 offset:37584
	s_waitcnt lgkmcnt(0)
	s_barrier
	ds_read_b128 v[20:23], v34 offset:46336
	ds_read_b128 v[24:27], v35 offset:37120
	ds_read_b128 v[76:79], v35 offset:18688
	s_waitcnt lgkmcnt(1)
	v_mfma_f32_16x16x32_bf16 v[24:27], v[24:27], v[20:23], 0
	s_add_u32 s40, s48, s28
	s_addc_u32 s41, s49, s29
	s_add_u32 s48, s53, s34
	s_waitcnt lgkmcnt(0)
	v_mfma_f32_16x16x32_bf16 v[24:27], v[76:79], v[16:19], v[24:27]
	ds_read_b128 v[76:79], v35 offset:39424
	ds_read_b128 v[80:83], v35 offset:20992
	s_addc_u32 s49, s54, s35
	s_waitcnt lgkmcnt(1)
	v_mfma_f32_16x16x32_bf16 v[76:79], v[76:79], v[20:23], 0
	s_waitcnt lgkmcnt(0)
	v_mfma_f32_16x16x32_bf16 v[76:79], v[80:83], v[16:19], v[76:79]
	ds_read_b128 v[80:83], v35 offset:41728
	ds_read_b128 v[84:87], v35 offset:23296
	s_waitcnt lgkmcnt(1)
	v_mfma_f32_16x16x32_bf16 v[80:83], v[80:83], v[20:23], 0
	s_waitcnt lgkmcnt(0)
	v_mfma_f32_16x16x32_bf16 v[80:83], v[84:87], v[16:19], v[80:83]
	ds_read_b128 v[84:87], v35 offset:44032
	ds_read_b128 v[88:91], v35 offset:25600
	s_waitcnt lgkmcnt(1)
	v_mfma_f32_16x16x32_bf16 v[20:23], v[84:87], v[20:23], 0
	s_waitcnt lgkmcnt(0)
	v_mfma_f32_16x16x32_bf16 v[84:87], v[88:91], v[16:19], v[20:23]
	ds_read_b128 v[88:91], v34 offset:46400
	ds_read_b128 v[16:19], v35 offset:37184
	s_nop 3
	ds_read_b128 v[20:23], v35 offset:18752
	s_waitcnt lgkmcnt(1)
	v_mfma_f32_16x16x32_bf16 v[16:19], v[16:19], v[88:91], v[24:27]
	s_waitcnt lgkmcnt(0)
	v_mfma_f32_16x16x32_bf16 v[16:19], v[20:23], v[28:31], v[16:19]
	ds_read_b128 v[20:23], v35 offset:39488
	ds_read_b128 v[24:27], v35 offset:21056
	s_waitcnt lgkmcnt(1)
	v_mfma_f32_16x16x32_bf16 v[20:23], v[20:23], v[88:91], v[76:79]
	s_waitcnt lgkmcnt(0)
	v_mfma_f32_16x16x32_bf16 v[20:23], v[24:27], v[28:31], v[20:23]
	ds_read_b128 v[24:27], v35 offset:41792
	ds_read_b128 v[76:79], v35 offset:23360
	s_waitcnt lgkmcnt(1)
	v_mfma_f32_16x16x32_bf16 v[24:27], v[24:27], v[88:91], v[80:83]
	s_waitcnt lgkmcnt(0)
	v_mfma_f32_16x16x32_bf16 v[24:27], v[76:79], v[28:31], v[24:27]
	ds_read_b128 v[76:79], v35 offset:44096
	ds_read_b128 v[80:83], v35 offset:25664
	s_waitcnt lgkmcnt(0)
	s_barrier
	v_mfma_f32_16x16x32_bf16 v[76:79], v[76:79], v[88:91], v[84:87]
	s_nop 0
	v_ashrrev_i32_e32 v66, 3, v75
	v_ashrrev_i32_e32 v67, 31, v66
	v_mfma_f32_16x16x32_bf16 v[28:31], v[80:83], v[28:31], v[76:79]
	v_lshlrev_b32_e32 v92, 2, v75
	s_nop 2
	v_lshlrev_b64 v[76:77], 7, v[66:67]
	v_lshlrev_b32_e32 v67, 3, v75
	v_lshl_add_u64 v[76:77], s[42:43], 0, v[76:77]
	v_and_b32_e32 v78, 56, v67
	v_mov_b32_e32 v79, v36
	v_lshl_add_u64 v[76:77], v[76:77], 0, v[78:79]
	v_lshlrev_b32_e32 v66, 6, v66
	v_add3_u32 v78, 0, v66, v78
	global_load_dwordx2 v[66:67], v[76:77], off offset:64
	v_ashrrev_i32_e32 v75, 6, v75
	v_lshl_add_u32 v88, v75, 9, 0
	s_waitcnt vmcnt(0)
	ds_write_b64 v78, v[66:67] offset:64768
	v_and_b32_e32 v66, 0xfc, v92
	v_mov_b32_e32 v67, v36
	v_lshl_add_u64 v[76:77], s[40:41], 0, v[66:67]
	global_load_dword v67, v66, s[40:41]
	global_load_dword v93, v66, s[40:41] offset:1024
	global_load_dword v94, v66, s[40:41] offset:2048
	global_load_dword v95, v66, s[40:41] offset:3072
	v_add_co_u32_e64 v78, s[40:41], s69, v76
	s_nop 1
	v_addc_co_u32_e64 v79, s[40:41], 0, v77, s[40:41]
	v_add_co_u32_e64 v80, s[40:41], s67, v76
	s_nop 1
	v_addc_co_u32_e64 v81, s[40:41], 0, v77, s[40:41]
	v_add_co_u32_e64 v76, s[40:41], s66, v76
	global_load_dword v96, v[80:81], off offset:-4096
	global_load_dword v97, v[78:79], off offset:1024
	global_load_dword v98, v[78:79], off offset:2048
	global_load_dword v99, v[78:79], off offset:3072
	global_load_dword v100, v[80:81], off
	global_load_dword v101, v[80:81], off offset:1024
	global_load_dword v102, v[80:81], off offset:2048
	global_load_dword v103, v[80:81], off offset:3072
	v_addc_co_u32_e64 v77, s[40:41], 0, v77, s[40:41]
	global_load_dword v104, v[76:77], off
	global_load_dword v105, v[76:77], off offset:1024
	global_load_dword v106, v[76:77], off offset:2048
	global_load_dword v107, v[76:77], off offset:3072
	global_load_dword v108, v66, s[48:49]
	s_waitcnt lgkmcnt(0)
	s_barrier
; __device__ __forceinline__ void gla_decay(unsigned char* lds, const float* glow_t0, const float* Wg  , const float* bg  , int dir) {
;     ...
;     float loc[8];
; #pragma unroll
;     for (int k = 0; k < 8; ++k) { const float* gl = GLs + (seg * 8 + k) * 16; float a = bias;
; #pragma unroll
;         for (int r = 0; r < 16; ++r) a += gl[r] * w[r];
;         loc[k] = (fminf(a, 0.f) - __logf(1.f + __expf(-fabsf(a)))) * (1.f / 16.f); }
	ds_read_b128 v[76:79], v88 offset:65216
	v_add_u32_e32 v66, 0, v66
	s_waitcnt vmcnt(0) lgkmcnt(0)
	v_fma_f32 v80, v67, v76, v108
	v_fmac_f32_e32 v80, v93, v77
	v_fmac_f32_e32 v80, v94, v78
	v_fmac_f32_e32 v80, v95, v79
	ds_read_b128 v[76:79], v88 offset:65232
	s_waitcnt lgkmcnt(0)
	v_fmac_f32_e32 v80, v96, v76
	v_fmac_f32_e32 v80, v97, v77
	v_fmac_f32_e32 v80, v98, v78
	v_fmac_f32_e32 v80, v99, v79
	ds_read_b128 v[76:79], v88 offset:65248
	s_waitcnt lgkmcnt(0)
	v_fmac_f32_e32 v80, v100, v76
	v_fmac_f32_e32 v80, v101, v77
	v_fmac_f32_e32 v80, v102, v78
	v_fmac_f32_e32 v80, v103, v79
	ds_read_b128 v[76:79], v88 offset:65264
	s_waitcnt lgkmcnt(0)
	v_fmac_f32_e32 v80, v104, v76
	v_fmac_f32_e32 v80, v105, v77
	v_fmac_f32_e32 v80, v106, v78
	v_fmac_f32_e32 v80, v107, v79
	v_mul_f32_e64 v77, |v80|, s55
	v_exp_f32_e32 v77, v77
	v_min_f32_e32 v76, 0, v80
	v_add_f32_e32 v77, 1.0, v77
	v_cmp_gt_f32_e64 s[40:41], s33, v77
	s_nop 1
	v_cndmask_b32_e64 v78, 0, 32, s[40:41]
	v_ldexp_f32 v77, v77, v78
	v_log_f32_e32 v77, v77
	s_nop 0
	v_mul_f32_e32 v78, 0x3f317217, v77
	v_fma_f32 v78, v77, s57, -v78
	v_fmac_f32_e32 v78, 0x3377d1cf, v77
	v_fmac_f32_e32 v78, 0x3f317217, v77
	v_cmp_lt_f32_e64 s[42:43], |v77|, s58
	s_nop 1
	v_cndmask_b32_e64 v77, v77, v78, s[42:43]
	v_cndmask_b32_e64 v78, 0, v229, s[40:41]
	v_sub_f32_e32 v77, v77, v78
	v_sub_f32_e32 v109, v76, v77
	ds_read_b128 v[76:79], v88 offset:65152
	s_waitcnt lgkmcnt(0)
	v_fma_f32 v80, v67, v76, v108
	v_fmac_f32_e32 v80, v93, v77
	v_fmac_f32_e32 v80, v94, v78
	v_fmac_f32_e32 v80, v95, v79
	ds_read_b128 v[76:79], v88 offset:65168
	s_waitcnt lgkmcnt(0)
	v_fmac_f32_e32 v80, v96, v76
	v_fmac_f32_e32 v80, v97, v77
	v_fmac_f32_e32 v80, v98, v78
	v_fmac_f32_e32 v80, v99, v79
	ds_read_b128 v[76:79], v88 offset:65184
	s_waitcnt lgkmcnt(0)
	v_fmac_f32_e32 v80, v100, v76
	v_fmac_f32_e32 v80, v101, v77
	v_fmac_f32_e32 v80, v102, v78
	v_fmac_f32_e32 v80, v103, v79
	ds_read_b128 v[76:79], v88 offset:65200
	s_waitcnt lgkmcnt(0)
	v_fmac_f32_e32 v80, v104, v76
	v_fmac_f32_e32 v80, v105, v77
	v_fmac_f32_e32 v80, v106, v78
	v_fmac_f32_e32 v80, v107, v79
	v_mul_f32_e64 v77, |v80|, s55
	v_exp_f32_e32 v77, v77
	v_min_f32_e32 v76, 0, v80
	v_add_f32_e32 v77, 1.0, v77
	v_cmp_gt_f32_e64 s[40:41], s33, v77
	s_nop 1
	v_cndmask_b32_e64 v78, 0, 32, s[40:41]
	v_ldexp_f32 v77, v77, v78
	v_log_f32_e32 v77, v77
	s_nop 0
	v_mul_f32_e32 v78, 0x3f317217, v77
	v_fma_f32 v78, v77, s57, -v78
	v_fmac_f32_e32 v78, 0x3377d1cf, v77
	v_fmac_f32_e32 v78, 0x3f317217, v77
	v_cmp_lt_f32_e64 s[42:43], |v77|, s58
	s_nop 1
	v_cndmask_b32_e64 v77, v77, v78, s[42:43]
	v_cndmask_b32_e64 v78, 0, v229, s[40:41]
	v_sub_f32_e32 v77, v77, v78
	v_sub_f32_e32 v110, v76, v77
	ds_read_b128 v[76:79], v88 offset:65088
	s_waitcnt lgkmcnt(0)
	v_fma_f32 v80, v67, v76, v108
	v_fmac_f32_e32 v80, v93, v77
	v_fmac_f32_e32 v80, v94, v78
	v_fmac_f32_e32 v80, v95, v79
	ds_read_b128 v[76:79], v88 offset:65104
	s_waitcnt lgkmcnt(0)
	v_fmac_f32_e32 v80, v96, v76
	v_fmac_f32_e32 v80, v97, v77
	v_fmac_f32_e32 v80, v98, v78
	v_fmac_f32_e32 v80, v99, v79
	ds_read_b128 v[76:79], v88 offset:65120
	s_waitcnt lgkmcnt(0)
	v_fmac_f32_e32 v80, v100, v76
	v_fmac_f32_e32 v80, v101, v77
	v_fmac_f32_e32 v80, v102, v78
	v_fmac_f32_e32 v80, v103, v79
	ds_read_b128 v[76:79], v88 offset:65136
	s_waitcnt lgkmcnt(0)
	v_fmac_f32_e32 v80, v104, v76
	v_fmac_f32_e32 v80, v105, v77
	v_fmac_f32_e32 v80, v106, v78
	v_fmac_f32_e32 v80, v107, v79
	v_mul_f32_e64 v77, |v80|, s55
	v_exp_f32_e32 v77, v77
	v_min_f32_e32 v76, 0, v80
	v_add_f32_e32 v77, 1.0, v77
	v_cmp_gt_f32_e64 s[40:41], s33, v77
	s_nop 1
	v_cndmask_b32_e64 v78, 0, 32, s[40:41]
	v_ldexp_f32 v77, v77, v78
	v_log_f32_e32 v77, v77
	s_nop 0
	v_mul_f32_e32 v78, 0x3f317217, v77
	v_fma_f32 v78, v77, s57, -v78
	v_fmac_f32_e32 v78, 0x3377d1cf, v77
	v_fmac_f32_e32 v78, 0x3f317217, v77
	v_cmp_lt_f32_e64 s[42:43], |v77|, s58
	s_nop 1
	v_cndmask_b32_e64 v77, v77, v78, s[42:43]
	v_cndmask_b32_e64 v78, 0, v229, s[40:41]
	v_sub_f32_e32 v77, v77, v78
	v_sub_f32_e32 v111, v76, v77
	ds_read_b128 v[76:79], v88 offset:65024
	s_waitcnt lgkmcnt(0)
	v_fma_f32 v80, v67, v76, v108
	v_fmac_f32_e32 v80, v93, v77
	v_fmac_f32_e32 v80, v94, v78
	v_fmac_f32_e32 v80, v95, v79
	ds_read_b128 v[76:79], v88 offset:65040
	s_waitcnt lgkmcnt(0)
	v_fmac_f32_e32 v80, v96, v76
	v_fmac_f32_e32 v80, v97, v77
	v_fmac_f32_e32 v80, v98, v78
	v_fmac_f32_e32 v80, v99, v79
	ds_read_b128 v[76:79], v88 offset:65056
	s_waitcnt lgkmcnt(0)
	v_fmac_f32_e32 v80, v100, v76
	v_fmac_f32_e32 v80, v101, v77
	v_fmac_f32_e32 v80, v102, v78
	v_fmac_f32_e32 v80, v103, v79
	ds_read_b128 v[76:79], v88 offset:65072
	s_waitcnt lgkmcnt(0)
	v_fmac_f32_e32 v80, v104, v76
	v_fmac_f32_e32 v80, v105, v77
	v_fmac_f32_e32 v80, v106, v78
	v_fmac_f32_e32 v80, v107, v79
	v_mul_f32_e64 v77, |v80|, s55
	v_exp_f32_e32 v77, v77
	v_min_f32_e32 v76, 0, v80
	v_add_f32_e32 v77, 1.0, v77
	v_cmp_gt_f32_e64 s[40:41], s33, v77
	s_nop 1
	v_cndmask_b32_e64 v78, 0, 32, s[40:41]
	v_ldexp_f32 v77, v77, v78
	v_log_f32_e32 v77, v77
	s_nop 0
	v_mul_f32_e32 v78, 0x3f317217, v77
	v_fma_f32 v78, v77, s57, -v78
	v_fmac_f32_e32 v78, 0x3377d1cf, v77
	v_fmac_f32_e32 v78, 0x3f317217, v77
	v_cmp_lt_f32_e64 s[42:43], |v77|, s58
	s_nop 1
	v_cndmask_b32_e64 v77, v77, v78, s[42:43]
	v_cndmask_b32_e64 v78, 0, v229, s[40:41]
	v_sub_f32_e32 v77, v77, v78
	v_sub_f32_e32 v112, v76, v77
	ds_read_b128 v[76:79], v88 offset:64960
	s_waitcnt lgkmcnt(0)
	v_fma_f32 v80, v67, v76, v108
	v_fmac_f32_e32 v80, v93, v77
	v_fmac_f32_e32 v80, v94, v78
	v_fmac_f32_e32 v80, v95, v79
	ds_read_b128 v[76:79], v88 offset:64976
	s_waitcnt lgkmcnt(0)
; __device__ __forceinline__ void gla_decay(unsigned char* lds, const float* glow_t0, const float* Wg  , const float* bg  , int dir) {
;     ...
;     float loc[8];
; #pragma unroll
;     for (int k = 0; k < 8; ++k) { const float* gl = GLs + (seg * 8 + k) * 16; float a = bias;
; #pragma unroll
;         for (int r = 0; r < 16; ++r) a += gl[r] * w[r];
;         loc[k] = (fminf(a, 0.f) - __logf(1.f + __expf(-fabsf(a)))) * (1.f / 16.f); }
	v_fmac_f32_e32 v80, v96, v76
	v_fmac_f32_e32 v80, v97, v77
	v_fmac_f32_e32 v80, v98, v78
	v_fmac_f32_e32 v80, v99, v79
	ds_read_b128 v[76:79], v88 offset:64992
	s_waitcnt lgkmcnt(0)
	v_fmac_f32_e32 v80, v100, v76
	v_fmac_f32_e32 v80, v101, v77
	v_fmac_f32_e32 v80, v102, v78
	v_fmac_f32_e32 v80, v103, v79
	ds_read_b128 v[76:79], v88 offset:65008
	s_waitcnt lgkmcnt(0)
	v_fmac_f32_e32 v80, v104, v76
	v_fmac_f32_e32 v80, v105, v77
	v_fmac_f32_e32 v80, v106, v78
	v_fmac_f32_e32 v80, v107, v79
	v_mul_f32_e64 v77, |v80|, s55
	v_exp_f32_e32 v77, v77
	v_min_f32_e32 v76, 0, v80
	v_add_f32_e32 v77, 1.0, v77
	v_cmp_gt_f32_e64 s[40:41], s33, v77
	s_nop 1
	v_cndmask_b32_e64 v78, 0, 32, s[40:41]
	v_ldexp_f32 v77, v77, v78
	v_log_f32_e32 v77, v77
	s_nop 0
	v_mul_f32_e32 v78, 0x3f317217, v77
	v_fma_f32 v78, v77, s57, -v78
	v_fmac_f32_e32 v78, 0x3377d1cf, v77
	v_fmac_f32_e32 v78, 0x3f317217, v77
	v_cmp_lt_f32_e64 s[42:43], |v77|, s58
	s_nop 1
	v_cndmask_b32_e64 v77, v77, v78, s[42:43]
	v_cndmask_b32_e64 v78, 0, v229, s[40:41]
	v_sub_f32_e32 v77, v77, v78
	v_sub_f32_e32 v113, v76, v77
	ds_read_b128 v[76:79], v88 offset:64896
	s_waitcnt lgkmcnt(0)
	v_fma_f32 v80, v67, v76, v108
	v_fmac_f32_e32 v80, v93, v77
	v_fmac_f32_e32 v80, v94, v78
	v_fmac_f32_e32 v80, v95, v79
	ds_read_b128 v[76:79], v88 offset:64912
	s_waitcnt lgkmcnt(0)
	v_fmac_f32_e32 v80, v96, v76
	v_fmac_f32_e32 v80, v97, v77
	v_fmac_f32_e32 v80, v98, v78
	v_fmac_f32_e32 v80, v99, v79
	ds_read_b128 v[76:79], v88 offset:64928
	s_waitcnt lgkmcnt(0)
	v_fmac_f32_e32 v80, v100, v76
	v_fmac_f32_e32 v80, v101, v77
	v_fmac_f32_e32 v80, v102, v78
	v_fmac_f32_e32 v80, v103, v79
	ds_read_b128 v[76:79], v88 offset:64944
	s_waitcnt lgkmcnt(0)
	v_fmac_f32_e32 v80, v104, v76
	v_fmac_f32_e32 v80, v105, v77
	v_fmac_f32_e32 v80, v106, v78
	v_fmac_f32_e32 v80, v107, v79
	v_mul_f32_e64 v77, |v80|, s55
	v_exp_f32_e32 v77, v77
	v_min_f32_e32 v76, 0, v80
	v_add_f32_e32 v77, 1.0, v77
	v_cmp_gt_f32_e64 s[40:41], s33, v77
	s_nop 1
	v_cndmask_b32_e64 v78, 0, 32, s[40:41]
	v_ldexp_f32 v77, v77, v78
	v_log_f32_e32 v77, v77
	s_nop 0
	v_mul_f32_e32 v78, 0x3f317217, v77
	v_fma_f32 v78, v77, s57, -v78
	v_fmac_f32_e32 v78, 0x3377d1cf, v77
	v_fmac_f32_e32 v78, 0x3f317217, v77
	v_cmp_lt_f32_e64 s[42:43], |v77|, s58
	s_nop 1
	v_cndmask_b32_e64 v77, v77, v78, s[42:43]
	v_cndmask_b32_e64 v78, 0, v229, s[40:41]
	v_sub_f32_e32 v77, v77, v78
	v_sub_f32_e32 v114, v76, v77
	ds_read_b128 v[76:79], v88 offset:64832
	s_waitcnt lgkmcnt(0)
	v_fma_f32 v80, v67, v76, v108
	v_fmac_f32_e32 v80, v93, v77
	v_fmac_f32_e32 v80, v94, v78
	v_fmac_f32_e32 v80, v95, v79
	ds_read_b128 v[76:79], v88 offset:64848
	s_waitcnt lgkmcnt(0)
	v_fmac_f32_e32 v80, v96, v76
	v_fmac_f32_e32 v80, v97, v77
	v_fmac_f32_e32 v80, v98, v78
	v_fmac_f32_e32 v80, v99, v79
	ds_read_b128 v[76:79], v88 offset:64864
	s_waitcnt lgkmcnt(0)
	v_fmac_f32_e32 v80, v100, v76
	v_fmac_f32_e32 v80, v101, v77
	v_fmac_f32_e32 v80, v102, v78
	v_fmac_f32_e32 v80, v103, v79
	ds_read_b128 v[76:79], v88 offset:64880
	s_waitcnt lgkmcnt(0)
	v_fmac_f32_e32 v80, v104, v76
	v_fmac_f32_e32 v80, v105, v77
	v_fmac_f32_e32 v80, v106, v78
	v_fmac_f32_e32 v80, v107, v79
	v_mul_f32_e64 v77, |v80|, s55
	v_exp_f32_e32 v77, v77
	v_min_f32_e32 v76, 0, v80
	v_add_f32_e32 v77, 1.0, v77
	v_cmp_gt_f32_e64 s[40:41], s33, v77
	s_nop 1
	v_cndmask_b32_e64 v78, 0, 32, s[40:41]
	v_ldexp_f32 v77, v77, v78
	v_log_f32_e32 v77, v77
	s_nop 0
	v_mul_f32_e32 v78, 0x3f317217, v77
	v_fma_f32 v78, v77, s57, -v78
	v_fmac_f32_e32 v78, 0x3377d1cf, v77
	v_fmac_f32_e32 v78, 0x3f317217, v77
	v_cmp_lt_f32_e64 s[42:43], |v77|, s58
	s_nop 1
	v_cndmask_b32_e64 v77, v77, v78, s[42:43]
	v_cndmask_b32_e64 v78, 0, v229, s[40:41]
	v_sub_f32_e32 v77, v77, v78
	v_sub_f32_e32 v115, v76, v77
	ds_read_b128 v[76:79], v88 offset:64768
	ds_read_b128 v[80:83], v88 offset:64784
	ds_read_b128 v[84:87], v88 offset:64800
	ds_read_b128 v[88:91], v88 offset:64816
	s_waitcnt lgkmcnt(3)
	v_fmac_f32_e32 v108, v67, v76
	v_fmac_f32_e32 v108, v93, v77
	v_fmac_f32_e32 v108, v94, v78
	v_fmac_f32_e32 v108, v95, v79
	s_waitcnt lgkmcnt(2)
	v_fmac_f32_e32 v108, v96, v80
	v_fmac_f32_e32 v108, v97, v81
	v_fmac_f32_e32 v108, v98, v82
	v_fmac_f32_e32 v108, v99, v83
	s_waitcnt lgkmcnt(1)
	v_fmac_f32_e32 v108, v100, v84
	v_fmac_f32_e32 v108, v101, v85
	v_fmac_f32_e32 v108, v102, v86
	v_fmac_f32_e32 v108, v103, v87
	s_waitcnt lgkmcnt(0)
	v_fmac_f32_e32 v108, v104, v88
	v_fmac_f32_e32 v108, v105, v89
	v_fmac_f32_e32 v108, v106, v90
	v_fmac_f32_e32 v108, v107, v91
	v_mul_f32_e64 v76, |v108|, s55
	v_exp_f32_e32 v76, v76
	v_fma_f32 v78, v109, s62, 0
	v_fmamk_f32 v79, v110, 0x3d800000, v78
	v_fmamk_f32 v80, v111, 0x3d800000, v79
	v_add_f32_e32 v76, 1.0, v76
	v_cmp_gt_f32_e64 s[40:41], s33, v76
	v_fmamk_f32 v81, v112, 0x3d800000, v80
	v_fmamk_f32 v82, v113, 0x3d800000, v81
	v_cndmask_b32_e64 v77, 0, 32, s[40:41]
	v_ldexp_f32 v76, v76, v77
	v_log_f32_e32 v76, v76
	v_min_f32_e32 v67, 0, v108
	v_fmamk_f32 v83, v114, 0x3d800000, v82
	v_fmamk_f32 v84, v115, 0x3d800000, v83
	v_mul_f32_e32 v77, 0x3f317217, v76
	v_fma_f32 v77, v76, s57, -v77
	v_fmac_f32_e32 v77, 0x3377d1cf, v76
	v_fmac_f32_e32 v77, 0x3f317217, v76
	v_cmp_lt_f32_e64 s[42:43], |v76|, s58
	s_nop 1
	v_cndmask_b32_e64 v76, v76, v77, s[42:43]
	v_cndmask_b32_e64 v77, 0, v229, s[40:41]
	v_sub_f32_e32 v76, v76, v77
	v_sub_f32_e32 v67, v67, v76
	v_fmamk_f32 v67, v67, 0x3d800000, v84
	v_add_u32_e32 v76, 0, v92
	ds_write_b32 v76, v67 offset:16640
	s_waitcnt lgkmcnt(0)
	s_barrier
; __device__ __forceinline__ unsigned f2bf(float f) { unsigned u = __float_as_uint(f); return (u + 0x7fffu + ((u >> 16) & 1u)) >> 16; }
; __device__ __forceinline__ u32x4 pack8(const float* v) { u32x4 w; w.x = pk2(v[0], v[1]); w.y = pk2(v[2], v[3]); w.z = pk2(v[4], v[5]); w.w = pk2(v[6], v[7]); return w; }
; __device__ __forceinline__ void gla_decay(unsigned char* lds, const float* glow_t0, const float* Wg  , const float* bg  , int dir) {
;     ...
;     float run = 0.f;
;     if (dir == 0) {
; #pragma unroll
;         for (int k = 0; k < 8; ++k) { run += loc[k]; loc[k] = run; }
;     } else {
; #pragma unroll
;         for (int k = 7; k >= 0; --k) { run += loc[k]; loc[k] = run; }
;     }
;     Tot[seg * 64 + d] = run;
;     __syncthreads();
;     float off = 0.f;
; #pragma unroll
;     for (int sg = 0; sg < 8; ++sg) { const float tv = Tot[sg * 64 + d]; if (dir == 0 ? (sg < seg) : (sg > seg)) off += tv; }
; #pragma unroll
;     for (int k = 0; k < 8; ++k) Bs[(seg * 8 + k) * 65 + d] = loc[k] + off;
;     __syncthreads();
; __device__ __forceinline__ void gla_out_item(unsigned char* lds, unsigned char* ws, const float* wgate, const float* bgate, const float* hnorm, int l, int item, bool dowrite = true) {
;     ...
;         { const int s = tid >> 3, dg = tid & 7;
;           float qv[8], kv[8];
;           unpack8(qraw, qv);
;           unpack8(kraw, kv);
; #pragma unroll
;           for (int e = 0; e < 8; ++e) { const float bv = Bs[s * 65 + dg * 8 + e]; qv[e] *= __expf(bv); kv[e] *= __expf(-bv); }
;           *(u32x4*)(QE + s * 72 + dg * 8) = pack8(qv); *(u32x4*)(KE + s * 72 + dg * 8) = pack8(kv); }
;         __syncthreads();
;         { const int rb = wid >> 1;
; #pragma unroll
;           for (int cc = 0; cc < 2; ++cc) { const int cb = (wid & 1) * 2 + cc; f32x4 a4 = (f32x4){0.f, 0.f, 0.f, 0.f};
; #pragma unroll
;               for (int kk = 0; kk < 2; ++kk) { const bf16x8 a = *(const bf16x8*)(QE + (rb * 16 + ql) * 72 + kk * 32 + g * 8); const bf16x8 bb = *(const bf16x8*)(KE + (cb * 16 + ql) * 72 + kk * 32 + g * 8);
;                   a4 = __builtin_amdgcn_mfma_f32_16x16x32_bf16(a, bb, a4, 0, 0, 0); }
; #pragma unroll
;               for (int j = 0; j < 4; ++j) { const int i = rb * 16 + g * 4 + j, ip = cb * 16 + ql; const bool keep = dir == 0 ? (ip <= i) : (ip >= i); ATT[i * 72 + ip] = (bf16_t)f2bf(keep ? a4[j] : 0.f); } } }
	ds_read2st64_b32 v[76:77], v66 offset0:65 offset1:66
	v_cmp_gt_i32_e64 s[40:41], 0, v75
	s_waitcnt lgkmcnt(0)
	v_add_f32_e32 v76, 0, v76
	v_cndmask_b32_e64 v76, 0, v76, s[40:41]
	v_cmp_gt_i32_e64 s[40:41], 1, v75
	v_add_f32_e32 v76, v77, v76
	s_nop 0
	v_cndmask_b32_e64 v85, 0, v76, s[40:41]
	ds_read2st64_b32 v[76:77], v66 offset0:67 offset1:68
	v_cmp_gt_i32_e64 s[40:41], 2, v75
	s_waitcnt lgkmcnt(0)
	v_add_f32_e32 v76, v76, v85
	v_cndmask_b32_e64 v76, 0, v76, s[40:41]
	v_cmp_gt_i32_e64 s[40:41], 3, v75
	v_add_f32_e32 v76, v77, v76
	s_nop 0
	v_cndmask_b32_e64 v85, 0, v76, s[40:41]
	ds_read2st64_b32 v[76:77], v66 offset0:69 offset1:70
	v_cmp_gt_i32_e64 s[40:41], 4, v75
	s_waitcnt lgkmcnt(0)
	v_add_f32_e32 v76, v76, v85
	v_cndmask_b32_e64 v76, 0, v76, s[40:41]
	v_cmp_gt_i32_e64 s[40:41], 5, v75
	v_add_f32_e32 v76, v77, v76
	s_nop 0
	v_cndmask_b32_e64 v85, 0, v76, s[40:41]
	ds_read2st64_b32 v[76:77], v66 offset0:71 offset1:72
	v_cmp_gt_i32_e64 s[40:41], 6, v75
	s_waitcnt lgkmcnt(0)
	v_add_f32_e32 v76, v76, v85
	v_cndmask_b32_e64 v76, 0, v76, s[40:41]
	v_cmp_gt_i32_e64 s[40:41], 7, v75
	v_add_f32_e32 v76, v77, v76
	s_nop 0
	v_cndmask_b32_e64 v76, 0, v76, s[40:41]
	v_add_f32_e32 v77, v67, v76
	v_mad_u64_u32 v[66:67], s[0:1], v75, s59, v[66:67]
	v_add_f32_e32 v67, v84, v76
	ds_write2_b32 v66, v77, v67 offset1:65
	v_add_f32_e32 v67, v83, v76
	v_add_f32_e32 v75, v82, v76
	ds_write2_b32 v66, v67, v75 offset0:130 offset1:195
	v_add_f32_e32 v67, v81, v76
	v_add_f32_e32 v75, v80, v76
	v_add_u32_e32 v66, 0x400, v66
	ds_write2_b32 v66, v67, v75 offset0:4 offset1:69
	v_add_f32_e32 v67, v79, v76
	v_add_f32_e32 v75, v78, v76
	ds_write2_b32 v66, v67, v75 offset0:134 offset1:199
	s_waitcnt lgkmcnt(0)
	s_barrier
	ds_read2_b32 v[66:67], v48 offset1:1
	v_cmp_ge_i32_e64 s[40:41], v71, v39
	s_movk_i32 s0, 0x210
	s_waitcnt lgkmcnt(0)
	v_mul_f32_e32 v75, 0x3fb8aa3b, v66
	v_exp_f32_e32 v76, v75
	v_mul_f32_e32 v66, 0xbfb8aa3b, v66
	v_mul_f32_e32 v75, 0x3fb8aa3b, v67
	v_mul_f32_e32 v67, 0xbfb8aa3b, v67
	v_exp_f32_e32 v66, v66
	v_exp_f32_e32 v67, v67
	v_exp_f32_e32 v77, v75
	v_pk_mul_f32 v[66:67], v[66:67], v[52:53]
	ds_read2_b32 v[52:53], v48 offset0:2 offset1:3
	v_pk_mul_f32 v[50:51], v[76:77], v[50:51]
	s_waitcnt lgkmcnt(0)
	v_mul_f32_e32 v75, 0x3fb8aa3b, v52
	v_exp_f32_e32 v76, v75
	v_mul_f32_e32 v52, 0xbfb8aa3b, v52
	v_mul_f32_e32 v75, 0x3fb8aa3b, v53
	v_mul_f32_e32 v53, 0xbfb8aa3b, v53
	v_exp_f32_e32 v52, v52
	v_exp_f32_e32 v53, v53
	v_exp_f32_e32 v77, v75
	v_cvt_pk_bf16_f32 v50, v50, v51
	v_pk_mul_f32 v[56:57], v[52:53], v[56:57]
	ds_read2_b32 v[52:53], v48 offset0:4 offset1:5
	v_pk_mul_f32 v[54:55], v[76:77], v[54:55]
	s_waitcnt lgkmcnt(0)
	v_mul_f32_e32 v75, 0x3fb8aa3b, v52
	v_exp_f32_e32 v76, v75
	v_mul_f32_e32 v52, 0xbfb8aa3b, v52
	v_mul_f32_e32 v75, 0x3fb8aa3b, v53
	v_mul_f32_e32 v53, 0xbfb8aa3b, v53
	v_exp_f32_e32 v52, v52
	v_exp_f32_e32 v53, v53
	v_exp_f32_e32 v77, v75
	v_cvt_pk_bf16_f32 v51, v54, v55
	v_pk_mul_f32 v[60:61], v[52:53], v[60:61]
	ds_read2_b32 v[52:53], v48 offset0:6 offset1:7
	v_pk_mul_f32 v[58:59], v[76:77], v[58:59]
	s_waitcnt lgkmcnt(0)
	v_mul_f32_e32 v48, 0x3fb8aa3b, v52
	v_exp_f32_e32 v76, v48
	v_mul_f32_e32 v48, 0xbfb8aa3b, v52
	v_exp_f32_e32 v52, v48
	v_mul_f32_e32 v48, 0x3fb8aa3b, v53
	v_exp_f32_e32 v77, v48
	v_mul_f32_e32 v48, 0xbfb8aa3b, v53
	v_exp_f32_e32 v53, v48
	v_pk_mul_f32 v[62:63], v[76:77], v[62:63]
	v_pk_mul_f32 v[64:65], v[52:53], v[64:65]
	v_cvt_pk_bf16_f32 v52, v58, v59
	v_cvt_pk_bf16_f32 v53, v62, v63
	ds_write_b128 v42, v[50:53] offset:18688
	v_cvt_pk_bf16_f32 v50, v66, v67
	v_cvt_pk_bf16_f32 v51, v56, v57
	v_cvt_pk_bf16_f32 v52, v60, v61
	v_cvt_pk_bf16_f32 v53, v64, v65
	ds_write_b128 v42, v[50:53] offset:27904
	s_waitcnt lgkmcnt(0)
	s_barrier
	ds_read_b128 v[50:53], v38 offset:18688
	ds_read_b128 v[54:57], v49 offset:27904
	s_waitcnt lgkmcnt(0)
	v_mfma_f32_16x16x32_bf16 v[50:53], v[50:53], v[54:57], 0
	ds_read_b128 v[54:57], v38 offset:18752
	ds_read_b128 v[58:61], v49 offset:27968
	v_and_b32_e32 v67, 0xffff0000, v0
	s_waitcnt lgkmcnt(0)
	v_mfma_f32_16x16x32_bf16 v[50:53], v[54:57], v[58:61], v[50:53]
	s_nop 7
	v_cndmask_b32_e64 v42, 0, v50, s[40:41]
	v_bfe_u32 v48, v42, 16, 1
	v_add3_u32 v42, v42, v48, s86
	ds_write_b16_d16_hi v43, v42 offset:37120
	v_cndmask_b32_e32 v42, 0, v51, vcc
	v_bfe_u32 v48, v42, 16, 1
	v_add3_u32 v42, v42, v48, s86
	v_cmp_ge_i32_e32 vcc, v71, v72
	ds_write_b16_d16_hi v43, v42 offset:37264
	s_nop 0
	v_cndmask_b32_e32 v42, 0, v52, vcc
	v_bfe_u32 v48, v42, 16, 1
	v_add3_u32 v42, v42, v48, s86
	v_cmp_ge_i32_e32 vcc, v71, v73
	ds_write_b16_d16_hi v43, v42 offset:37408
	s_nop 0
	v_cndmask_b32_e32 v42, 0, v53, vcc
	v_bfe_u32 v48, v42, 16, 1
	v_add3_u32 v42, v42, v48, s86
	ds_write_b16_d16_hi v43, v42 offset:37552
	ds_read_b128 v[50:53], v38 offset:18688
	ds_read_b128 v[54:57], v49 offset:30208
	s_waitcnt lgkmcnt(0)
	v_mfma_f32_16x16x32_bf16 v[50:53], v[50:53], v[54:57], 0
	ds_read_b128 v[54:57], v38 offset:18752
	ds_read_b128 v[58:61], v49 offset:30272
	v_cmp_ge_i32_e32 vcc, v74, v39
	v_lshlrev_b32_e32 v42, 16, v6
	s_waitcnt lgkmcnt(0)
	v_mfma_f32_16x16x32_bf16 v[48:51], v[54:57], v[58:61], v[50:53]
	s_nop 7
	v_cndmask_b32_e32 v38, 0, v48, vcc
	v_bfe_u32 v39, v38, 16, 1
	v_add3_u32 v38, v38, v39, s86
	ds_write_b16_d16_hi v43, v38 offset:37152
	v_cndmask_b32_e64 v38, 0, v49, s[38:39]
	v_bfe_u32 v39, v38, 16, 1
	v_add3_u32 v38, v38, v39, s86
	v_cmp_ge_i32_e32 vcc, v74, v72
	ds_write_b16_d16_hi v43, v38 offset:37296
	s_nop 0
	v_cndmask_b32_e32 v38, 0, v50, vcc
	v_bfe_u32 v39, v38, 16, 1
	v_add3_u32 v38, v38, v39, s86
	v_cmp_ge_i32_e32 vcc, v74, v73
	ds_write_b16_d16_hi v43, v38 offset:37440
	s_nop 0
	v_cndmask_b32_e32 v38, 0, v51, vcc
	v_bfe_u32 v39, v38, 16, 1
	v_add3_u32 v38, v38, v39, s86
	ds_write_b16_d16_hi v43, v38 offset:37584
	s_waitcnt lgkmcnt(0)
	s_barrier
; __device__ __forceinline__ void gla_out_item(unsigned char* lds, unsigned char* ws, const float* wgate, const float* bgate, const float* hnorm, int l, int item, bool dowrite = true) {
;     ...
;         { const int sidx = ((b * 4 + h) * 2 + dir) * 132 + c;
;           const bf16_t* st = (const bf16_t*)(ws + O_ST) + (size_t)sidx * 8192;
; #pragma unroll
;           for (int kk = 0; kk < 2; ++kk) {
;               const bf16x8 bv = *(const bf16x8*)(Vt + (wid * 16 + ql) * 72 + kk * 32 + g * 8);
;               const bf16x8 bs = dir == 0 ? sfr[0][kk] : sfr[1][kk];
; #pragma unroll
;               for (int rb = 0; rb < 4; ++rb) {
;                   const bf16x8 a1 = *(const bf16x8*)(ATT + (rb * 16 + ql) * 72 + kk * 32 + g * 8);
;                   const bf16x8 a2 = *(const bf16x8*)(QE + (rb * 16 + ql) * 72 + kk * 32 + g * 8);
;                   oacc[rb] = __builtin_amdgcn_mfma_f32_16x16x32_bf16(a1, bv, oacc[rb], 0, 0, 0);
;                   oacc[rb] = __builtin_amdgcn_mfma_f32_16x16x32_bf16(a2, bs, oacc[rb], 0, 0, 0);
;               } } }
;         __syncthreads();
;     }
;     float* Os = (float*)(lds + GL_O);
; #pragma unroll
;     for (int rb = 0; rb < 4; ++rb)
; #pragma unroll
;         for (int j = 0; j < 4; ++j) Os[(rb * 16 + g * 4 + j) * 132 + wid * 16 + ql] = oacc[rb][j];
;     __syncthreads();
	ds_read_b128 v[48:51], v34 offset:46336
	ds_read_b128 v[52:55], v35 offset:37120
	ds_read_b128 v[56:59], v35 offset:18688
	s_waitcnt lgkmcnt(1)
	v_mfma_f32_16x16x32_bf16 v[16:19], v[52:55], v[48:51], v[16:19]
	v_and_b32_e32 v43, 0xffff0000, v6
	v_mul_f32_e32 v6, 0xbfb8aa3b, v42
	v_exp_f32_e32 v6, v6
	s_waitcnt lgkmcnt(0)
	v_mfma_f32_16x16x32_bf16 v[16:19], v[56:59], v[12:15], v[16:19]
	ds_read_b128 v[52:55], v35 offset:39424
	ds_read_b128 v[56:59], v35 offset:20992
	v_cmp_lt_i32_e32 vcc, v220, v219
	s_waitcnt lgkmcnt(1)
	v_mfma_f32_16x16x32_bf16 v[20:23], v[52:55], v[48:51], v[20:23]
	s_waitcnt lgkmcnt(0)
	v_mfma_f32_16x16x32_bf16 v[20:23], v[56:59], v[12:15], v[20:23]
	ds_read_b128 v[52:55], v35 offset:41728
	ds_read_b128 v[56:59], v35 offset:23296
	s_waitcnt lgkmcnt(1)
	v_mfma_f32_16x16x32_bf16 v[24:27], v[52:55], v[48:51], v[24:27]
	s_waitcnt lgkmcnt(0)
	v_mfma_f32_16x16x32_bf16 v[24:27], v[56:59], v[12:15], v[24:27]
	ds_read_b128 v[52:55], v35 offset:44032
	ds_read_b128 v[56:59], v35 offset:25600
	s_waitcnt lgkmcnt(1)
	v_mfma_f32_16x16x32_bf16 v[28:31], v[52:55], v[48:51], v[28:31]
	s_waitcnt lgkmcnt(0)
	v_mfma_f32_16x16x32_bf16 v[12:15], v[56:59], v[12:15], v[28:31]
	s_nop 5
	ds_read_b128 v[28:31], v34 offset:46400
	ds_read_b128 v[48:51], v35 offset:37184
	ds_read_b128 v[52:55], v35 offset:18752
	s_waitcnt lgkmcnt(1)
	v_mfma_f32_16x16x32_bf16 v[16:19], v[48:51], v[28:31], v[16:19]
	s_waitcnt lgkmcnt(0)
	v_mfma_f32_16x16x32_bf16 v[16:19], v[52:55], v[8:11], v[16:19]
	ds_read_b128 v[48:51], v35 offset:39488
	ds_read_b128 v[52:55], v35 offset:21056
	s_waitcnt lgkmcnt(1)
	v_mfma_f32_16x16x32_bf16 v[20:23], v[48:51], v[28:31], v[20:23]
	s_waitcnt lgkmcnt(0)
	v_mfma_f32_16x16x32_bf16 v[20:23], v[52:55], v[8:11], v[20:23]
	ds_read_b128 v[48:51], v35 offset:41792
	ds_read_b128 v[52:55], v35 offset:23360
	s_waitcnt lgkmcnt(1)
	v_mfma_f32_16x16x32_bf16 v[24:27], v[48:51], v[28:31], v[24:27]
	s_waitcnt lgkmcnt(0)
	v_mfma_f32_16x16x32_bf16 v[24:27], v[52:55], v[8:11], v[24:27]
	ds_read_b128 v[48:51], v35 offset:44096
	ds_read_b128 v[52:55], v35 offset:25664
	s_waitcnt lgkmcnt(0)
	s_barrier
	v_mfma_f32_16x16x32_bf16 v[12:15], v[48:51], v[28:31], v[12:15]
	v_lshlrev_b32_e32 v28, 6, v41
	v_and_b32_e32 v41, 0xffff0000, v7
	v_mfma_f32_16x16x32_bf16 v[8:11], v[52:55], v[8:11], v[12:15]
	v_cndmask_b32_e32 v29, v218, v220, vcc
	v_cmp_lt_i32_e32 vcc, v221, v219
	v_lshlrev_b32_e32 v29, 2, v29
	s_nop 1
	v_and_b32_e32 v12, 0xffffffc0, v68
	v_add_u32_e32 v12, 0, v12
	v_lshlrev_b32_e32 v13, 2, v69
	v_mul_u32_u24_e32 v14, 0x840, v70
	v_add3_u32 v12, v12, v13, v14
	v_add_u32_e32 v13, 0xfd00, v12
	v_add_u32_e32 v12, 0xfc00, v12
	ds_write2_b32 v12, v16, v17 offset0:64 offset1:196
	v_add_u32_e32 v12, 0x400, v13
	ds_write2_b32 v12, v18, v19 offset0:8 offset1:140
	v_add_u32_e32 v12, 0x2000, v13
	ds_write2_b32 v12, v20, v21 offset0:64 offset1:196
	v_add_u32_e32 v12, 0x2400, v13
	ds_write2_b32 v12, v22, v23 offset0:72 offset1:204
	v_add_u32_e32 v12, 0x4200, v13
	ds_write2_b32 v12, v24, v25 offset1:132
	v_add_u32_e32 v12, 0x4600, v13
	ds_write2_b32 v12, v26, v27 offset0:8 offset1:140
	v_add_u32_e32 v12, 0x6200, v13
	ds_write2_b32 v12, v8, v9 offset0:64 offset1:196
	v_add_u32_e32 v8, 0x6600, v13
	ds_write2_b32 v8, v10, v11 offset0:72 offset1:204
	v_mul_lo_u32 v8, v37, s0
	v_lshlrev_b32_e32 v37, 16, v7
	v_mul_f32_e32 v7, 0xbfb8aa3b, v43
	v_exp_f32_e32 v7, v7
	v_cndmask_b32_e32 v30, v218, v221, vcc
	v_cmp_lt_i32_e32 vcc, v222, v219
	s_lshl_b32 s0, s52, 9
	v_pk_add_f32 v[6:7], v[6:7], 1.0 op_sel_hi:[1,0]
	v_cndmask_b32_e32 v31, v218, v222, vcc
	s_add_u32 s0, s27, s0
	v_add3_u32 v8, 0, v8, v28
	s_addc_u32 s1, s36, 0
	v_rcp_f32_e32 v56, v7
	s_nop 0
	v_mul_f32_e32 v7, v43, v56
	s_waitcnt lgkmcnt(0)
	s_barrier
; __device__ __forceinline__ u32x4 pack8(const float* v) { u32x4 w; w.x = pk2(v[0], v[1]); w.y = pk2(v[2], v[3]); w.z = pk2(v[4], v[5]); w.w = pk2(v[6], v[7]); return w; }
; __device__ __forceinline__ void unpack8(u32x4 w, float* v) { v[0] = bflo(w.x); v[1] = bfhi(w.x); v[2] = bflo(w.y); v[3] = bfhi(w.y); v[4] = bflo(w.z); v[5] = bfhi(w.z); v[6] = bflo(w.w); v[7] = bfhi(w.w); }
; __device__ __forceinline__ float siluf_(float x) { return x / (1.f + __expf(-x)); }
; __device__ __forceinline__ void gla_out_item(unsigned char* lds, unsigned char* ws, const float* wgate, const float* bgate, const float* hnorm, int l, int item, bool dowrite = true) {
;     ...
;     { const int i = tid >> 3, eg = tid & 7;
;       float ov[16]; float ss = 0.f;
; #pragma unroll
;       for (int e = 0; e < 16; ++e) { ov[e] = Os[i * 132 + eg * 16 + e]; ss += ov[e] * ov[e]; }
;       ss += __shfl_xor(ss, 1); ss += __shfl_xor(ss, 2); ss += __shfl_xor(ss, 4);
;       const float rstd = rsqrtf(ss * (1.f / 128.f) + EPS);
;       const float* gn = hnorm + l * 512 + h * 128 + eg * 16;
;       bf16_t* rp = (bf16_t*)(ws + O_CR) + (size_t)(t0 + i) * 512 + h * 128 + eg * 16;
; #pragma unroll
;       for (int hh = 0; hh < 2; ++hh) { float rv[8]; unpack8(hh == 0 ? rraw0 : rraw1, rv);
; #pragma unroll
;           for (int e = 0; e < 8; ++e) rv[e] = ov[hh * 8 + e] * rstd * gn[hh * 8 + e] * siluf_(rv[e]);
;           if (dowrite) *(u32x4*)(rp + hh * 8) = pack8(rv); } }
; __global__ void __launch_bounds__(NTHR, 2) mk_fwd(Args args) {
;     ...
;                 for (int item = bid; item < 1056; item += G) gla_out_item(lds, ws, ap->in[I_WGATE], ap->in[I_BGATE], ap->in[I_HNORM], l, item);
	v_lshlrev_b32_e32 v58, 16, v5
	v_and_b32_e32 v5, 0xffff0000, v5
	v_mul_f32_e32 v56, 0xbfb8aa3b, v58
	v_mul_f32_e32 v57, 0xbfb8aa3b, v5
	v_exp_f32_e32 v56, v56
	v_exp_f32_e32 v57, v57
	ds_read_b128 v[20:23], v8 offset:64768
	ds_read_b128 v[16:19], v8 offset:64784
	ds_read_b128 v[12:15], v8 offset:64800
	ds_read_b128 v[8:11], v8 offset:64816
	global_load_dwordx4 v[48:51], v28, s[0:1] offset:16
	global_load_dwordx4 v[52:55], v28, s[0:1]
	v_rcp_f32_e32 v43, v6
	s_nop 0
	v_mul_f32_e32 v6, v42, v43
	v_pk_add_f32 v[56:57], v[56:57], 1.0 op_sel_hi:[1,0]
	s_waitcnt lgkmcnt(3)
	v_pk_mul_f32 v[42:43], v[22:23], v[22:23]
	s_waitcnt lgkmcnt(2)
	v_pk_mul_f32 v[38:39], v[16:17], v[16:17]
	v_pk_mul_f32 v[34:35], v[18:19], v[18:19]
	s_waitcnt lgkmcnt(0)
	v_pk_mul_f32 v[26:27], v[8:9], v[8:9]
	v_rcp_f32_e32 v59, v57
	s_nop 0
	v_mul_f32_e32 v57, v5, v59
	v_pk_mul_f32 v[24:25], v[10:11], v[10:11]
	v_lshlrev_b32_e32 v30, 2, v30
	v_lshlrev_b32_e32 v31, 2, v31
	v_lshlrev_b32_e32 v60, 16, v4
	v_and_b32_e32 v61, 0xffff0000, v4
	v_rcp_f32_e32 v5, v56
	s_nop 0
	v_mul_f32_e32 v56, v58, v5
	v_mul_f32_e32 v4, 0xbfb8aa3b, v60
	v_mul_f32_e32 v5, 0xbfb8aa3b, v61
	v_exp_f32_e32 v4, v4
	v_exp_f32_e32 v5, v5
	v_pk_mul_f32 v[58:59], v[20:21], v[20:21]
	s_add_i32 s98, s98, s97
	v_add_f32_e32 v58, v58, v59
	v_pk_add_f32 v[4:5], v[4:5], 1.0 op_sel_hi:[1,0]
	v_add_f32_e32 v42, v58, v42
	v_add_f32_e32 v42, v42, v43
	v_add_f32_e32 v38, v42, v38
	v_add_f32_e32 v38, v38, v39
	v_rcp_f32_e32 v62, v5
	s_nop 0
	v_mul_f32_e32 v5, v61, v62
	v_add_f32_e32 v34, v38, v34
	v_add_f32_e32 v34, v34, v35
	v_rcp_f32_e32 v61, v4
	s_nop 0
	v_mul_f32_e32 v4, v60, v61
	v_mul_f32_e32 v60, 0xbfb8aa3b, v37
	v_mul_f32_e32 v61, 0xbfb8aa3b, v41
	v_exp_f32_e32 v60, v60
	v_exp_f32_e32 v61, v61
	s_cmp_gt_i32 s98, s99
	v_pk_add_f32 v[60:61], v[60:61], 1.0 op_sel_hi:[1,0]
	s_nop 0
	s_nop 0
	v_rcp_f32_e32 v62, v61
	s_nop 0
	v_mul_f32_e32 v61, v41, v62
	v_lshlrev_b32_e32 v66, 16, v0
	v_mul_f32_e32 v0, 0xbfb8aa3b, v66
	v_exp_f32_e32 v0, v0
	v_rcp_f32_e32 v41, v60
	s_nop 0
	v_mul_f32_e32 v60, v37, v41
	v_lshlrev_b32_e32 v37, 16, v1
	v_and_b32_e32 v41, 0xffff0000, v1
	v_mul_f32_e32 v1, 0xbfb8aa3b, v67
	v_pk_mul_f32 v[64:65], v[12:13], v[12:13]
	v_exp_f32_e32 v1, v1
	v_add_f32_e32 v34, v34, v64
	v_pk_mul_f32 v[62:63], v[14:15], v[14:15]
	v_add_f32_e32 v34, v34, v65
	v_add_f32_e32 v34, v34, v62
	v_pk_add_f32 v[0:1], v[0:1], 1.0 op_sel_hi:[1,0]
	v_add_f32_e32 v34, v34, v63
	v_add_f32_e32 v26, v34, v26
	v_add_f32_e32 v26, v26, v27
	v_add_f32_e32 v24, v26, v24
	v_add_f32_e32 v24, v24, v25
	ds_bpermute_b32 v25, v29, v24
	s_waitcnt lgkmcnt(0)
	v_add_f32_e32 v24, v24, v25
	ds_bpermute_b32 v25, v30, v24
	v_rcp_f32_e32 v68, v1
	s_nop 0
	v_mul_f32_e32 v1, v67, v68
	s_waitcnt lgkmcnt(0)
	v_add_f32_e32 v24, v24, v25
	ds_bpermute_b32 v25, v31, v24
	s_waitcnt lgkmcnt(0)
	v_add_f32_e32 v24, v24, v25
	v_fmamk_f32 v24, v24, 0x3c000000, v216
	v_cmp_gt_f32_e32 vcc, s33, v24
	v_mul_f32_e32 v25, 0x4b800000, v24
	v_rcp_f32_e32 v67, v0
	s_nop 0
	v_mul_f32_e32 v0, v66, v67
	v_cndmask_b32_e32 v24, v24, v25, vcc
	v_rsq_f32_e32 v24, v24
	s_nop 0
	v_mul_f32_e32 v25, 0x45800000, v24
	v_cndmask_b32_e32 v24, v24, v25, vcc
	v_pk_mul_f32 v[20:21], v[20:21], v[24:25] op_sel_hi:[1,0]
	v_pk_mul_f32 v[16:17], v[16:17], v[24:25] op_sel_hi:[1,0]
	s_waitcnt vmcnt(0)
	v_pk_mul_f32 v[20:21], v[52:53], v[20:21]
	v_pk_mul_f32 v[16:17], v[48:49], v[16:17]
	v_pk_mul_f32 v[4:5], v[4:5], v[20:21]
	v_pk_mul_f32 v[20:21], v[22:23], v[24:25] op_sel_hi:[1,0]
	v_pk_mul_f32 v[6:7], v[6:7], v[16:17]
	v_pk_mul_f32 v[16:17], v[18:19], v[24:25] op_sel_hi:[1,0]
	v_pk_mul_f32 v[20:21], v[54:55], v[20:21]
	v_pk_mul_f32 v[16:17], v[50:51], v[16:17]
	v_pk_mul_f32 v[20:21], v[56:57], v[20:21]
	v_pk_mul_f32 v[16:17], v[60:61], v[16:17]
	v_cvt_pk_bf16_f32 v4, v4, v5
	v_cvt_pk_bf16_f32 v5, v20, v21
	v_cvt_pk_bf16_f32 v6, v6, v7
	v_cvt_pk_bf16_f32 v7, v16, v17
	global_store_dwordx4 v[32:33], v[4:7], off
	global_load_dwordx4 v[4:7], v28, s[0:1] offset:48
	s_nop 0
	global_load_dwordx4 v[16:19], v28, s[0:1] offset:32
	v_pk_mul_f32 v[12:13], v[12:13], v[24:25] op_sel_hi:[1,0]
	v_pk_mul_f32 v[14:15], v[14:15], v[24:25] op_sel_hi:[1,0]
	v_pk_mul_f32 v[8:9], v[8:9], v[24:25] op_sel_hi:[1,0]
	s_waitcnt vmcnt(0)
	v_pk_mul_f32 v[12:13], v[12:13], v[16:17]
	s_nop 0
	v_pk_mul_f32 v[0:1], v[0:1], v[12:13]
	v_mul_f32_e32 v12, 0xbfb8aa3b, v37
	v_mul_f32_e32 v13, 0xbfb8aa3b, v41
	v_exp_f32_e32 v12, v12
	v_exp_f32_e32 v13, v13
	v_pk_mul_f32 v[14:15], v[14:15], v[18:19]
	v_pk_mul_f32 v[4:5], v[8:9], v[4:5]
	v_cvt_pk_bf16_f32 v0, v0, v1
	v_pk_add_f32 v[12:13], v[12:13], 1.0 op_sel_hi:[1,0]
	s_nop 0
	s_nop 0
	v_rcp_f32_e32 v16, v13
	s_nop 0
	v_mul_f32_e32 v13, v41, v16
	s_nop 0
	v_rcp_f32_e32 v16, v12
	s_nop 0
	v_mul_f32_e32 v12, v37, v16
	v_lshlrev_b32_e32 v16, 16, v2
	v_and_b32_e32 v2, 0xffff0000, v2
	v_pk_mul_f32 v[12:13], v[12:13], v[14:15]
	v_mul_f32_e32 v14, 0xbfb8aa3b, v16
	v_mul_f32_e32 v8, 0xbfb8aa3b, v2
	v_exp_f32_e32 v14, v14
	v_exp_f32_e32 v15, v8
	v_cvt_pk_bf16_f32 v1, v12, v13
	v_pk_add_f32 v[8:9], v[14:15], 1.0 op_sel_hi:[1,0]
	s_nop 0
	s_nop 0
	v_rcp_f32_e32 v14, v9
	s_nop 0
	v_mul_f32_e32 v9, v2, v14
	s_nop 0
	v_lshlrev_b32_e32 v14, 16, v3
	v_and_b32_e32 v15, 0xffff0000, v3
	v_rcp_f32_e32 v2, v8
	s_nop 0
	v_mul_f32_e32 v8, v16, v2
	v_mul_f32_e32 v2, 0xbfb8aa3b, v14
	v_mul_f32_e32 v3, 0xbfb8aa3b, v15
	v_exp_f32_e32 v2, v2
	v_exp_f32_e32 v3, v3
	v_pk_mul_f32 v[4:5], v[8:9], v[4:5]
	v_pk_mul_f32 v[8:9], v[10:11], v[24:25] op_sel_hi:[1,0]
	v_pk_add_f32 v[2:3], v[2:3], 1.0 op_sel_hi:[1,0]
	v_pk_mul_f32 v[6:7], v[8:9], v[6:7]
	s_nop 0
	v_rcp_f32_e32 v8, v3
	s_nop 0
	v_mul_f32_e32 v3, v15, v8
	s_nop 0
	v_rcp_f32_e32 v8, v2
	s_nop 0
	v_mul_f32_e32 v2, v14, v8
	v_pk_mul_f32 v[6:7], v[2:3], v[6:7]
	v_cvt_pk_bf16_f32 v2, v4, v5
	v_cvt_pk_bf16_f32 v3, v6, v7
	global_store_dwordx4 v[32:33], v[0:3], off offset:16
	s_barrier
	s_cbranch_scc0 .LBB0_394

; __device__ __forceinline__ unsigned pk2(float lo, float hi) { f32x2_t v = {lo, hi}; bf16x2_t b = __builtin_convertvector(v, bf16x2_t); return __builtin_bit_cast(unsigned, b); }
; template <int DQK, bool MASK, int NQ>
; __device__ __forceinline__ void attn_unit(unsigned char* lds, const bf16_t* Qg, int ldq, const bf16_t* Kg, int ldk, const bf16_t* Vtg, bf16_t* Og, int ldo,
;                                           int qi0, int a0, int n1, int b0, int n2, float m0, bool sink) {
;     ...
;         bf16_t* op = Og + (size_t)(qw0 + qb * 16 + ql) * ldo + g * 4;
;         if (Og)
; #pragma unroll
;         for (int eb = 0; eb < 4; ++eb) { u32x2 w; w.x = pk2(o[eb][qb][0] * inv, o[eb][qb][1] * inv); w.y = pk2(o[eb][qb][2] * inv, o[eb][qb][3] * inv); *(u32x2*)(op + eb * 16) = w; }
; __global__ void __launch_bounds__(NTHR, 2) mk_fwd(Args args) {
;     ...
;                 for (int L = bid; L < (rep == 0 ? 544 : 256); L += G) {
.LBB0_406:
	s_add_i32 s69, s69, s97
	v_cvt_pk_bf16_f32 v1, v2, v3
	global_store_dwordx2 v[18:19], v[0:1], off offset:96
	v_readlane_b32 s0, v254, 27
	s_movk_i32 s1, 0x21f
	s_nop 2
	s_cmp_eq_u32 s0, 3
	s_cselect_b32 s0, 0x1ff, s1
	s_cmp_gt_i32 s69, s0
	s_cbranch_scc1 .LBB0_506

; template <int DQK, bool MASK, int NQ>
; __device__ __forceinline__ void attn_unit(unsigned char* lds, const bf16_t* Qg, int ldq, const bf16_t* Kg, int ldk, const bf16_t* Vtg, bf16_t* Og, int ldo,
;                                           int qi0, int a0, int n1, int b0, int n2, float m0, bool sink) {
;     ...
;           for (int hb = 0; hb < 2; ++hb) {
;             f32x4 sc[2][NQ];
;             { const unsigned char* kb_ = lds + KOFF + (tt & 1) * KBYTES + hb * 512 + g * 1024 + ql * 16;
;               __builtin_amdgcn_s_setprio(1);
; #pragma unroll
;               for (int k2 = 0; k2 < 2; ++k2) {
; #pragma unroll
;                   for (int c = 0; c < NC; ++c) {
;                       const bf16x8 kf = *(const bf16x8*)(kb_ + c * 4096 + k2 * 256);
; #pragma unroll
;                       for (int qb = 0; qb < NQ; ++qb) sc[k2][qb] = __builtin_amdgcn_mfma_f32_16x16x32_bf16(kf, qf[qb][c], c == 0 ? negm[qb] : sc[k2][qb], 0, 0, 0);
;                   } }
;               __builtin_amdgcn_s_setprio(0); }
;             if (MASK) { if (kt >= 4) { int dl = kt * 64 + hb * 32 + g * 4 - qw0 - ql; asm volatile("" : "+v"(dl));
; #pragma unroll
;                 for (int k2 = 0; k2 < 2; ++k2)
; #pragma unroll
;                     for (int qb = 0; qb < NQ; ++qb)
; #pragma unroll
;                         for (int j = 0; j < 4; ++j) { const int d = dl + (k2 * 16 + j - qb * 16); if (d > 128 || d < -128) sc[k2][qb][j] = -1e30f; } } }
;             float am = fmaxf(fmaxf(sc[0][0][0], sc[0][0][1]), sc[0][0][2]); am = fmaxf(fmaxf(am, sc[0][0][3]), sc[1][0][0]); am = fmaxf(fmaxf(am, sc[1][0][1]), sc[1][0][2]); am = fmaxf(am, sc[1][0][3]);
; #pragma unroll
;             for (int qb = 1; qb < NQ; ++qb) { am = fmaxf(fmaxf(am, sc[0][qb][0]), sc[0][qb][1]); am = fmaxf(fmaxf(am, sc[0][qb][2]), sc[0][qb][3]);
;                 am = fmaxf(fmaxf(am, sc[1][qb][0]), sc[1][qb][1]); am = fmaxf(fmaxf(am, sc[1][qb][2]), sc[1][qb][3]); }
;             if (__any(first || (am > ATT_THR))) {
.Lmla_noload:
	s_and_b32 s0, s13, 1
	s_mul_i32 s1, s0, 0x3000
	s_mulk_i32 s0, 0x2400
	v_add_u32_e32 v37, s1, v250
	v_add_u32_e32 v38, s0, v251
	ds_read_b128 v[196:199], v37
	ds_read_b128 v[192:195], v37 offset:4096
	ds_read_b128 v[188:191], v37 offset:8192
	ds_read_b128 v[184:187], v37 offset:256
	ds_read_b128 v[242:245], v37 offset:4352
	ds_read_b128 v[246:249], v37 offset:8448
	s_waitcnt lgkmcnt(5)
	v_mfma_f32_16x16x32_bf16 v[180:183], v[196:199], v[92:95], v[160:163]
	v_mfma_f32_16x16x32_bf16 v[176:179], v[196:199], v[104:107], v[156:159]
	v_mfma_f32_16x16x32_bf16 v[172:175], v[196:199], v[116:119], v[152:155]
	v_mfma_f32_16x16x32_bf16 v[168:171], v[196:199], v[128:131], v[164:167]
	s_waitcnt lgkmcnt(4)
	v_mfma_f32_16x16x32_bf16 v[180:183], v[192:195], v[96:99], v[180:183]
	v_mfma_f32_16x16x32_bf16 v[176:179], v[192:195], v[108:111], v[176:179]
	v_mfma_f32_16x16x32_bf16 v[172:175], v[192:195], v[120:123], v[172:175]
	v_mfma_f32_16x16x32_bf16 v[168:171], v[192:195], v[132:135], v[168:171]
	s_waitcnt lgkmcnt(3)
	v_mfma_f32_16x16x32_bf16 v[180:183], v[188:191], v[100:103], v[180:183]
	v_mfma_f32_16x16x32_bf16 v[176:179], v[188:191], v[112:115], v[176:179]
	v_mfma_f32_16x16x32_bf16 v[172:175], v[188:191], v[124:127], v[172:175]
	v_mfma_f32_16x16x32_bf16 v[168:171], v[188:191], v[136:139], v[168:171]
	s_waitcnt lgkmcnt(2)
	v_mfma_f32_16x16x32_bf16 v[196:199], v[184:187], v[92:95], v[160:163]
	v_mfma_f32_16x16x32_bf16 v[192:195], v[184:187], v[104:107], v[156:159]
	v_mfma_f32_16x16x32_bf16 v[188:191], v[184:187], v[116:119], v[152:155]
	v_mfma_f32_16x16x32_bf16 v[184:187], v[184:187], v[128:131], v[164:167]
	s_waitcnt lgkmcnt(1)
	v_mfma_f32_16x16x32_bf16 v[196:199], v[242:245], v[96:99], v[196:199]
	v_mfma_f32_16x16x32_bf16 v[192:195], v[242:245], v[108:111], v[192:195]
	v_mfma_f32_16x16x32_bf16 v[188:191], v[242:245], v[120:123], v[188:191]
	v_mfma_f32_16x16x32_bf16 v[184:187], v[242:245], v[132:135], v[184:187]
	s_waitcnt lgkmcnt(0)
	v_mfma_f32_16x16x32_bf16 v[196:199], v[246:249], v[100:103], v[196:199]
	v_mfma_f32_16x16x32_bf16 v[192:195], v[246:249], v[112:115], v[192:195]
	v_mfma_f32_16x16x32_bf16 v[188:191], v[246:249], v[124:127], v[188:191]
	v_mfma_f32_16x16x32_bf16 v[184:187], v[246:249], v[136:139], v[184:187]
	ds_read_b128 v[232:235], v37 offset:512
	ds_read_b128 v[44:47], v37 offset:4608
	ds_read_b128 v[200:203], v37 offset:8704
	ds_read_b128 v[236:239], v37 offset:768
	ds_read_b128 v[242:245], v37 offset:4864
	ds_read_b128 v[246:249], v37 offset:8960
	v_max_f32_e32 v216, v180, v181
	v_max_f32_e32 v217, v176, v177
	v_max_f32_e32 v218, v172, v173
	v_max_f32_e32 v219, v168, v169
	v_max3_f32 v216, v216, v182, v183
	v_max3_f32 v217, v217, v178, v179
	v_max3_f32 v218, v218, v174, v175
	v_max3_f32 v219, v219, v170, v171
	v_max3_f32 v216, v216, v196, v197
	v_max3_f32 v217, v217, v192, v193
	v_max3_f32 v218, v218, v188, v189
	v_max3_f32 v219, v219, v184, v185
	v_max3_f32 v216, v216, v198, v199
	v_max3_f32 v217, v217, v194, v195
	v_max3_f32 v218, v218, v190, v191
	v_max3_f32 v219, v219, v186, v187
	v_max3_f32 v220, v216, v217, v218
	v_max_f32_e32 v220, v220, v219
	v_cmp_lt_f32_e32 vcc, 4.0, v220
	s_or_b64 s[0:1], s[10:11], vcc
	s_cmp_lg_u64 s[0:1], 0
	s_cbranch_scc1 .Lmla_rare_a
; template <int DQK, bool MASK, int NQ>
; __device__ __forceinline__ void attn_unit(unsigned char* lds, const bf16_t* Qg, int ldq, const bf16_t* Kg, int ldk, const bf16_t* Vtg, bf16_t* Og, int ldo,
;                                           int qi0, int a0, int n1, int b0, int n2, float m0, bool sink) {
;     ...
;             { const unsigned char* kb_ = lds + KOFF + (tt & 1) * KBYTES + hb * 512 + g * 1024 + ql * 16;
;               __builtin_amdgcn_s_setprio(1);
; #pragma unroll
;               for (int k2 = 0; k2 < 2; ++k2) {
; #pragma unroll
;                   for (int c = 0; c < NC; ++c) {
;                       const bf16x8 kf = *(const bf16x8*)(kb_ + c * 4096 + k2 * 256);
; #pragma unroll
;                       for (int qb = 0; qb < NQ; ++qb) sc[k2][qb] = __builtin_amdgcn_mfma_f32_16x16x32_bf16(kf, qf[qb][c], c == 0 ? negm[qb] : sc[k2][qb], 0, 0, 0);
;                   } }
;               __builtin_amdgcn_s_setprio(0); }
;             if (MASK) { if (kt >= 4) { int dl = kt * 64 + hb * 32 + g * 4 - qw0 - ql; asm volatile("" : "+v"(dl));
; #pragma unroll
;                 for (int k2 = 0; k2 < 2; ++k2)
; #pragma unroll
;                     for (int qb = 0; qb < NQ; ++qb)
; #pragma unroll
;                         for (int j = 0; j < 4; ++j) { const int d = dl + (k2 * 16 + j - qb * 16); if (d > 128 || d < -128) sc[k2][qb][j] = -1e30f; } } }
;             float am = fmaxf(fmaxf(sc[0][0][0], sc[0][0][1]), sc[0][0][2]); am = fmaxf(fmaxf(am, sc[0][0][3]), sc[1][0][0]); am = fmaxf(fmaxf(am, sc[1][0][1]), sc[1][0][2]); am = fmaxf(am, sc[1][0][3]);
; #pragma unroll
;             for (int qb = 1; qb < NQ; ++qb) { am = fmaxf(fmaxf(am, sc[0][qb][0]), sc[0][qb][1]); am = fmaxf(fmaxf(am, sc[0][qb][2]), sc[0][qb][3]);
;                 am = fmaxf(fmaxf(am, sc[1][qb][0]), sc[1][qb][1]); am = fmaxf(fmaxf(am, sc[1][qb][2]), sc[1][qb][3]); }
;             if (__any(first || (am > ATT_THR))) {
; #pragma unroll
;                 for (int qb = 0; qb < NQ; ++qb) {
;                     float a = fmaxf(fmaxf(sc[0][qb][0], sc[0][qb][1]), sc[0][qb][2]);
;                     a = fmaxf(fmaxf(a, sc[0][qb][3]), sc[1][qb][0]); a = fmaxf(fmaxf(a, sc[1][qb][1]), sc[1][qb][2]); a = fmaxf(a, sc[1][qb][3]);
;                     { auto r16 = __builtin_amdgcn_permlane16_swap(__float_as_uint(a), __float_as_uint(a), false, false); a = fmaxf(__uint_as_float(r16[0]), __uint_as_float(r16[1])); }
.Lmla_common_a:
	s_waitcnt lgkmcnt(5)
	v_mfma_f32_16x16x32_bf16 v[216:219], v[232:235], v[92:95], v[160:163]
	v_exp_f32_e32 v180, v180
	v_exp_f32_e32 v181, v181
	v_mfma_f32_16x16x32_bf16 v[220:223], v[232:235], v[104:107], v[156:159]
	v_exp_f32_e32 v182, v182
	v_exp_f32_e32 v183, v183
	v_mfma_f32_16x16x32_bf16 v[224:227], v[232:235], v[116:119], v[152:155]
	v_exp_f32_e32 v196, v196
	v_exp_f32_e32 v197, v197
	v_mfma_f32_16x16x32_bf16 v[228:231], v[232:235], v[128:131], v[164:167]
	v_exp_f32_e32 v198, v198
	v_exp_f32_e32 v199, v199
	s_waitcnt lgkmcnt(4)
	v_mfma_f32_16x16x32_bf16 v[216:219], v[44:47], v[96:99], v[216:219]
	v_cvt_pk_bf16_f32 v180, v180, v181
	v_cvt_pk_bf16_f32 v181, v182, v183
	v_mfma_f32_16x16x32_bf16 v[220:223], v[44:47], v[108:111], v[220:223]
	v_cvt_pk_bf16_f32 v182, v196, v197
	v_cvt_pk_bf16_f32 v183, v198, v199
	v_mfma_f32_16x16x32_bf16 v[224:227], v[44:47], v[120:123], v[224:227]
	v_exp_f32_e32 v176, v176
	v_exp_f32_e32 v177, v177
	v_mfma_f32_16x16x32_bf16 v[228:231], v[44:47], v[132:135], v[228:231]
	v_exp_f32_e32 v178, v178
	v_exp_f32_e32 v179, v179
	s_waitcnt lgkmcnt(3)
	v_mfma_f32_16x16x32_bf16 v[216:219], v[200:203], v[100:103], v[216:219]
	v_exp_f32_e32 v192, v192
	v_exp_f32_e32 v193, v193
	v_mfma_f32_16x16x32_bf16 v[220:223], v[200:203], v[112:115], v[220:223]
	v_exp_f32_e32 v194, v194
	v_exp_f32_e32 v195, v195
	v_mfma_f32_16x16x32_bf16 v[224:227], v[200:203], v[124:127], v[224:227]
	v_cvt_pk_bf16_f32 v176, v176, v177
	v_cvt_pk_bf16_f32 v177, v178, v179
	v_mfma_f32_16x16x32_bf16 v[228:231], v[200:203], v[136:139], v[228:231]
	v_cvt_pk_bf16_f32 v178, v192, v193
	v_cvt_pk_bf16_f32 v179, v194, v195
	s_waitcnt lgkmcnt(2)
	v_mfma_f32_16x16x32_bf16 v[232:235], v[236:239], v[92:95], v[160:163]
	v_exp_f32_e32 v172, v172
	v_exp_f32_e32 v173, v173
	v_mfma_f32_16x16x32_bf16 v[44:47], v[236:239], v[104:107], v[156:159]
	v_exp_f32_e32 v174, v174
	v_exp_f32_e32 v175, v175
	v_mfma_f32_16x16x32_bf16 v[200:203], v[236:239], v[116:119], v[152:155]
	v_exp_f32_e32 v188, v188
	v_exp_f32_e32 v189, v189
	v_mfma_f32_16x16x32_bf16 v[236:239], v[236:239], v[128:131], v[164:167]
	v_exp_f32_e32 v190, v190
	v_exp_f32_e32 v191, v191
	s_waitcnt lgkmcnt(1)
	v_mfma_f32_16x16x32_bf16 v[232:235], v[242:245], v[96:99], v[232:235]
	v_cvt_pk_bf16_f32 v172, v172, v173
	v_cvt_pk_bf16_f32 v173, v174, v175
	v_mfma_f32_16x16x32_bf16 v[44:47], v[242:245], v[108:111], v[44:47]
	v_cvt_pk_bf16_f32 v174, v188, v189
	v_cvt_pk_bf16_f32 v175, v190, v191
	v_mfma_f32_16x16x32_bf16 v[200:203], v[242:245], v[120:123], v[200:203]
	v_exp_f32_e32 v168, v168
	v_exp_f32_e32 v169, v169
	v_mfma_f32_16x16x32_bf16 v[236:239], v[242:245], v[132:135], v[236:239]
	v_exp_f32_e32 v170, v170
	v_exp_f32_e32 v171, v171
	s_waitcnt lgkmcnt(0)
	v_mfma_f32_16x16x32_bf16 v[232:235], v[246:249], v[100:103], v[232:235]
	v_exp_f32_e32 v184, v184
	v_exp_f32_e32 v185, v185
	v_mfma_f32_16x16x32_bf16 v[44:47], v[246:249], v[112:115], v[44:47]
	v_exp_f32_e32 v186, v186
	v_exp_f32_e32 v187, v187
	v_mfma_f32_16x16x32_bf16 v[200:203], v[246:249], v[124:127], v[200:203]
	v_cvt_pk_bf16_f32 v168, v168, v169
	v_cvt_pk_bf16_f32 v169, v170, v171
	v_mfma_f32_16x16x32_bf16 v[236:239], v[246:249], v[136:139], v[236:239]
	v_cvt_pk_bf16_f32 v170, v184, v185
	v_cvt_pk_bf16_f32 v171, v186, v187
	ds_read_b128 v[196:199], v38 offset:24576
	ds_read_b128 v[192:195], v38 offset:26880
	ds_read_b128 v[188:191], v38 offset:29184
	ds_read_b128 v[184:187], v38 offset:31488
	v_mov_b32_e32 v246, s12
	v_mov_b32_e32 v247, s12
	v_mov_b32_e32 v248, s12
	v_mov_b32_e32 v249, s12
	v_max_f32_e32 v242, v216, v217
	v_max_f32_e32 v243, v220, v221
	v_max_f32_e32 v244, v224, v225
	v_max_f32_e32 v245, v228, v229
	v_max3_f32 v242, v242, v218, v219
	v_max3_f32 v243, v243, v222, v223
	v_max3_f32 v244, v244, v226, v227
	v_max3_f32 v245, v245, v230, v231
	v_max3_f32 v242, v242, v232, v233
	v_max3_f32 v243, v243, v44, v45
	v_max3_f32 v244, v244, v200, v201
	v_max3_f32 v245, v245, v236, v237
	v_max3_f32 v242, v242, v234, v235
	v_max3_f32 v243, v243, v46, v47
	v_max3_f32 v244, v244, v202, v203
	v_max3_f32 v245, v245, v238, v239
	v_max3_f32 v39, v242, v243, v244
	v_max_f32_e32 v39, v39, v245
	s_waitcnt lgkmcnt(3)
	v_mfma_f32_16x16x32_bf16 v[76:79], v[196:199], v[180:183], v[76:79]
	v_mfma_f32_16x16x32_bf16 v[56:59], v[196:199], v[176:179], v[56:59]
	v_mfma_f32_16x16x32_bf16 v[24:27], v[196:199], v[172:175], v[24:27]
	v_mfma_f32_16x16x32_bf16 v[4:7], v[196:199], v[168:171], v[4:7]
	s_waitcnt lgkmcnt(2)
	v_mfma_f32_16x16x32_bf16 v[80:83], v[192:195], v[180:183], v[80:83]
	v_mfma_f32_16x16x32_bf16 v[60:63], v[192:195], v[176:179], v[60:63]
	v_mfma_f32_16x16x32_bf16 v[28:31], v[192:195], v[172:175], v[28:31]
	v_mfma_f32_16x16x32_bf16 v[8:11], v[192:195], v[168:171], v[8:11]
	s_waitcnt lgkmcnt(1)
	v_mfma_f32_16x16x32_bf16 v[84:87], v[188:191], v[180:183], v[84:87]
	v_mfma_f32_16x16x32_bf16 v[64:67], v[188:191], v[176:179], v[64:67]
	v_mfma_f32_16x16x32_bf16 v[32:35], v[188:191], v[172:175], v[32:35]
	v_mfma_f32_16x16x32_bf16 v[12:15], v[188:191], v[168:171], v[12:15]
	s_waitcnt lgkmcnt(0)
	v_mfma_f32_16x16x32_bf16 v[72:75], v[184:187], v[180:183], v[72:75]
	v_mfma_f32_16x16x32_bf16 v[52:55], v[184:187], v[176:179], v[52:55]
	v_mfma_f32_16x16x32_bf16 v[20:23], v[184:187], v[172:175], v[20:23]
	v_mfma_f32_16x16x32_bf16 v[0:3], v[184:187], v[168:171], v[0:3]
	v_mfma_f32_16x16x32_bf16 v[88:91], v[246:249], v[180:183], v[88:91]
	v_mfma_f32_16x16x32_bf16 v[68:71], v[246:249], v[176:179], v[68:71]
	v_mfma_f32_16x16x32_bf16 v[48:51], v[246:249], v[172:175], v[48:51]
	v_mfma_f32_16x16x32_bf16 v[16:19], v[246:249], v[168:171], v[16:19]
	v_cmp_lt_f32_e32 vcc, 4.0, v39
	s_or_b64 s[0:1], s[10:11], vcc
	s_cmp_lg_u64 s[0:1], 0
	s_cbranch_scc1 .Lmla_rare_b

; template <int DQK, bool MASK, int NQ>
; __device__ __forceinline__ void attn_unit(unsigned char* lds, const bf16_t* Qg, int ldq, const bf16_t* Kg, int ldk, const bf16_t* Vtg, bf16_t* Og, int ldo,
;                                           int qi0, int a0, int n1, int b0, int n2, float m0, bool sink) {
;     ...
;             if (__any(first || (am > ATT_THR))) {
; #pragma unroll
;                 for (int qb = 0; qb < NQ; ++qb) {
;                     float a = fmaxf(fmaxf(sc[0][qb][0], sc[0][qb][1]), sc[0][qb][2]);
;                     a = fmaxf(fmaxf(a, sc[0][qb][3]), sc[1][qb][0]); a = fmaxf(fmaxf(a, sc[1][qb][1]), sc[1][qb][2]); a = fmaxf(a, sc[1][qb][3]);
;                     { auto r16 = __builtin_amdgcn_permlane16_swap(__float_as_uint(a), __float_as_uint(a), false, false); a = fmaxf(__uint_as_float(r16[0]), __uint_as_float(r16[1])); }
;                     { auto r32 = __builtin_amdgcn_permlane32_swap(__float_as_uint(a), __float_as_uint(a), false, false); a = fmaxf(__uint_as_float(r32[0]), __uint_as_float(r32[1])); }
;                     const float dlt = first ? a : fmaxf(a, 0.f);
;                     mrow[qb] += dlt; negm[qb] = (f32x4){-mrow[qb], -mrow[qb], -mrow[qb], -mrow[qb]};
;                     sc[0][qb] = sc[0][qb] - dlt; sc[1][qb] = sc[1][qb] - dlt;
;                     if (!first) { const float alpha = __builtin_amdgcn_exp2f(-dlt); ol[qb] = ol[qb] * alpha;
; #pragma unroll
;                         for (int eb = 0; eb < 4; ++eb) o[eb][qb] = o[eb][qb] * alpha; } }
;                 first = false; }
.Lmla_rare_a:
	v_mov_b32_e32 v39, v216
	s_nop 1
	v_permlane16_swap_b32_e32 v216, v39
	v_max_f32_e32 v39, v39, v39
	v_max_f32_e32 v216, v216, v216
	v_max_f32_e32 v216, v216, v39
	v_mov_b32_e32 v39, v216
	s_nop 1
	v_permlane32_swap_b32_e32 v216, v39
	v_max_f32_e32 v39, v39, v39
	v_max_f32_e32 v216, v216, v216
	v_max_f32_e32 v216, v216, v39
	v_max_f32_e32 v220, 0, v216
	v_mov_b32_e32 v39, v217
	s_nop 1
	v_permlane16_swap_b32_e32 v217, v39
	v_max_f32_e32 v39, v39, v39
	v_max_f32_e32 v217, v217, v217
	v_max_f32_e32 v217, v217, v39
	v_mov_b32_e32 v39, v217
	s_nop 1
	v_permlane32_swap_b32_e32 v217, v39
	v_max_f32_e32 v39, v39, v39
	v_max_f32_e32 v217, v217, v217
	v_max_f32_e32 v217, v217, v39
	v_max_f32_e32 v221, 0, v217
	v_mov_b32_e32 v39, v218
	s_nop 1
	v_permlane16_swap_b32_e32 v218, v39
	v_max_f32_e32 v39, v39, v39
	v_max_f32_e32 v218, v218, v218
	v_max_f32_e32 v218, v218, v39
	v_mov_b32_e32 v39, v218
	s_nop 1
	v_permlane32_swap_b32_e32 v218, v39
	v_max_f32_e32 v39, v39, v39
	v_max_f32_e32 v218, v218, v218
	v_max_f32_e32 v218, v218, v39
	v_max_f32_e32 v222, 0, v218
	v_mov_b32_e32 v39, v219
	s_nop 1
	v_permlane16_swap_b32_e32 v219, v39
	v_max_f32_e32 v39, v39, v39
	v_max_f32_e32 v219, v219, v219
	v_max_f32_e32 v219, v219, v39
	v_mov_b32_e32 v39, v219
	s_nop 1
	v_permlane32_swap_b32_e32 v219, v39
	v_max_f32_e32 v39, v39, v39
	v_max_f32_e32 v219, v219, v219
	v_max_f32_e32 v219, v219, v39
	v_max_f32_e32 v223, 0, v219
	s_cmp_lg_u64 s[10:11], 0
	s_cbranch_scc1 .Lmla_rare_a_ns
	v_exp_f32_e64 v224, -v220
	v_exp_f32_e64 v226, -v221
	v_exp_f32_e64 v228, -v222
	v_exp_f32_e64 v230, -v223
	s_nop 0
	v_pk_mul_f32 v[88:89], v[88:89], v[224:225] op_sel_hi:[1,0]
	v_pk_mul_f32 v[90:91], v[90:91], v[224:225] op_sel_hi:[1,0]
	v_pk_mul_f32 v[76:77], v[76:77], v[224:225] op_sel_hi:[1,0]
	v_pk_mul_f32 v[78:79], v[78:79], v[224:225] op_sel_hi:[1,0]
	v_pk_mul_f32 v[80:81], v[80:81], v[224:225] op_sel_hi:[1,0]
	v_pk_mul_f32 v[82:83], v[82:83], v[224:225] op_sel_hi:[1,0]
	v_pk_mul_f32 v[84:85], v[84:85], v[224:225] op_sel_hi:[1,0]
	v_pk_mul_f32 v[86:87], v[86:87], v[224:225] op_sel_hi:[1,0]
	v_pk_mul_f32 v[72:73], v[72:73], v[224:225] op_sel_hi:[1,0]
	v_pk_mul_f32 v[74:75], v[74:75], v[224:225] op_sel_hi:[1,0]
	v_pk_mul_f32 v[68:69], v[68:69], v[226:227] op_sel_hi:[1,0]
	v_pk_mul_f32 v[70:71], v[70:71], v[226:227] op_sel_hi:[1,0]
	v_pk_mul_f32 v[56:57], v[56:57], v[226:227] op_sel_hi:[1,0]
	v_pk_mul_f32 v[58:59], v[58:59], v[226:227] op_sel_hi:[1,0]
	v_pk_mul_f32 v[60:61], v[60:61], v[226:227] op_sel_hi:[1,0]
	v_pk_mul_f32 v[62:63], v[62:63], v[226:227] op_sel_hi:[1,0]
	v_pk_mul_f32 v[64:65], v[64:65], v[226:227] op_sel_hi:[1,0]
	v_pk_mul_f32 v[66:67], v[66:67], v[226:227] op_sel_hi:[1,0]
	v_pk_mul_f32 v[52:53], v[52:53], v[226:227] op_sel_hi:[1,0]
	v_pk_mul_f32 v[54:55], v[54:55], v[226:227] op_sel_hi:[1,0]
	v_pk_mul_f32 v[48:49], v[48:49], v[228:229] op_sel_hi:[1,0]
	v_pk_mul_f32 v[50:51], v[50:51], v[228:229] op_sel_hi:[1,0]
	v_pk_mul_f32 v[24:25], v[24:25], v[228:229] op_sel_hi:[1,0]
	v_pk_mul_f32 v[26:27], v[26:27], v[228:229] op_sel_hi:[1,0]
	v_pk_mul_f32 v[28:29], v[28:29], v[228:229] op_sel_hi:[1,0]
	v_pk_mul_f32 v[30:31], v[30:31], v[228:229] op_sel_hi:[1,0]
	v_pk_mul_f32 v[32:33], v[32:33], v[228:229] op_sel_hi:[1,0]
	v_pk_mul_f32 v[34:35], v[34:35], v[228:229] op_sel_hi:[1,0]
	v_pk_mul_f32 v[20:21], v[20:21], v[228:229] op_sel_hi:[1,0]
	v_pk_mul_f32 v[22:23], v[22:23], v[228:229] op_sel_hi:[1,0]
	v_pk_mul_f32 v[16:17], v[16:17], v[230:231] op_sel_hi:[1,0]
	v_pk_mul_f32 v[18:19], v[18:19], v[230:231] op_sel_hi:[1,0]
	v_pk_mul_f32 v[4:5], v[4:5], v[230:231] op_sel_hi:[1,0]
	v_pk_mul_f32 v[6:7], v[6:7], v[230:231] op_sel_hi:[1,0]
	v_pk_mul_f32 v[8:9], v[8:9], v[230:231] op_sel_hi:[1,0]
	v_pk_mul_f32 v[10:11], v[10:11], v[230:231] op_sel_hi:[1,0]
	v_pk_mul_f32 v[12:13], v[12:13], v[230:231] op_sel_hi:[1,0]
	v_pk_mul_f32 v[14:15], v[14:15], v[230:231] op_sel_hi:[1,0]
	v_pk_mul_f32 v[0:1], v[0:1], v[230:231] op_sel_hi:[1,0]
	v_pk_mul_f32 v[2:3], v[2:3], v[230:231] op_sel_hi:[1,0]
.Lmla_rare_a_ns:
	v_cndmask_b32_e64 v220, v220, v216, s[10:11]
	v_cndmask_b32_e64 v221, v221, v217, s[10:11]
	v_cndmask_b32_e64 v222, v222, v218, s[10:11]
	v_cndmask_b32_e64 v223, v223, v219, s[10:11]
	v_add_f32_e32 v241, v241, v220
	v_sub_f32_e32 v180, v180, v220
	v_sub_f32_e32 v181, v181, v220
	v_sub_f32_e32 v182, v182, v220
	v_sub_f32_e32 v183, v183, v220
	v_sub_f32_e32 v196, v196, v220
	v_sub_f32_e32 v197, v197, v220
	v_sub_f32_e32 v198, v198, v220
	v_sub_f32_e32 v199, v199, v220
	v_add_f32_e32 v240, v240, v221
	v_sub_f32_e32 v176, v176, v221
	v_sub_f32_e32 v177, v177, v221
	v_sub_f32_e32 v178, v178, v221
	v_sub_f32_e32 v179, v179, v221
	v_sub_f32_e32 v192, v192, v221
	v_sub_f32_e32 v193, v193, v221
	v_sub_f32_e32 v194, v194, v221
	v_sub_f32_e32 v195, v195, v221
	v_add_f32_e32 v255, v255, v222
	v_sub_f32_e32 v172, v172, v222
	v_sub_f32_e32 v173, v173, v222
	v_sub_f32_e32 v174, v174, v222
	v_sub_f32_e32 v175, v175, v222
	v_sub_f32_e32 v188, v188, v222
	v_sub_f32_e32 v189, v189, v222
	v_sub_f32_e32 v190, v190, v222
	v_sub_f32_e32 v191, v191, v222
	v_add_f32_e32 v40, v40, v223
	v_sub_f32_e32 v168, v168, v223
	v_sub_f32_e32 v169, v169, v223
	v_sub_f32_e32 v170, v170, v223
	v_sub_f32_e32 v171, v171, v223
	v_sub_f32_e32 v184, v184, v223
	v_sub_f32_e32 v185, v185, v223
	v_sub_f32_e32 v186, v186, v223
	v_sub_f32_e32 v187, v187, v223
	v_xor_b32_e32 v160, 0x80000000, v241
	v_xor_b32_e32 v156, 0x80000000, v240
	v_xor_b32_e32 v152, 0x80000000, v255
	v_xor_b32_e32 v164, 0x80000000, v40
	v_mov_b32_e32 v161, v160
	v_mov_b32_e32 v162, v160
	v_mov_b32_e32 v163, v160
	v_mov_b32_e32 v157, v156
	v_mov_b32_e32 v158, v156
	v_mov_b32_e32 v159, v156
	v_mov_b32_e32 v153, v152
	v_mov_b32_e32 v154, v152
	v_mov_b32_e32 v155, v152
	v_mov_b32_e32 v165, v164
	v_mov_b32_e32 v166, v164
	v_mov_b32_e32 v167, v164
	s_mov_b64 s[10:11], 0
	s_branch .Lmla_common_a
